# cache ws kernarg pointer in s[100:101], replace 40 s_load by s_mov_b64
# baseline (speedup 1.0000x reference)
.LBB0_3:
	s_or_b64 exec, exec, s[4:5]
	s_waitcnt lgkmcnt(0)
	s_mov_b64 s[100:101], s[22:23]
	s_barrier
	s_add_u32 s24, s22, 0x4000
	s_getreg_b32 s3, hwreg(HW_REG_XCC_ID, 0, 4)
	s_addc_u32 s25, s23, 0
	s_and_b32 s3, s3, 15
	v_cmp_eq_u32_e32 vcc, 0, v0
	v_writelane_b32 v252, s3, 2
	s_and_saveexec_b64 s[4:5], vcc
	s_cbranch_execz .LBB0_7
	s_mov_b64 s[8:9], exec
	v_mbcnt_lo_u32_b32 v0, s8, 0
	v_mbcnt_hi_u32_b32 v0, s9, v0
	v_cmp_eq_u32_e32 vcc, 0, v0
	s_and_saveexec_b64 s[6:7], vcc
	s_cbranch_execz .LBB0_6
	v_readlane_b32 s3, v252, 2
	s_lshl_b32 s3, s3, 8
	s_bcnt1_i32_b64 s8, s[8:9]
	v_mov_b32_e32 v0, s3
	v_mov_b32_e32 v1, s8
	global_atomic_add v0, v1, s[24:25] offset:1024

.LBB0_7:
	s_or_b64 exec, exec, s[4:5]
	s_and_b32 s3, s33, 7
	s_cmp_eq_u32 s3, 0
	s_cselect_b64 s[84:85], -1, 0
	s_cmp_lt_i32 s20, 1
	s_cselect_b64 s[4:5], -1, 0
	s_cmp_gt_i32 s21, 0
	s_cselect_b64 s[6:7], -1, 0
	s_and_b64 s[4:5], s[4:5], s[6:7]
	s_andn2_b64 vcc, exec, s[4:5]
	s_cbranch_vccnz .LBB0_118
	s_ashr_i32 s4, s2, 31
	s_lshr_b32 s4, s4, 29
	s_mov_b64 s[38:39], s[0:1]
	s_add_i32 s4, s2, s4
	v_mov_b32_e32 v2, v244
	s_and_b32 s5, s4, -8
	s_load_dwordx4 s[12:15], s[38:39], 0x30
	s_load_dwordx4 s[8:11], s[38:39], 0x48
	s_mov_b64 s[16:17], s[100:101]
	s_load_dwordx2 s[6:7], s[38:39], 0x60
	s_load_dwordx2 s[18:19], s[38:39], 0x88
	s_ashr_i32 s3, s33, 3
	s_sub_i32 s5, s2, s5
	s_mul_i32 s3, s3, s5
	s_ashr_i32 s4, s4, 3
	s_add_i32 s3, s3, s4
	s_lshl_b32 s4, s75, 14
	s_add_i32 s28, s4, 0
	s_and_b64 s[4:5], s[84:85], exec
	s_cselect_b32 s3, s3, s2
	s_cmpk_gt_i32 s3, 0xbf
	v_add_u32_e32 v0, s76, v2
	s_cbranch_scc1 .LBB0_18
	s_lshl_b32 s4, s3, 3
	s_add_i32 s4, s75, s4
	s_add_i32 s42, s4, 0x500
	s_add_i32 s29, s4, 0xfffffc00
	s_cmpk_lt_i32 s42, 0x900
	s_cselect_b64 s[4:5], -1, 0
	s_and_b64 s[26:27], s[4:5], exec
	s_cselect_b32 s27, 0x90, 32
	v_cvt_f32_ubyte0_e32 v1, s27
	v_rcp_iflag_f32_e32 v1, v1
	s_load_dwordx2 s[36:37], s[38:39], 0x8
	s_load_dwordx2 s[34:35], s[38:39], 0x18
	s_load_dwordx2 s[40:41], s[38:39], 0x28
	s_load_dwordx2 s[30:31], s[38:39], 0x40
	s_cselect_b32 s29, s42, s29
	s_sub_i32 s39, 0, s27
	v_mul_f32_e32 v1, 0x4f7ffffe, v1
	v_cvt_u32_f32_e32 v1, v1
	s_abs_i32 s38, s29
	s_ashr_i32 s26, s29, 31
	v_readfirstlane_b32 s43, v1
	s_mul_i32 s39, s39, s43
	s_mul_hi_u32 s39, s43, s39
	s_add_i32 s43, s43, s39
	s_mul_hi_u32 s39, s38, s43
	s_mul_i32 s43, s39, s27
	s_sub_i32 s38, s38, s43
	s_add_i32 s43, s39, 1
	s_sub_i32 s44, s38, s27
	s_cmp_ge_u32 s38, s27
	s_cselect_b32 s39, s43, s39
	s_cselect_b32 s38, s44, s38
	s_add_i32 s43, s39, 1
	s_cmp_ge_u32 s38, s27
	s_cselect_b32 s38, s43, s39
	s_xor_b32 s38, s38, s26
	s_sub_i32 s26, s38, s26
	s_mul_i32 s27, s26, s27
	s_sub_i32 s27, s29, s27
	s_lshl_b32 s29, s27, 5
	s_cmpk_gt_i32 s42, 0x8ff
	s_mov_b64 s[38:39], 0x400
	s_mov_b32 s42, s29
	s_cbranch_scc1 .LBB0_55
	s_cmp_gt_i32 s27, 31
	s_cbranch_scc0 .LBB0_28
	s_cmpk_gt_u32 s29, 0x5ff
	s_cbranch_scc0 .LBB0_29
	s_cmpk_gt_u32 s29, 0x7ff
	s_cbranch_scc0 .LBB0_30
	s_cmpk_gt_u32 s29, 0x9ff
	s_cbranch_scc0 .LBB0_31
	s_cmpk_gt_u32 s29, 0xbff
	s_cbranch_scc0 .LBB0_32
	s_cmpk_gt_u32 s29, 0xdff
	s_cbranch_scc0 .LBB0_33
	s_cmpk_gt_u32 s29, 0xfff
	s_cbranch_scc0 .LBB0_34
	s_add_i32 s42, s29, 0xfffffa00
	s_mov_b64 s[38:39], 0
	s_branch .LBB0_35

.LBB0_118:
	s_cmp_lt_i32 s20, 2
	s_cselect_b64 s[4:5], -1, 0
	s_cmp_gt_i32 s21, 1
	s_waitcnt lgkmcnt(0)
	s_cselect_b64 s[6:7], -1, 0
	s_and_b64 s[4:5], s[4:5], s[6:7]
	s_andn2_b64 vcc, exec, s[4:5]
	s_mov_b64 s[4:5], 0
	s_cbranch_vccnz .LBB0_302
	s_ashr_i32 s4, s2, 31
	s_lshr_b32 s4, s4, 29
	s_add_i32 s4, s2, s4
	s_and_b32 s5, s4, 0x1ffffff8
	s_lshr_b32 s3, s33, 3
	s_sub_i32 s5, s2, s5
	s_mul_i32 s3, s3, s5
	s_lshr_b32 s4, s4, 3
	s_add_i32 s3, s3, s4
	s_bitcmp0_b32 s2, 0
	s_cselect_b64 s[4:5], -1, 0
	s_lshl_b32 s6, s2, 4
	s_and_b32 s6, s6, 0x60
	s_ashr_i32 s7, s2, 3
	s_add_i32 s6, s6, s7
	s_mul_i32 s6, s6, 28
	s_ashr_i32 s7, s6, 31
	s_and_b64 s[10:11], s[84:85], exec
	s_cselect_b32 s3, s3, s2
	s_lshl_b32 s3, s3, 3
	s_add_i32 s3, s3, s75
	s_lshl_b32 s42, s3, 3
	s_mov_b64 s[8:9], s[0:1]
	s_or_b32 s30, s42, 3
	v_mov_b32_e32 v144, v244
	s_cmpk_gt_i32 s3, 0x7ff
	s_load_dwordx2 s[38:39], s[8:9], 0x0
	s_load_dwordx2 s[40:41], s[8:9], 0x10
	s_load_dwordx2 s[50:51], s[8:9], 0x20
	s_load_dwordx2 s[10:11], s[8:9], 0x70
	s_cselect_b64 s[54:55], -1, 0
	s_add_i32 s65, s42, 0xffffc000
	s_ashr_i32 s43, s42, 31
	s_cmpk_lt_i32 s3, 0x800
	s_cselect_b32 s13, s43, 0
	s_cselect_b32 s12, s42, s65
	s_waitcnt lgkmcnt(0)
	s_cselect_b32 s14, s39, s41
	s_cselect_b32 s15, s38, s40
	s_lshl_b64 s[12:13], s[12:13], 12
	s_add_u32 s12, s15, s12
	s_addc_u32 s13, s14, s13
	s_cmpk_gt_i32 s30, 0x3fff
	v_ashrrev_i32_e32 v145, 31, v144
	s_cselect_b64 s[36:37], -1, 0
	s_add_i32 s64, s42, 0xffffc003
	s_ashr_i32 s31, s30, 31
	v_lshlrev_b64 v[146:147], 4, v[144:145]
	s_cmpk_lt_i32 s30, 0x4000
	v_lshl_add_u64 v[0:1], s[12:13], 0, v[146:147]
	s_cselect_b32 s13, s31, 0
	s_cselect_b32 s12, s30, s64
	s_cselect_b32 s14, s39, s41
	s_cselect_b32 s15, s38, s40
	s_lshl_b64 s[12:13], s[12:13], 12
	s_add_u32 s12, s15, s12
	s_addc_u32 s13, s14, s13
	s_or_b32 s48, s42, 1
	s_cmpk_gt_i32 s48, 0x3fff
	global_load_dwordx4 v[108:111], v[0:1], off nt
	global_load_dwordx4 v[104:107], v[0:1], off offset:1024 nt
	global_load_dwordx4 v[100:103], v[0:1], off offset:2048 nt
	global_load_dwordx4 v[96:99], v[0:1], off offset:3072 nt
	v_lshl_add_u64 v[0:1], s[12:13], 0, v[146:147]
	s_cselect_b64 s[52:53], -1, 0
	s_add_i32 s12, s42, 0xffffc001
	s_ashr_i32 s49, s48, 31
	s_cmpk_lt_i32 s48, 0x4000
	s_cselect_b32 s13, s49, 0
	s_cselect_b32 s12, s48, s12
	s_cselect_b32 s14, s39, s41
	s_cselect_b32 s15, s38, s40
	s_lshl_b64 s[12:13], s[12:13], 12
	s_add_u32 s12, s15, s12
	s_addc_u32 s13, s14, s13
	s_or_b32 s16, s42, 4
	s_cmpk_gt_i32 s16, 0x3fff
	s_cselect_b64 s[18:19], -1, 0
	s_add_i32 s29, s42, 0xffffc004
	s_ashr_i32 s17, s16, 31
	s_cmpk_lt_i32 s16, 0x4000
	global_load_dwordx4 v[44:47], v[0:1], off nt
	global_load_dwordx4 v[40:43], v[0:1], off offset:1024 nt
	global_load_dwordx4 v[36:39], v[0:1], off offset:2048 nt
	global_load_dwordx4 v[32:35], v[0:1], off offset:3072 nt
	v_lshl_add_u64 v[0:1], s[12:13], 0, v[146:147]
	s_cselect_b32 s13, s17, 0
	s_cselect_b32 s12, s16, s29
	s_cselect_b32 s14, s39, s41
	s_cselect_b32 s15, s38, s40
	s_lshl_b64 s[12:13], s[12:13], 12
	s_add_u32 s12, s15, s12
	s_addc_u32 s13, s14, s13
	s_or_b32 s44, s42, 2
	s_cmpk_gt_i32 s44, 0x3fff
	global_load_dwordx4 v[92:95], v[0:1], off nt
	global_load_dwordx4 v[88:91], v[0:1], off offset:1024 nt
	global_load_dwordx4 v[84:87], v[0:1], off offset:2048 nt
	global_load_dwordx4 v[76:79], v[0:1], off offset:3072 nt
	v_lshl_add_u64 v[0:1], s[12:13], 0, v[146:147]
	s_cselect_b64 s[46:47], -1, 0
	s_add_i32 s12, s42, 0xffffc002
	s_ashr_i32 s45, s44, 31
	s_cmpk_lt_i32 s44, 0x4000
	s_cselect_b32 s13, s45, 0
	s_cselect_b32 s12, s44, s12
	s_cselect_b32 s14, s39, s41
	s_cselect_b32 s15, s38, s40
	s_lshl_b64 s[12:13], s[12:13], 12
	s_add_u32 s12, s15, s12
	s_addc_u32 s13, s14, s13
	global_load_dwordx4 v[28:31], v[0:1], off nt
	global_load_dwordx4 v[24:27], v[0:1], off offset:1024 nt
	global_load_dwordx4 v[16:19], v[0:1], off offset:2048 nt
	global_load_dwordx4 v[12:15], v[0:1], off offset:3072 nt
	v_lshl_add_u64 v[0:1], s[12:13], 0, v[146:147]
	s_or_b32 s12, s42, 5
	s_cmpk_gt_i32 s12, 0x3fff
	s_cselect_b64 s[14:15], -1, 0
	s_add_i32 s28, s42, 0xffffc005
	s_ashr_i32 s13, s12, 31
	s_cmpk_lt_i32 s12, 0x4000
	s_cselect_b32 s27, s13, 0
	s_cselect_b32 s26, s12, s28
	s_cselect_b32 s34, s39, s41
	s_cselect_b32 s35, s38, s40
	s_lshl_b64 s[26:27], s[26:27], 12
	s_add_u32 s26, s35, s26
	s_addc_u32 s27, s34, s27
	global_load_dwordx4 v[68:71], v[0:1], off nt
	global_load_dwordx4 v[60:63], v[0:1], off offset:1024 nt
	global_load_dwordx4 v[52:55], v[0:1], off offset:2048 nt
	global_load_dwordx4 v[48:51], v[0:1], off offset:3072 nt
	v_lshl_add_u64 v[0:1], s[26:27], 0, v[146:147]
	global_load_dwordx4 v[20:23], v[0:1], off nt
	global_load_dwordx4 v[8:11], v[0:1], off offset:1024 nt
	global_load_dwordx4 v[4:7], v[0:1], off offset:2048 nt
	s_nop 0
	global_load_dwordx4 v[0:3], v[0:1], off offset:3072 nt
	s_mov_b64 s[8:9], s[100:101]
	v_and_b32_e32 v217, 15, v144
	v_add_u32_e32 v152, s76, v144
	v_cmp_gt_u32_e32 vcc, 14, v217
	v_ashrrev_i32_e32 v218, 4, v152
	s_and_b64 s[34:35], s[4:5], vcc
	v_mov_b32_e32 v186, 0
	v_mov_b32_e32 v189, 0
	v_mov_b32_e32 v190, 0
	v_mov_b32_e32 v191, 0
	v_mov_b32_e32 v188, 0
	v_mov_b32_e32 v192, 0
	v_mov_b32_e32 v185, 0
	v_mov_b32_e32 v187, 0
	v_mov_b32_e32 v194, 0
	v_mov_b32_e32 v197, 0
	v_mov_b32_e32 v198, 0
	v_mov_b32_e32 v199, 0
	v_mov_b32_e32 v196, 0
	v_mov_b32_e32 v200, 0
	v_mov_b32_e32 v193, 0
	v_mov_b32_e32 v195, 0
	v_mov_b32_e32 v202, 0
	v_mov_b32_e32 v205, 0
	v_mov_b32_e32 v206, 0
	v_mov_b32_e32 v207, 0
	v_mov_b32_e32 v204, 0
	v_mov_b32_e32 v208, 0
	v_mov_b32_e32 v201, 0
	v_mov_b32_e32 v203, 0
	v_mov_b32_e32 v209, 0
	v_mov_b32_e32 v211, 0
	v_mov_b32_e32 v212, 0
	v_mov_b32_e32 v213, 0
	v_mov_b32_e32 v210, 0
	v_mov_b32_e32 v216, 0
	v_mov_b32_e32 v214, 0
	v_mov_b32_e32 v215, 0
	s_and_saveexec_b64 s[56:57], s[34:35]
	s_cbranch_execz .LBB0_133
	v_add_u32_e32 v56, s6, v217
	v_and_b32_e32 v58, 0xffffffe0, v56
	s_movk_i32 s26, 0x3ff
	v_cmp_lt_i32_e32 vcc, s26, v58
	s_and_saveexec_b64 s[26:27], vcc
	s_xor_b64 s[58:59], exec, s[26:27]
	s_cbranch_execz .LBB0_130
	s_movk_i32 s26, 0x7ff
	v_cmp_lt_u32_e32 vcc, s26, v56
	s_and_saveexec_b64 s[26:27], vcc
	s_xor_b64 s[60:61], exec, s[26:27]
	s_cbranch_execz .LBB0_127
	s_movk_i32 s26, 0xbff
	v_cmp_lt_u32_e32 vcc, s26, v56
	s_and_saveexec_b64 s[26:27], vcc
	s_xor_b64 s[62:63], exec, s[26:27]
	v_add_u32_e32 v57, 0xfffff600, v58
	s_andn2_saveexec_b64 s[62:63], s[62:63]
	s_cbranch_execz .LBB0_126
	v_add_u32_e32 v57, 0xfffff800, v56
	v_and_b32_e32 v58, 0x80, v56
	v_mov_b32_e32 v59, 0xa00
	v_mov_b32_e32 v64, 0x800
	v_cmp_eq_u32_e32 vcc, 0, v58
	v_lshrrev_b32_e32 v57, 1, v57
	v_and_b32_e32 v57, 0x7fffff80, v57
	v_cndmask_b32_e32 v58, v59, v64, vcc
	v_add_u32_e32 v57, v58, v57
	s_movk_i32 s26, 0x60
	v_and_or_b32 v57, v56, s26, v57

.LBB0_205:
	s_cmp_lt_i32 s21, 3
	s_mov_b64 s[4:5], 0
	s_cbranch_scc1 .LBB0_302
	s_mov_b64 s[4:5], s[0:1]
	v_mov_b32_e32 v0, v244
	s_mov_b64 s[4:5], s[100:101]
	s_andn2_b64 vcc, exec, s[10:11]
	s_cbranch_vccnz .LBB0_219
	v_mov_b32_e32 v0, 0x28000
	s_waitcnt lgkmcnt(0)
	global_load_dword v0, v0, s[4:5] offset:256 sc1
	s_movk_i32 s3, 0xff
	s_add_u32 s6, s4, 0x28100
	s_addc_u32 s7, s5, 0
	s_waitcnt vmcnt(0)
	v_cmp_lt_u32_e32 vcc, s3, v0
	s_cbranch_vccnz .LBB0_218
	s_mov_b32 s10, 0x3ffff8
	v_mov_b32_e32 v0, 0
	s_movk_i32 s11, 0x100
	s_branch .LBB0_210

.LBB0_291:
	s_mov_b64 s[4:5], 0
	s_and_b64 vcc, exec, s[6:7]
	s_cbranch_vccz .LBB0_301
	s_mov_b64 s[6:7], s[0:1]
	v_mov_b32_e32 v0, v244
	s_waitcnt vmcnt(0)
	s_nop 0
	v_sub_u32_e32 v0, 0, v0
	v_cmp_eq_u32_e32 vcc, s76, v0
	s_barrier
	s_and_saveexec_b64 s[4:5], vcc
	s_cbranch_execz .LBB0_300
	s_mov_b64 s[6:7], s[100:101]
	s_mov_b64 s[8:9], exec
	s_lshl_b32 s3, s2, 9
	s_and_b32 s3, s3, 0xe00
	v_mbcnt_lo_u32_b32 v0, s8, 0
	s_waitcnt lgkmcnt(0)
	s_add_u32 s6, s6, s3
	v_mbcnt_hi_u32_b32 v0, s9, v0
	s_addc_u32 s7, s7, 0
	v_cmp_eq_u32_e32 vcc, 0, v0
	s_and_saveexec_b64 s[10:11], vcc
	s_cbranch_execz .LBB0_295
	s_bcnt1_i32_b64 s3, s[8:9]
	s_waitcnt vmcnt(0)
	v_mov_b32_e32 v1, 0x34000
	v_mov_b32_e32 v2, s3
	global_atomic_add v1, v1, v2, s[6:7] sc0

.LBB0_301:
.LBB0_302:
	s_xor_b64 s[4:5], s[4:5], -1
	v_writelane_b32 v252, s4, 3
	s_cmp_lt_i32 s20, 3
	s_nop 0
	v_writelane_b32 v252, s5, 4
	s_cselect_b64 s[4:5], -1, 0
	s_cmp_gt_i32 s21, 2
	s_cselect_b64 s[6:7], -1, 0
	s_and_b64 s[4:5], s[4:5], s[6:7]
	s_andn2_b64 vcc, exec, s[4:5]
	s_cbranch_vccnz .LBB0_640
	s_mov_b64 s[4:5], s[0:1]
	v_mov_b32_e32 v0, v244
	s_mov_b64 s[6:7], s[100:101]
	v_add_u32_e32 v0, s76, v0
	s_waitcnt vmcnt(0)
	v_ashrrev_i32_e32 v1, 31, v0
	s_mov_b64 s[4:5], s[0:1]
	s_waitcnt lgkmcnt(0)
	v_lshl_add_u64 v[2:3], v[0:1], 2, s[6:7]
	v_add_co_u32_e32 v4, vcc, 0x136000, v2
	s_movk_i32 s3, 0x80
	s_nop 0
	v_addc_co_u32_e32 v5, vcc, 0, v3, vcc
	v_add_co_u32_e32 v6, vcc, 0x137000, v2
	s_nop 1
	v_addc_co_u32_e32 v7, vcc, 0, v3, vcc
	v_add_co_u32_e32 v8, vcc, 0x138000, v2
	s_nop 1
	v_addc_co_u32_e32 v9, vcc, 0, v3, vcc
	global_load_dword v10, v[4:5], off
	global_load_dword v11, v[4:5], off offset:2048
	global_load_dword v12, v[6:7], off
	global_load_dword v13, v[6:7], off offset:2048
	global_load_dword v1, v[8:9], off
	global_load_dword v2, v[8:9], off offset:2048
	v_lshl_add_u32 v3, v0, 2, 0
	v_add_u32_e32 v3, 0x20000, v3
	v_cmp_gt_i32_e32 vcc, s3, v0
	s_waitcnt vmcnt(4)
	ds_write2st64_b32 v3, v10, v11 offset1:8
	s_waitcnt vmcnt(2)
	ds_write2st64_b32 v3, v12, v13 offset0:16 offset1:24
	s_and_saveexec_b64 s[6:7], vcc
	s_cbranch_execz .LBB0_305
	s_load_dwordx2 s[4:5], s[4:5], 0x48
	v_and_b32_e32 v0, 0x7f, v0
	v_lshlrev_b32_e32 v0, 2, v0
	s_waitcnt lgkmcnt(0)
	global_load_dword v0, v0, s[4:5]
	s_waitcnt vmcnt(0)
	ds_write_b32 v3, v0 offset:8192
.LBB0_305:
	s_or_b64 exec, exec, s[6:7]
	v_mov_b32_e32 v8, v244
	s_mov_b64 s[4:5], s[0:1]
	s_waitcnt vmcnt(0)
	ds_write2st64_b32 v3, v1, v2 offset0:34 offset1:42
	s_waitcnt lgkmcnt(0)
	s_barrier
	s_mov_b64 s[4:5], s[100:101]
	s_lshl_b32 s3, s2, 3
	s_waitcnt lgkmcnt(0)
	s_add_u32 s18, s4, 0x1800000
	s_addc_u32 s19, s5, 0
	s_add_u32 s16, s4, 0x200000
	s_addc_u32 s17, s5, 0
	s_cmpk_gt_i32 s2, 0x37f
	s_cbranch_scc0 .LBB0_310
	s_cmpk_gt_u32 s2, 0x47f
	s_cbranch_scc0 .LBB0_311
	v_mov_b32_e32 v0, 0x4b0
	v_sub_co_u32_e32 v0, vcc, s2, v0
	s_and_b32 s6, s2, 7
	v_readfirstlane_b32 s4, v0
	s_andn2_b64 vcc, exec, vcc
	s_lshl_b32 s13, s6, 23
	s_cbranch_vccz .LBB0_312
	s_cmpk_gt_u32 s2, 0x4cf
	s_mov_b64 s[14:15], 0
	s_cbranch_scc1 .LBB0_313
	s_lshr_b32 s12, s4, 3
	s_add_i32 s4, s12, 14
	s_mov_b32 s5, 0
	s_lshl_b64 s[4:5], s[4:5], 19
	s_add_u32 s4, s16, s4
	s_addc_u32 s5, s17, s5
	s_add_u32 s7, s18, s13
	s_addc_u32 s9, s19, 0
	s_add_u32 s8, s7, 0x400000
	s_addc_u32 s9, s9, 0
	s_mov_b32 s7, 1
	s_mov_b32 s52, 5
	s_mov_b64 s[10:11], -1
	s_branch .LBB0_315

.LBB0_327:
	s_mov_b64 s[10:11], s[0:1]
	s_mov_b64 s[10:11], s[100:101]
	s_add_i32 s30, s30, 1
	s_mul_i32 s53, s30, s33
	s_add_i32 s53, s53, s2
	s_waitcnt lgkmcnt(0)
	s_add_u32 s50, s10, 0x1800000
	s_addc_u32 s51, s11, 0
	s_add_u32 s26, s10, 0x200000
	s_addc_u32 s27, s11, 0
	s_cmpk_gt_i32 s53, 0x37f
	s_mov_b64 s[10:11], -1
	s_cbranch_scc0 .LBB0_338
	s_cmpk_gt_u32 s53, 0x47f
	s_cbranch_scc0 .LBB0_335
	s_cmpk_gt_u32 s53, 0x4af
	s_cbranch_scc0 .LBB0_332
	s_mov_b64 s[10:11], 0
	s_cmpk_gt_u32 s53, 0x4cf
	s_mov_b64 s[48:49], 0
	s_cbranch_scc1 .LBB0_332
	s_add_i32 s16, s53, 0xfffffb50
	s_lshr_b32 s42, s16, 3
	s_add_i32 s16, s42, 14
	s_and_b32 s54, s53, 7
	s_lshl_b64 s[44:45], s[16:17], 19
	s_add_u32 s44, s26, s44
	s_addc_u32 s45, s27, s45
	s_lshl_b32 s16, s54, 23
	s_add_u32 s16, s50, s16
	s_addc_u32 s31, s51, 0
	s_add_u32 s46, s16, 0x400000
	s_addc_u32 s47, s31, 0
	s_mov_b32 s43, 1
	s_mov_b32 s31, 5
	s_mov_b64 s[48:49], -1
	s_mov_b32 s16, s54

.LBB0_346:
	v_mov_b32_e32 v128, v244
	s_mov_b64 s[4:5], s[0:1]
	s_mov_b64 s[8:9], s[100:101]
	v_and_b32_e32 v178, 15, v128
	v_ashrrev_i32_e32 v165, 4, v128
	s_cmp_gt_u32 s52, 1
	s_mov_b64 s[4:5], -1
	s_cbranch_scc0 .LBB0_413
	s_cmp_gt_u32 s52, 3
	s_cbranch_scc0 .LBB0_377
	s_cmp_eq_u32 s52, 4
	v_lshlrev_b32_e32 v128, 3, v165
	s_cbranch_scc1 .LBB0_350
	s_lshl_b32 s4, s12, 8
	s_lshl_b32 s10, s6, 8
	s_add_i32 s53, s4, s59
	s_and_b32 s10, s10, 0x700
	s_bfe_u32 s4, s53, 0x20007
	s_ashr_i32 s5, s6, 3
	s_addk_i32 s10, 0x100
	s_cmp_eq_u32 s7, 0
	s_cselect_b32 s5, s5, s6
	s_cselect_b32 s10, s10, 0
	s_lshl_b32 s54, s5, 2
	v_or_b32_e32 v138, s53, v178
	s_or_b32 s4, s4, s54
	v_cmp_gt_i32_e32 vcc, s65, v138
	s_ashr_i32 s5, s4, 31
	v_and_b32_e32 v132, 0x4f, v138
	v_cndmask_b32_e32 v152, v173, v174, vcc
	s_lshl_b64 s[50:51], s[4:5], 7
	s_waitcnt lgkmcnt(0)
	v_lshl_add_u64 v[130:131], s[8:9], 0, v[152:153]
	v_or_b32_e32 v132, s50, v132
	v_mad_u64_u32 v[130:131], s[4:5], v132, s66, v[130:131]
	v_mad_i32_i24 v131, s51, v175, v131
	s_lshl_b32 s4, s10, 1
	s_mov_b32 s5, s17
	v_ashrrev_i32_e32 v129, 31, v128
	v_lshl_add_u64 v[130:131], v[130:131], 0, s[4:5]
	s_lshl_b32 s10, s60, 1
	s_mov_b32 s11, s17
	v_lshl_add_u64 v[130:131], v[130:131], 0, s[10:11]
	v_lshlrev_b64 v[134:135], 1, v[128:129]
	v_or_b32_e32 v129, 16, v138
	v_lshl_add_u64 v[136:137], v[130:131], 0, v[134:135]
	v_cvt_pk_bf16_f32 v130, v124, v125
	v_cvt_pk_bf16_f32 v131, v126, v127
	v_cvt_pk_bf16_f32 v132, v120, v121
	v_cvt_pk_bf16_f32 v133, v122, v123
	v_cmp_gt_i32_e32 vcc, s65, v129
	global_store_dwordx4 v[136:137], v[130:133], off
	v_bitop3_b32 v129, v138, s67, 16 bitop3:0xc8
	v_cndmask_b32_e32 v152, v173, v174, vcc
	v_cvt_pk_bf16_f32 v130, v116, v117
	v_cvt_pk_bf16_f32 v131, v118, v119
	v_cvt_pk_bf16_f32 v132, v112, v113
	v_cvt_pk_bf16_f32 v133, v114, v115
	global_store_dwordx4 v[136:137], v[130:133], off offset:256
	v_or_b32_e32 v129, s50, v129
	s_addk_i32 s53, 0x80
	v_lshl_add_u64 v[130:131], s[8:9], 0, v[152:153]
	v_mad_u64_u32 v[130:131], s[26:27], v129, s66, v[130:131]
	v_mad_i32_i24 v131, s51, v175, v131
	v_lshl_add_u64 v[130:131], v[130:131], 0, s[4:5]
	v_lshl_add_u64 v[130:131], v[130:131], 0, s[10:11]
	v_or_b32_e32 v129, 32, v138
	v_lshl_add_u64 v[136:137], v[130:131], 0, v[134:135]
	v_cvt_pk_bf16_f32 v130, v108, v109
	v_cvt_pk_bf16_f32 v131, v110, v111
	v_cvt_pk_bf16_f32 v132, v104, v105
	v_cvt_pk_bf16_f32 v133, v106, v107
	v_cmp_gt_i32_e32 vcc, s65, v129
	global_store_dwordx4 v[136:137], v[130:133], off
	v_bitop3_b32 v129, v138, s68, 32 bitop3:0xc8
	v_cndmask_b32_e32 v152, v173, v174, vcc
	v_cvt_pk_bf16_f32 v130, v100, v101
	v_cvt_pk_bf16_f32 v131, v102, v103
	v_cvt_pk_bf16_f32 v132, v96, v97
	v_cvt_pk_bf16_f32 v133, v98, v99
	global_store_dwordx4 v[136:137], v[130:133], off offset:256
	v_or_b32_e32 v129, s50, v129
	s_nop 0
	v_lshl_add_u64 v[130:131], s[8:9], 0, v[152:153]
	v_mad_u64_u32 v[130:131], s[26:27], v129, s66, v[130:131]
	v_mad_i32_i24 v131, s51, v175, v131
	v_lshl_add_u64 v[130:131], v[130:131], 0, s[4:5]
	v_lshl_add_u64 v[130:131], v[130:131], 0, s[10:11]
	v_or_b32_e32 v129, 48, v138
	v_lshl_add_u64 v[136:137], v[130:131], 0, v[134:135]
	v_cvt_pk_bf16_f32 v130, v92, v93
	v_cvt_pk_bf16_f32 v131, v94, v95
	v_cvt_pk_bf16_f32 v132, v88, v89
	v_cvt_pk_bf16_f32 v133, v90, v91
	v_cmp_gt_i32_e32 vcc, s65, v129
	global_store_dwordx4 v[136:137], v[130:133], off
	v_bitop3_b32 v129, v138, s69, 48 bitop3:0xc8
	v_cndmask_b32_e32 v152, v173, v174, vcc
	v_cvt_pk_bf16_f32 v130, v84, v85
	v_cvt_pk_bf16_f32 v131, v86, v87
	v_cvt_pk_bf16_f32 v132, v80, v81
	v_cvt_pk_bf16_f32 v133, v82, v83
	global_store_dwordx4 v[136:137], v[130:133], off offset:256
	v_or_b32_e32 v129, s50, v129
	s_nop 0
	v_lshl_add_u64 v[130:131], s[8:9], 0, v[152:153]
	v_mad_u64_u32 v[130:131], s[26:27], v129, s66, v[130:131]
	v_mad_i32_i24 v131, s51, v175, v131
	v_lshl_add_u64 v[130:131], v[130:131], 0, s[4:5]
	v_lshl_add_u64 v[130:131], v[130:131], 0, s[10:11]
	s_bfe_u32 s26, s53, 0x20007
	v_lshl_add_u64 v[136:137], v[130:131], 0, v[134:135]
	v_cvt_pk_bf16_f32 v130, v76, v77
	v_cvt_pk_bf16_f32 v131, v78, v79
	v_cvt_pk_bf16_f32 v132, v72, v73
	v_cvt_pk_bf16_f32 v133, v74, v75
	v_or_b32_e32 v129, s53, v178
	s_or_b32 s26, s26, s54
	global_store_dwordx4 v[136:137], v[130:133], off
	v_cmp_gt_i32_e32 vcc, s65, v129
	s_ashr_i32 s27, s26, 31
	v_cvt_pk_bf16_f32 v130, v68, v69
	v_cvt_pk_bf16_f32 v131, v70, v71
	v_cvt_pk_bf16_f32 v132, v64, v65
	v_cvt_pk_bf16_f32 v133, v66, v67
	global_store_dwordx4 v[136:137], v[130:133], off offset:256
	v_cndmask_b32_e32 v152, v173, v174, vcc
	s_lshl_b64 s[50:51], s[26:27], 7
	v_and_b32_e32 v132, 0x4f, v129
	v_lshl_add_u64 v[130:131], s[8:9], 0, v[152:153]
	v_or_b32_e32 v132, s50, v132
	v_mad_u64_u32 v[130:131], s[26:27], v132, s66, v[130:131]
	v_mad_i32_i24 v131, s51, v175, v131
	v_lshl_add_u64 v[130:131], v[130:131], 0, s[4:5]
	v_lshl_add_u64 v[130:131], v[130:131], 0, s[10:11]
	v_lshl_add_u64 v[136:137], v[130:131], 0, v[134:135]
	v_cvt_pk_bf16_f32 v130, v60, v61
	v_cvt_pk_bf16_f32 v131, v62, v63
	v_cvt_pk_bf16_f32 v132, v56, v57
	v_cvt_pk_bf16_f32 v133, v58, v59
	global_store_dwordx4 v[136:137], v[130:133], off
	s_nop 1
	v_cvt_pk_bf16_f32 v130, v52, v53
	v_cvt_pk_bf16_f32 v131, v54, v55
	v_cvt_pk_bf16_f32 v132, v48, v49
	v_cvt_pk_bf16_f32 v133, v50, v51
	global_store_dwordx4 v[136:137], v[130:133], off offset:256
	s_nop 1
	v_or_b32_e32 v130, 16, v129
	v_cmp_gt_i32_e32 vcc, s65, v130
	v_bitop3_b32 v132, v129, s67, 16 bitop3:0xc8
	v_or_b32_e32 v132, s50, v132
	v_cndmask_b32_e32 v152, v173, v174, vcc
	v_lshl_add_u64 v[130:131], s[8:9], 0, v[152:153]
	v_mad_u64_u32 v[130:131], s[26:27], v132, s66, v[130:131]
	v_mad_i32_i24 v131, s51, v175, v131
	v_lshl_add_u64 v[130:131], v[130:131], 0, s[4:5]
	v_lshl_add_u64 v[130:131], v[130:131], 0, s[10:11]
	v_lshl_add_u64 v[136:137], v[130:131], 0, v[134:135]
	v_cvt_pk_bf16_f32 v130, v44, v45
	v_cvt_pk_bf16_f32 v131, v46, v47
	v_cvt_pk_bf16_f32 v132, v40, v41
	v_cvt_pk_bf16_f32 v133, v42, v43
	global_store_dwordx4 v[136:137], v[130:133], off
	s_nop 1
	v_cvt_pk_bf16_f32 v130, v36, v37
	v_cvt_pk_bf16_f32 v131, v38, v39
	v_cvt_pk_bf16_f32 v132, v32, v33
	v_cvt_pk_bf16_f32 v133, v34, v35
	global_store_dwordx4 v[136:137], v[130:133], off offset:256
	s_nop 1
	v_or_b32_e32 v130, 32, v129
	v_cmp_gt_i32_e32 vcc, s65, v130
	v_bitop3_b32 v132, v129, s68, 32 bitop3:0xc8
	v_or_b32_e32 v132, s50, v132
	v_cndmask_b32_e32 v152, v173, v174, vcc
	v_lshl_add_u64 v[130:131], s[8:9], 0, v[152:153]
	v_mad_u64_u32 v[130:131], s[26:27], v132, s66, v[130:131]
	v_mad_i32_i24 v131, s51, v175, v131
	v_lshl_add_u64 v[130:131], v[130:131], 0, s[4:5]
	v_lshl_add_u64 v[130:131], v[130:131], 0, s[10:11]
	v_lshl_add_u64 v[136:137], v[130:131], 0, v[134:135]
	v_cvt_pk_bf16_f32 v130, v28, v29
	v_cvt_pk_bf16_f32 v131, v30, v31
	v_cvt_pk_bf16_f32 v132, v24, v25
	v_cvt_pk_bf16_f32 v133, v26, v27
	global_store_dwordx4 v[136:137], v[130:133], off
	s_nop 1
	v_cvt_pk_bf16_f32 v130, v20, v21
	v_cvt_pk_bf16_f32 v131, v22, v23
	v_cvt_pk_bf16_f32 v132, v16, v17
	v_cvt_pk_bf16_f32 v133, v18, v19
	global_store_dwordx4 v[136:137], v[130:133], off offset:256
	s_nop 1
	v_or_b32_e32 v130, 48, v129
	v_cmp_gt_i32_e32 vcc, s65, v130
	v_bitop3_b32 v129, v129, s69, 48 bitop3:0xc8
	v_or_b32_e32 v129, s50, v129
	v_cndmask_b32_e32 v152, v173, v174, vcc
	v_lshl_add_u64 v[130:131], s[8:9], 0, v[152:153]
	v_mad_u64_u32 v[130:131], s[26:27], v129, s66, v[130:131]
	v_mad_i32_i24 v131, s51, v175, v131
	v_lshl_add_u64 v[130:131], v[130:131], 0, s[4:5]
	v_lshl_add_u64 v[130:131], v[130:131], 0, s[10:11]
	v_lshl_add_u64 v[134:135], v[130:131], 0, v[134:135]
	v_cvt_pk_bf16_f32 v130, v12, v13
	v_cvt_pk_bf16_f32 v131, v14, v15
	v_cvt_pk_bf16_f32 v132, v8, v9
	v_cvt_pk_bf16_f32 v133, v10, v11
	global_store_dwordx4 v[134:135], v[130:133], off
	s_mov_b64 s[4:5], 0
	s_nop 0
	v_cvt_pk_bf16_f32 v130, v4, v5
	v_cvt_pk_bf16_f32 v131, v6, v7
	v_cvt_pk_bf16_f32 v132, v0, v1
	v_cvt_pk_bf16_f32 v133, v2, v3
	global_store_dwordx4 v[134:135], v[130:133], off offset:256

.LBB0_506:
	s_mov_b64 s[8:9], s[0:1]
	v_mov_b32_e32 v16, v244
	s_mov_b64 s[4:5], s[100:101]
	s_add_i32 s3, s3, s75
	s_addk_i32 s3, 0xf980
	s_cmpk_gt_i32 s3, 0x8ff
	s_cbranch_scc1 .LBB0_561
	s_lshl_b32 s6, s75, 14
	s_load_dwordx4 s[12:15], s[8:9], 0x38
	s_load_dwordx4 s[16:19], s[8:9], 0x70
	v_ashrrev_i32_e32 v17, 5, v16
	v_lshlrev_b32_e32 v0, 2, v16
	s_movk_i32 s8, 0x84
	s_add_i32 s6, s6, 0
	v_and_b32_e32 v12, 0x7c, v0
	v_mul_lo_u32 v2, v17, s8
	v_add3_u32 v18, s6, v12, v2
	v_lshlrev_b32_e32 v2, 3, v16
	v_mov_b32_e32 v13, 0
	v_and_b32_e32 v2, 56, v2
	v_mul_u32_u24_e32 v4, 0x84, v2
	v_lshlrev_b32_e32 v2, 1, v2
	v_mov_b32_e32 v3, v13
	s_waitcnt lgkmcnt(0)
	v_lshl_add_u64 v[14:15], s[4:5], 0, v[2:3]
	s_mov_b64 s[8:9], 0x1400000
	v_ashrrev_i32_e32 v19, 3, v16
	v_lshl_add_u64 v[2:3], v[14:15], 0, s[8:9]
	s_mov_b64 s[8:9], 0xd00000
	s_addk_i32 s3, 0xb00
	v_lshlrev_b32_e32 v5, 2, v19
	v_lshl_add_u64 v[6:7], v[14:15], 0, s[8:9]
	s_mov_b64 s[8:9], 0xb00000
	v_add3_u32 v20, s6, v4, v5
	v_lshl_add_u64 v[10:11], v[14:15], 0, s[8:9]
	s_mov_b64 s[8:9], 0x200000
	s_lshl_b32 s6, s3, 5
	s_mov_b32 s7, 0
	v_lshl_add_u64 v[0:1], s[18:19], 0, v[12:13]
	v_add_u32_e32 v21, 8, v19
	v_add_u32_e32 v22, 16, v19
	v_add_u32_e32 v23, 24, v19
	v_lshl_add_u64 v[4:5], s[16:17], 0, v[12:13]
	v_lshl_add_u64 v[8:9], s[14:15], 0, v[12:13]
	v_lshl_add_u64 v[12:13], s[12:13], 0, v[12:13]
	v_lshl_add_u64 v[14:15], v[14:15], 0, s[8:9]
	s_add_i32 s10, s6, 0xfffffa00
	s_lshl_b32 s11, s3, 6
	s_lshl_b32 s12, s3, 1
	s_movk_i32 s13, 0x800
	s_movk_i32 s14, 0xc00
	s_movk_i32 s15, 0x3800
	s_movk_i32 s16, 0x4800
	v_add_u32_e32 v24, 0x400, v18
	v_add_u32_e32 v25, 0x800, v18
	v_add_u32_e32 v26, 0xc00, v18
	v_add_u32_e32 v27, 0x1000, v18
	v_add_u32_e32 v28, 0x1400, v18
	v_add_u32_e32 v29, 0x1800, v18
	v_add_u32_e32 v30, 0x1c00, v18
	s_branch .LBB0_510

.LBB0_629:
	s_and_b64 vcc, exec, s[4:5]
	s_cbranch_vccz .LBB0_639
	s_mov_b64 s[6:7], s[0:1]
	v_mov_b32_e32 v0, v244
	s_waitcnt vmcnt(0)
	s_waitcnt vmcnt(0)
	v_sub_u32_e32 v0, 0, v0
	v_cmp_eq_u32_e32 vcc, s76, v0
	s_barrier
	s_and_saveexec_b64 s[4:5], vcc
	s_cbranch_execz .LBB0_638
	s_mov_b64 s[6:7], s[100:101]
	s_mov_b64 s[8:9], exec
	s_lshl_b32 s3, s2, 9
	s_and_b32 s3, s3, 0xe00
	v_mbcnt_lo_u32_b32 v0, s8, 0
	s_waitcnt lgkmcnt(0)
	s_add_u32 s6, s6, s3
	v_mbcnt_hi_u32_b32 v0, s9, v0
	s_addc_u32 s7, s7, 0
	v_cmp_eq_u32_e32 vcc, 0, v0
	s_and_saveexec_b64 s[10:11], vcc
	s_cbranch_execz .LBB0_633
	s_bcnt1_i32_b64 s3, s[8:9]
	v_mov_b32_e32 v1, 0x33000
	v_mov_b32_e32 v2, s3
	global_atomic_add v1, v1, v2, s[6:7] sc0

.LBB0_640:
	s_cmp_lt_i32 s20, 4
	s_cselect_b64 s[4:5], -1, 0
	s_cmp_gt_i32 s21, 3
	s_cselect_b64 s[6:7], -1, 0
	s_and_b64 s[4:5], s[4:5], s[6:7]
	s_andn2_b64 vcc, exec, s[4:5]
	s_cbranch_vccnz .LBB0_807
	s_mov_b64 s[4:5], s[0:1]
	v_mov_b32_e32 v0, v244
	s_mov_b64 s[4:5], s[100:101]
	v_mov_b32_e32 v0, 0x139000
	s_and_b32 s28, s2, 7
	s_waitcnt lgkmcnt(0)
	global_load_dword v1, v0, s[4:5] sc1
	global_load_dword v2, v0, s[4:5] offset:4 sc1
	s_bfe_u32 s3, s74, 0x20006
	s_lshl_b32 s8, s75, 7
	s_sub_i32 s9, s33, s28
	s_lshl_b32 s10, s3, 5
	s_lshl_b32 s65, s3, 4
	s_add_i32 s79, s8, 0
	s_lshl_b32 s3, s3, 14
	s_add_i32 s8, s9, 7
	s_add_i32 s80, s3, 0
	s_ashr_i32 s3, s8, 31
	s_lshl_b32 s7, s75, 11
	s_lshr_b32 s3, s3, 29
	s_lshr_b32 s6, s74, 8
	s_add_i32 s67, s7, 0
	s_add_i32 s8, s8, s3
	s_ashr_i32 s29, s2, 3
	s_lshl_b32 s64, s75, 4
	s_lshl_b32 s31, s28, 6
	s_lshl_b32 s66, s6, 6
	s_lshl_b32 s68, s6, 13
	s_lshl_b32 s69, s6, 4
	s_add_i32 s70, s67, 0x4000
	s_add_i32 s71, s67, 0x8000
	s_add_i32 s72, s67, 0x8400
	s_add_i32 s73, s67, 0xc000
	s_add_i32 s78, s67, 0xc400
	s_add_i32 s79, s79, 0x20000
	s_add_i32 s80, s80, 0x10000
	s_ashr_i32 s3, s8, 3
	s_cmpk_lt_u32 s74, 0x100
	s_cselect_b64 s[46:47], -1, 0
	s_cmp_eq_u32 s6, 1
	v_writelane_b32 v252, s24, 5
	s_cselect_b64 s[48:49], -1, 0
	s_lshl_b32 s6, s75, 5
	s_and_b32 s82, s75, 0x3fffffc
	s_and_b32 s83, s64, 0x3fffffc0
	v_writelane_b32 v252, s25, 6
	s_mov_b64 s[24:25], s[84:85]
	s_lshl_b32 s81, s28, 3
	s_or_b32 s84, s75, 3
	s_and_b32 s85, s6, 0x60
	s_or_b32 s86, s82, 1
	s_or_b32 s87, s82, 2
	s_or_b32 s88, s83, 32
	s_cmp_lt_u32 s74, 64
	s_mul_i32 s7, s28, 0x120000
	s_cselect_b64 s[44:45], -1, 0
	s_lshl_b32 s62, s28, 11
	s_mov_b32 s35, 0
	s_movk_i32 s63, 0xc8
	s_mov_b64 s[4:5], -1
	s_mov_b64 s[36:37], 0x10000
	s_movk_i32 s30, 0x1200
	v_mov_b32_e32 v145, 0
	s_mov_b64 s[38:39], 0x80
	s_mov_b64 s[40:41], 0x20000
	s_mov_b64 s[42:43], 0x100
	v_mov_b32_e32 v147, 1
	s_lshl_b32 s51, s28, 9
	s_add_i32 s89, 0, 0x27c40
	s_or_b32 s90, s62, s10
	s_add_i32 s91, 0, 0x19000
	s_add_i32 s92, 0, 0x1a000
	s_add_i32 s93, 0, 0x1b000
	s_brev_b32 s50, 60
	s_mov_b32 s94, 0x800000
	v_mov_b32_e32 v151, 0x20000
	s_lshl_b32 s95, s7, 1
	v_mov_b32_e32 v155, 0x1200
	s_waitcnt vmcnt(0)
	v_cndmask_b32_e64 v149, v1, 1.0, s[46:47]
	v_xor_b32_e32 v0, 0x80000000, v2
	v_mov_b32_e32 v1, v0
	v_mov_b32_e32 v2, v0
	v_mov_b32_e32 v3, v0
	v_mov_b32_e32 v4, v0
	v_mov_b32_e32 v5, v0
	v_mov_b32_e32 v6, v0
	v_mov_b32_e32 v7, v0
	v_mov_b32_e32 v8, v0
	v_mov_b32_e32 v9, v0
	v_mov_b32_e32 v10, v0
	v_mov_b32_e32 v11, v0
	v_mov_b32_e32 v12, v0
	v_mov_b32_e32 v13, v0
	v_mov_b32_e32 v14, v0
	v_mov_b32_e32 v15, v0
	s_branch .LBB0_644

.LBB0_646:
	s_cmpk_gt_i32 s58, 0x47
	s_cselect_b64 s[52:53], -1, 0
	s_mov_b64 s[4:5], s[0:1]
	s_and_b64 vcc, exec, s[52:53]
	s_cbranch_vccnz .LBB0_642
	s_mov_b64 s[4:5], s[100:101]
	s_lshl_b32 s6, s31, 2
	s_waitcnt lgkmcnt(0)
	s_add_u32 s4, s4, s6
	s_addc_u32 s5, s5, 0
	s_add_u32 s54, s4, 0x10000
	s_addc_u32 s55, s5, 0
	s_cmp_gt_i32 s58, 7
	s_mov_b64 s[4:5], -1
	s_cbranch_scc0 .LBB0_661
	s_mov_b64 s[8:9], s[0:1]
	s_mov_b64 s[4:5], s[100:101]
	s_add_i32 s10, s58, -8
	v_mov_b32_e32 v146, v244
	s_load_dwordx2 s[8:9], s[8:9], 0x58
	s_waitcnt lgkmcnt(0)
	s_add_u32 s6, s4, 0x5800000
	s_addc_u32 s7, s5, 0
	s_lshl_b32 s11, s10, 7
	s_and_b32 s11, s11, 0x780
	v_ashrrev_i32_e32 v24, 3, v146
	v_lshrrev_b32_e32 v19, 4, v146
	s_or_b32 s59, s11, s90
	v_add_u32_e32 v16, s65, v24
	v_xor_b32_e32 v19, v19, v146
	s_add_u32 s11, s4, s95
	v_add_u32_e32 v18, 8, v16
	v_lshlrev_b32_e32 v19, 3, v19
	s_addc_u32 s12, s5, 0
	s_lshl_b32 s10, s10, 3
	v_and_b32_e32 v26, 56, v19
	v_ashrrev_i32_e32 v19, 31, v18
	s_and_b32 s60, s10, 0x7fffff80
	v_lshlrev_b64 v[20:21], 10, v[18:19]
	v_lshrrev_b32_e32 v18, 1, v18
	s_lshl_b32 s34, s60, 1
	v_xor_b32_e32 v18, v18, v146
	s_add_u32 s16, s11, s34
	v_lshlrev_b32_e32 v18, 3, v18
	s_addc_u32 s17, s12, 0
	v_and_b32_e32 v30, 56, v18
	v_add_u32_e32 v18, s64, v24
	s_add_u32 s12, s16, 0x7800000
	v_ashrrev_i32_e32 v17, 31, v16
	v_add_u32_e32 v31, 8, v18
	s_addc_u32 s13, s17, 0
	s_add_i32 s10, s51, s60
	v_lshlrev_b64 v[16:17], 10, v[16:17]
	v_lshrrev_b32_e32 v27, 1, v31
	v_or_b32_e32 v29, s66, v26
	s_mulk_i32 s10, 0x900
	s_mov_b32 s11, s35
	v_xor_b32_e32 v27, v27, v146
	v_lshl_add_u32 v156, v29, 1, v16
	v_or_b32_e32 v29, s66, v30
	v_and_b32_e32 v152, 31, v146
	s_lshl_b64 s[10:11], s[10:11], 1
	v_lshl_add_u64 v[22:23], s[12:13], 0, v[20:21]
	v_lshl_add_u32 v154, v29, 1, v20
	v_lshlrev_b32_e32 v20, 4, v27
	s_add_u32 s14, s4, s10
	v_mul_lo_u32 v21, v18, s30
	v_lshlrev_b32_e32 v144, 1, v26
	v_and_b32_e32 v26, 0x70, v20
	v_or_b32_e32 v20, s59, v152
	s_addc_u32 s15, s5, s11
	v_or_b32_e32 v150, v144, v21
	v_lshlrev_b32_e32 v20, 11, v20
	v_mov_b32_e32 v21, v145
	v_ashrrev_i32_e32 v153, 5, v146
	s_add_u32 s10, s14, 0x8a00000
	v_mul_lo_u32 v28, v31, s30
	v_lshl_add_u64 v[20:21], s[6:7], 0, v[20:21]
	s_addc_u32 s11, s15, 0
	v_or_b32_e32 v148, v26, v28
	v_lshl_add_u64 v[20:21], v[20:21], 0, s[34:35]
	s_lshl_b32 s34, s66, 1
	v_lshlrev_b32_e32 v28, 3, v153
	v_lshl_add_u64 v[20:21], v[20:21], 0, s[34:35]
	v_ashrrev_i32_e32 v29, 31, v28
	v_lshl_add_u64 v[28:29], v[28:29], 1, v[20:21]
	global_load_dwordx4 v[124:127], v[28:29], off
	global_load_dwordx4 v[120:123], v[28:29], off offset:32
	global_load_dwordx4 v[116:119], v[28:29], off offset:64
	global_load_dwordx4 v[112:115], v[28:29], off offset:96
	v_lshl_add_u64 v[16:17], s[12:13], 0, v[16:17]
	v_lshl_add_u64 v[16:17], v[16:17], 0, s[34:35]
	v_mov_b64_e32 v[24:25], s[10:11]
	v_lshl_add_u64 v[20:21], v[16:17], 0, v[144:145]
	v_lshl_add_u64 v[16:17], v[22:23], 0, s[34:35]
	v_lshlrev_b32_e32 v22, 1, v30
	v_mov_b32_e32 v23, v145
	v_mad_i64_i32 v[18:19], s[18:19], v18, s30, v[24:25]
	v_mov_b32_e32 v27, v145
	v_lshl_add_u64 v[22:23], v[16:17], 0, v[22:23]
	v_mad_i64_i32 v[16:17], s[18:19], v31, s30, v[24:25]
	s_mov_b32 s61, 1
	v_lshl_add_u64 v[18:19], v[18:19], 0, v[144:145]
	v_lshl_add_u64 v[16:17], v[16:17], 0, v[26:27]
	v_lshlrev_b32_e32 v25, 1, v146
	v_lshrrev_b32_e32 v56, 1, v146
	s_mov_b32 s18, m0
	s_mov_b32 m0, s67
	s_nop 0
	global_load_lds_dwordx4 v[20:21], off
	s_mov_b32 m0, s18
	v_and_b32_e32 v24, 19, v146
	v_and_b32_e32 v25, 8, v25
	v_and_b32_e32 v26, 4, v56
	s_add_i32 s18, s67, 0x400
	s_mov_b32 s19, m0
	s_mov_b32 m0, s18
	s_nop 0
	global_load_lds_dwordx4 v[22:23], off
	s_mov_b32 m0, s19
	v_or3_b32 v24, v25, v24, v26
	s_mov_b32 s18, m0
	s_mov_b32 m0, s70
	s_nop 0
	global_load_lds_dwordx4 v[18:19], off
	s_mov_b32 m0, s18
	v_lshrrev_b32_e32 v58, 1, v24
	s_add_i32 s18, s67, 0x4400
	s_mov_b32 s19, m0
	s_mov_b32 m0, s18
	s_nop 0
	global_load_lds_dwordx4 v[16:17], off
	s_mov_b32 m0, s19
	v_lshl_or_b32 v57, v24, 7, s68
	v_bitop3_b32 v24, v58, v153, 7 bitop3:0x6c
	v_lshl_add_u32 v144, v24, 4, v57
	s_waitcnt vmcnt(0) lgkmcnt(0)
	s_barrier
	s_waitcnt vmcnt(3)
	s_waitcnt vmcnt(2)
	s_waitcnt vmcnt(1)
	s_waitcnt vmcnt(0)
	v_lshl_add_u64 v[24:25], v[20:21], 0, s[36:37]
	s_mov_b32 s18, m0
	s_mov_b32 m0, s71
	s_nop 0
	global_load_lds_dwordx4 v[24:25], off
	s_mov_b32 m0, s18
	v_lshl_add_u64 v[24:25], v[22:23], 0, s[36:37]
	s_mov_b32 s18, m0
	s_mov_b32 m0, s72
	s_nop 0
	global_load_lds_dwordx4 v[24:25], off
	s_mov_b32 m0, s18
	v_lshl_add_u64 v[24:25], v[18:19], 0, s[38:39]
	s_mov_b32 s18, m0
	s_mov_b32 m0, s73
	s_nop 0
	global_load_lds_dwordx4 v[24:25], off
	s_mov_b32 m0, s18
	v_lshl_add_u64 v[24:25], v[16:17], 0, s[38:39]
	s_mov_b32 s18, m0
	s_mov_b32 m0, s78
	s_nop 0
	global_load_lds_dwordx4 v[24:25], off
	s_mov_b32 m0, s18
	v_lshl_add_u64 v[20:21], v[20:21], 0, s[40:41]
	s_add_i32 s18, s67, 0x10000
	s_mov_b32 s19, m0
	s_mov_b32 m0, s18
	s_nop 0
	global_load_lds_dwordx4 v[20:21], off
	s_mov_b32 m0, s19
	v_lshl_add_u64 v[20:21], v[22:23], 0, s[40:41]
	s_add_i32 s18, s67, 0x10400
	s_mov_b32 s19, m0
	s_mov_b32 m0, s18
	s_nop 0
	global_load_lds_dwordx4 v[20:21], off
	s_mov_b32 m0, s19
	v_lshl_add_u64 v[18:19], v[18:19], 0, s[42:43]
	s_add_i32 s18, s67, 0x14000
	s_mov_b32 s19, m0
	s_mov_b32 m0, s18
	s_nop 0
	global_load_lds_dwordx4 v[18:19], off
	s_mov_b32 m0, s19
	v_lshl_add_u64 v[16:17], v[16:17], 0, s[42:43]
	s_add_i32 s18, s67, 0x14400
	s_mov_b32 s19, m0
	s_mov_b32 m0, s18
	s_nop 0
	global_load_lds_dwordx4 v[16:17], off
	s_mov_b32 m0, s19
	v_add_u32_e32 v16, 0, v144
	ds_read_b128 v[32:35], v16
	ds_read_b128 v[48:51], v16 offset:4096
	s_waitcnt lgkmcnt(1)
	v_mfma_f32_32x32x16_bf16 v[16:31], v[32:35], v[124:127], v[0:15]
	v_add_u32_e32 v59, 2, v153
	v_bitop3_b32 v32, v58, v59, 7 bitop3:0x6c
	v_lshl_add_u32 v157, v32, 4, v57
	v_add_u32_e32 v52, 0, v157
	v_add_u32_e32 v60, 4, v153
	v_add_u32_e32 v61, 6, v153
	s_add_u32 s14, s14, 0x8a00180
	s_waitcnt lgkmcnt(0)
	v_mfma_f32_32x32x16_bf16 v[32:47], v[48:51], v[124:127], v[0:15]
	ds_read_b128 v[48:51], v52
	ds_read_b128 v[52:55], v52 offset:4096
	s_addc_u32 s15, s15, 0
	v_lshlrev_b32_e32 v166, 7, v152
	s_add_u32 s16, s16, 0x7830000
	v_mov_b32_e32 v158, 0
	s_addc_u32 s17, s17, 0
	s_movk_i32 s96, 0x100
	s_waitcnt lgkmcnt(1)
	v_mfma_f32_32x32x16_bf16 v[16:31], v[48:51], v[120:123], v[16:31]
	v_bitop3_b32 v48, v58, v60, 7 bitop3:0x6c
	v_lshl_add_u32 v159, v48, 4, v57
	s_mov_b32 s97, 0x20000
	v_mov_b32_e32 v62, v158
	v_mov_b32_e32 v63, v158
	v_mov_b32_e32 v64, 0
	v_mov_b32_e32 v65, v158
	s_waitcnt lgkmcnt(0)
	v_mfma_f32_32x32x16_bf16 v[32:47], v[52:55], v[120:123], v[32:47]
	v_add_u32_e32 v52, 0, v159
	ds_read_b128 v[48:51], v52
	ds_read_b128 v[52:55], v52 offset:4096
	v_mov_b32_e32 v66, v158
	v_mov_b32_e32 v67, v158
	v_mov_b32_e32 v68, v158
	v_mov_b32_e32 v69, v158
	v_mov_b32_e32 v70, v158
	s_waitcnt lgkmcnt(1)
	v_mfma_f32_32x32x16_bf16 v[16:31], v[48:51], v[116:119], v[16:31]
	v_bitop3_b32 v48, v58, v61, 7 bitop3:0x6c
	v_lshl_add_u32 v160, v48, 4, v57
	v_bitop3_b32 v57, v56, v153, 7 bitop3:0x6c
	v_lshlrev_b32_e32 v162, 4, v57
	v_add_u32_e32 v167, v162, v166
	v_mov_b32_e32 v57, v158
	v_mov_b32_e32 v58, v158
	s_waitcnt lgkmcnt(0)
	v_mfma_f32_32x32x16_bf16 v[32:47], v[52:55], v[116:119], v[32:47]
	v_add_u32_e32 v52, 0, v160
	ds_read_b128 v[48:51], v52
	ds_read_b128 v[52:55], v52 offset:4096
	v_mov_b32_e32 v71, v158
	v_mov_b32_e32 v72, v158
	v_mov_b32_e32 v73, v158
	v_mov_b32_e32 v74, v158
	s_waitcnt lgkmcnt(1)
	v_mfma_f32_32x32x16_bf16 v[16:31], v[48:51], v[112:115], v[16:31]
	v_bitop3_b32 v48, v59, v56, 7 bitop3:0x78
	v_lshlrev_b32_e32 v163, 4, v48
	v_bitop3_b32 v48, v60, v56, 7 bitop3:0x78
	v_lshlrev_b32_e32 v164, 4, v48
	v_bitop3_b32 v48, v61, v56, 7 bitop3:0x78
	v_lshlrev_b32_e32 v165, 4, v48
	v_add_u32_e32 v168, v163, v166
	s_waitcnt lgkmcnt(0)
	v_mfma_f32_32x32x16_bf16 v[32:47], v[52:55], v[112:115], v[32:47]
	s_nop 2
	v_exp_f32_e32 v194, v16
	v_exp_f32_e32 v195, v17
	v_exp_f32_e32 v196, v18
	v_exp_f32_e32 v197, v19
	v_exp_f32_e32 v198, v20
	v_exp_f32_e32 v200, v21
	v_exp_f32_e32 v199, v22
	s_nop 1
	v_exp_f32_e32 v173, v32
	v_exp_f32_e32 v174, v33
	v_exp_f32_e32 v175, v34
	v_exp_f32_e32 v176, v35
	v_exp_f32_e32 v191, v36
	v_exp_f32_e32 v188, v37
	v_exp_f32_e32 v171, v38
	v_exp_f32_e32 v201, v23
	v_exp_f32_e32 v172, v39
	v_exp_f32_e32 v180, v24
	v_exp_f32_e32 v185, v40
	v_exp_f32_e32 v181, v25
	v_exp_f32_e32 v186, v41
	v_exp_f32_e32 v182, v26
	v_exp_f32_e32 v187, v42
	v_exp_f32_e32 v183, v27
	v_exp_f32_e32 v184, v43
	v_exp_f32_e32 v193, v28
	v_exp_f32_e32 v177, v44
	v_exp_f32_e32 v189, v29
	v_exp_f32_e32 v178, v45
	v_exp_f32_e32 v190, v30
	v_exp_f32_e32 v179, v46
	v_exp_f32_e32 v192, v31
	v_exp_f32_e32 v161, v47
	v_add_u32_e32 v169, v164, v166
	v_add_u32_e32 v170, v165, v166
	v_mov_b32_e32 v16, 0
	v_mov_b32_e32 v17, v158
	v_mov_b32_e32 v18, v158
	v_mov_b32_e32 v19, v158
	v_mov_b32_e32 v20, v158
	v_mov_b32_e32 v21, v158
	v_mov_b32_e32 v22, v158
	v_mov_b32_e32 v23, v158
	v_mov_b32_e32 v24, v158
	v_mov_b32_e32 v25, v158
	v_mov_b32_e32 v26, v158
	v_mov_b32_e32 v27, v158
	v_mov_b32_e32 v28, v158
	v_mov_b32_e32 v29, v158
	v_mov_b32_e32 v30, v158
	v_mov_b32_e32 v31, v158
	v_mov_b32_e32 v32, 0
	v_mov_b32_e32 v33, v158
	v_mov_b32_e32 v34, v158
	v_mov_b32_e32 v35, v158
	v_mov_b32_e32 v36, v158
	v_mov_b32_e32 v37, v158
	v_mov_b32_e32 v38, v158
	v_mov_b32_e32 v39, v158
	v_mov_b32_e32 v40, v158
	v_mov_b32_e32 v41, v158
	v_mov_b32_e32 v42, v158
	v_mov_b32_e32 v43, v158
	v_mov_b32_e32 v44, v158
	v_mov_b32_e32 v45, v158
	v_mov_b32_e32 v46, v158
	v_mov_b32_e32 v47, v158
	v_mov_b32_e32 v48, 0
	v_mov_b32_e32 v49, v158
	v_mov_b32_e32 v50, v158
	v_mov_b32_e32 v51, v158
	v_mov_b32_e32 v52, v158
	v_mov_b32_e32 v53, v158
	v_mov_b32_e32 v54, v158
	v_mov_b32_e32 v55, v158
	v_mov_b32_e32 v56, v158
	v_mov_b32_e32 v59, v158
	v_mov_b32_e32 v60, v158
	v_mov_b32_e32 v61, v158
	v_mov_b32_e32 v75, v158
	v_mov_b32_e32 v76, v158
	v_mov_b32_e32 v77, v158
	v_mov_b32_e32 v78, v158
	v_mov_b32_e32 v79, v158

.LBB0_661:
	s_and_b64 vcc, exec, s[4:5]
	s_cbranch_vccz .LBB0_643
	s_add_i32 s96, s58, s81
	s_mov_b64 s[4:5], s[0:1]
	s_ashr_i32 s8, s96, 3
	s_mov_b64 s[6:7], s[100:101]
	s_bfe_u32 s10, s58, 0x20001
	s_lshl_b32 s12, s8, 2
	s_and_b32 s11, s58, 1
	s_or_b32 s12, s12, s10
	s_lshl_b32 s5, s11, 3
	s_ashr_i32 s13, s12, 31
	s_add_i32 s5, s5, s8
	s_lshl_b64 s[12:13], s[12:13], 7
	s_bfe_i32 s4, s58, 0x10000
	v_mov_b32_e32 v112, v244
	s_mul_hi_i32 s9, s5, 0x240000
	s_mul_i32 s5, s5, 0x240000
	s_or_b32 s12, s12, s85
	s_waitcnt lgkmcnt(0)
	s_add_u32 s5, s6, s5
	v_and_b32_e32 v39, 31, v112
	v_add_u32_e32 v38, s76, v112
	v_or_b32_e32 v20, s12, v39
	s_addc_u32 s9, s7, s9
	s_lshl_b32 s12, s10, 8
	v_and_b32_e32 v41, 0x7f, v38
	s_add_u32 s14, s5, s12
	s_addc_u32 s15, s9, 0
	v_lshlrev_b32_e32 v144, 1, v41
	v_lshl_add_u64 v[18:19], s[14:15], 0, v[144:145]
	s_mov_b64 s[14:15], 0xbe00000
	v_lshl_add_u64 v[84:85], v[18:19], 0, s[14:15]
	v_mov_b64_e32 v[18:19], s[6:7]
	v_mad_u64_u32 v[18:19], s[14:15], v20, s30, v[18:19]
	s_cmp_eq_u32 s11, 0
	v_ashrrev_i32_e32 v42, 7, v38
	s_cselect_b64 s[14:15], -1, 0
	s_cmp_eq_u32 s11, 1
	s_cselect_b64 s[18:19], -1, 0
	s_and_b32 s9, s4, 0xc0
	v_lshlrev_b32_e32 v120, 4, v42
	v_add_u32_e32 v20, s9, v120
	v_ashrrev_i32_e32 v21, 31, v20
	v_or_b32_e32 v24, 1, v20
	v_or_b32_e32 v26, 2, v20
	v_or_b32_e32 v28, 3, v20
	v_or_b32_e32 v30, 4, v20
	v_or_b32_e32 v32, 5, v20
	v_or_b32_e32 v34, 6, v20
	v_or_b32_e32 v36, 7, v20
	v_lshlrev_b64 v[22:23], 10, v[20:21]
	v_ashrrev_i32_e32 v25, 31, v24
	v_ashrrev_i32_e32 v27, 31, v26
	v_ashrrev_i32_e32 v29, 31, v28
	v_ashrrev_i32_e32 v31, 31, v30
	v_ashrrev_i32_e32 v33, 31, v32
	v_ashrrev_i32_e32 v35, 31, v34
	v_ashrrev_i32_e32 v37, 31, v36
	v_lshl_add_u64 v[22:23], v[84:85], 0, v[22:23]
	v_lshlrev_b64 v[24:25], 10, v[24:25]
	v_lshlrev_b64 v[26:27], 10, v[26:27]
	v_lshlrev_b64 v[28:29], 10, v[28:29]
	v_lshlrev_b64 v[30:31], 10, v[30:31]
	v_lshlrev_b64 v[32:33], 10, v[32:33]
	v_lshlrev_b64 v[34:35], 10, v[34:35]
	v_lshlrev_b64 v[36:37], 10, v[36:37]
	v_lshl_add_u64 v[24:25], v[84:85], 0, v[24:25]
	v_lshl_add_u64 v[26:27], v[84:85], 0, v[26:27]
	v_lshl_add_u64 v[28:29], v[84:85], 0, v[28:29]
	v_lshl_add_u64 v[30:31], v[84:85], 0, v[30:31]
	v_lshl_add_u64 v[32:33], v[84:85], 0, v[32:33]
	v_lshl_add_u64 v[34:35], v[84:85], 0, v[34:35]
	v_lshl_add_u64 v[36:37], v[84:85], 0, v[36:37]
	global_load_ushort v111, v[22:23], off
	global_load_ushort v113, v[24:25], off
	global_load_ushort v114, v[26:27], off
	global_load_ushort v115, v[28:29], off
	global_load_ushort v116, v[30:31], off
	global_load_ushort v117, v[32:33], off
	global_load_ushort v118, v[34:35], off
	global_load_ushort v119, v[36:37], off
	v_or_b32_e32 v22, 8, v20
	v_ashrrev_i32_e32 v23, 31, v22
	v_or_b32_e32 v24, 9, v20
	v_or_b32_e32 v26, 10, v20
	v_or_b32_e32 v28, 11, v20
	v_or_b32_e32 v30, 12, v20
	v_or_b32_e32 v32, 13, v20
	v_or_b32_e32 v34, 14, v20
	v_or_b32_e32 v20, 15, v20
	v_ashrrev_i32_e32 v40, 5, v112
	v_lshlrev_b64 v[22:23], 10, v[22:23]
	v_ashrrev_i32_e32 v25, 31, v24
	v_ashrrev_i32_e32 v27, 31, v26
	v_ashrrev_i32_e32 v29, 31, v28
	v_ashrrev_i32_e32 v31, 31, v30
	v_ashrrev_i32_e32 v33, 31, v32
	v_ashrrev_i32_e32 v35, 31, v34
	v_ashrrev_i32_e32 v21, 31, v20
	v_lshlrev_b32_e32 v16, 3, v40
	v_lshl_add_u64 v[22:23], v[84:85], 0, v[22:23]
	v_lshlrev_b64 v[24:25], 10, v[24:25]
	v_lshlrev_b64 v[26:27], 10, v[26:27]
	v_lshlrev_b64 v[28:29], 10, v[28:29]
	v_lshlrev_b64 v[30:31], 10, v[30:31]
	v_lshlrev_b64 v[32:33], 10, v[32:33]
	v_lshlrev_b64 v[34:35], 10, v[34:35]
	v_lshlrev_b64 v[20:21], 10, v[20:21]
	v_ashrrev_i32_e32 v17, 31, v16
	v_mad_i32_i24 v19, s13, v155, v19
	v_lshl_add_u64 v[24:25], v[84:85], 0, v[24:25]
	v_lshl_add_u64 v[26:27], v[84:85], 0, v[26:27]
	v_lshl_add_u64 v[28:29], v[84:85], 0, v[28:29]
	v_lshl_add_u64 v[30:31], v[84:85], 0, v[30:31]
	v_lshl_add_u64 v[32:33], v[84:85], 0, v[32:33]
	v_lshl_add_u64 v[34:35], v[84:85], 0, v[34:35]
	v_lshl_add_u64 v[20:21], v[84:85], 0, v[20:21]
	global_load_ushort v121, v[22:23], off
	global_load_ushort v122, v[24:25], off
	global_load_ushort v123, v[26:27], off
	global_load_ushort v124, v[28:29], off
	global_load_ushort v125, v[30:31], off
	global_load_ushort v126, v[32:33], off
	global_load_ushort v127, v[34:35], off
	global_load_ushort v128, v[20:21], off
	v_lshl_add_u64 v[16:17], v[16:17], 1, v[18:19]
	s_mov_b64 s[4:5], 0xac00000
	v_lshl_add_u64 v[86:87], v[16:17], 0, s[4:5]
	s_lshl_b32 s34, s9, 1
	v_lshl_add_u64 v[16:17], v[86:87], 0, s[34:35]
	global_load_dwordx4 v[76:79], v[16:17], off
	global_load_dwordx4 v[72:75], v[16:17], off offset:32
	global_load_dwordx4 v[68:71], v[16:17], off offset:64
	global_load_dwordx4 v[64:67], v[16:17], off offset:96
	v_lshlrev_b32_e32 v16, 1, v42
	v_lshrrev_b32_e32 v18, 1, v112
	v_bfe_u32 v17, v112, 1, 3
	v_bitop3_b32 v19, v16, v18, 7 bitop3:0x78
	v_bitop3_b32 v16, v16, v17, 1 bitop3:0x36
	s_ashr_i32 s9, s8, 31
	v_lshlrev_b32_e32 v105, 4, v16
	v_or_b32_e32 v16, s85, v39
	s_lshl_b64 s[8:9], s[8:9], 23
	v_ashrrev_i32_e32 v17, 2, v38
	v_lshlrev_b32_e32 v106, 4, v19
	v_lshl_add_u32 v19, v16, 7, 0
	s_add_u32 s6, s6, s8
	v_lshlrev_b32_e32 v16, 7, v17
	v_cmp_lt_i32_e32 vcc, 0, v42
	s_addc_u32 s7, s7, s9
	v_lshrrev_b32_e32 v22, 1, v17
	v_ashrrev_i32_e32 v17, 31, v16
	v_lshrrev_b32_e32 v43, 31, v38
	v_cndmask_b32_e64 v44, 0, 1, vcc
	v_add_u32_e32 v92, 0, v16
	v_lshl_add_u64 v[16:17], s[6:7], 0, v[16:17]
	s_mov_b64 s[6:7], 0x1800000
	v_lshl_add_u64 v[80:81], v[16:17], 0, s[6:7]
	v_cndmask_b32_e64 v16, v43, v44, s[14:15]
	v_and_b32_e32 v16, 1, v16
	v_cmp_lt_i32_e32 vcc, 1, v42
	v_cmp_eq_u32_e64 s[6:7], 1, v16
	s_lshl_b32 s8, s10, 6
	v_cndmask_b32_e64 v16, 0, 1, vcc
	v_cmp_gt_i32_e32 vcc, 1, v42
	s_lshl_b32 s9, s11, 5
	s_or_b32 s97, s9, s8
	v_cndmask_b32_e64 v17, 0, 1, vcc
	v_cndmask_b32_e64 v16, v17, v16, s[14:15]
	v_and_b32_e32 v16, 1, v16
	v_cmp_lt_i32_e32 vcc, 2, v42
	v_cmp_eq_u32_e64 s[8:9], 1, v16
	v_and_b32_e32 v20, 3, v112
	v_cndmask_b32_e64 v16, 0, 1, vcc
	v_cmp_gt_i32_e32 vcc, 2, v42
	v_lshlrev_b32_e32 v21, 1, v20
	s_lshl_b32 s16, s83, 2
	v_cndmask_b32_e64 v17, 0, 1, vcc
	v_cndmask_b32_e64 v16, v17, v16, s[14:15]
	v_and_b32_e32 v16, 1, v16
	v_cmp_lt_i32_e32 vcc, 3, v42
	v_cmp_eq_u32_e64 s[12:13], 1, v16
	s_movk_i32 s4, 0x80
	v_cndmask_b32_e64 v16, 0, 1, vcc
	v_cmp_gt_i32_e32 vcc, 3, v42
	v_lshlrev_b32_e32 v144, 5, v20
	s_add_i32 s16, s16, 0
	v_cndmask_b32_e64 v17, 0, 1, vcc
	v_cndmask_b32_e64 v16, v17, v16, s[14:15]
	v_and_b32_e32 v16, 1, v16
	v_cmp_eq_u32_e64 s[10:11], 1, v16
	v_bitop3_b32 v16, v18, s82, 7 bitop3:0x6c
	v_lshl_add_u32 v109, v16, 4, v19
	v_bitop3_b32 v16, v18, s86, 7 bitop3:0x6c
	v_lshl_add_u32 v108, v16, 4, v19
	v_bitop3_b32 v16, v18, s87, 7 bitop3:0x6c
	v_lshl_add_u32 v107, v16, 4, v19
	v_bitop3_b32 v16, v18, s84, 7 bitop3:0x6c
	v_lshl_add_u32 v103, v16, 4, v19
	v_bitop3_b32 v16, v22, v21, 7 bitop3:0x6c
	v_lshlrev_b32_e32 v93, 4, v16
	v_or_b32_e32 v16, 1, v21
	v_bitop3_b32 v16, v22, v16, 7 bitop3:0x6c
	v_lshlrev_b32_e32 v94, 4, v16
	v_bitop3_b32 v16, v18, v40, 7 bitop3:0x6c
	v_lshlrev_b32_e32 v97, 4, v16
	v_or_b32_e32 v16, s83, v39
	v_lshlrev_b32_e32 v102, 7, v16
	v_add_u32_e32 v16, 2, v40
	v_bitop3_b32 v16, v16, v18, 7 bitop3:0x78
	v_lshlrev_b32_e32 v98, 4, v16
	v_add_u32_e32 v16, 4, v40
	v_bitop3_b32 v16, v16, v18, 7 bitop3:0x78
	v_lshlrev_b32_e32 v96, 4, v16
	v_add_u32_e32 v16, 6, v40
	v_bitop3_b32 v16, v16, v18, 7 bitop3:0x78
	v_lshlrev_b32_e32 v95, 4, v16
	v_or_b32_e32 v16, s88, v39
	v_mov_b32_e32 v32, 0
	s_mov_b32 s58, 0
	v_lshl_add_u32 v91, v41, 2, 0
	v_lshl_add_u32 v90, v38, 2, 0
	v_lshlrev_b32_e32 v104, 7, v41
	v_cmp_gt_u32_e64 s[4:5], s4, v38
	v_lshlrev_b32_e32 v101, 2, v40
	s_add_i32 s97, s97, -4
	v_lshlrev_b32_e32 v99, 7, v16
	v_lshlrev_b32_e32 v110, 9, v42
	v_lshl_add_u64 v[82:83], v[80:81], 0, v[144:145]
	v_lshl_add_u32 v100, v40, 4, s16
	s_mov_b32 s34, -1
	v_mov_b32_e32 v33, v32
	v_mov_b32_e32 v34, v32
	v_mov_b32_e32 v35, v32
	v_mov_b32_e32 v36, v32
	v_mov_b32_e32 v37, v32
	v_mov_b32_e32 v38, v32
	v_mov_b32_e32 v39, v32
	v_mov_b32_e32 v40, v32
	v_mov_b32_e32 v41, v32
	v_mov_b32_e32 v42, v32
	v_mov_b32_e32 v43, v32
	v_mov_b32_e32 v44, v32
	v_mov_b32_e32 v45, v32
	v_mov_b32_e32 v46, v32
	v_mov_b32_e32 v47, v32
	v_mov_b32_e32 v16, v32
	v_mov_b32_e32 v17, v32
	v_mov_b32_e32 v18, v32
	v_mov_b32_e32 v19, v32
	v_mov_b32_e32 v20, v32
	v_mov_b32_e32 v21, v32
	v_mov_b32_e32 v22, v32
	v_mov_b32_e32 v23, v32
	v_mov_b32_e32 v24, v32
	v_mov_b32_e32 v25, v32
	v_mov_b32_e32 v26, v32
	v_mov_b32_e32 v27, v32
	v_mov_b32_e32 v28, v32
	v_mov_b32_e32 v29, v32
	v_mov_b32_e32 v30, v32
	v_mov_b32_e32 v31, v32

.LBB0_689:
	ds_write_b32 v87, v77 offset:35840
	s_waitcnt lgkmcnt(0)
	s_barrier
	ds_read2st64_b32 v[78:79], v91 offset0:140 offset1:142
	ds_read2st64_b32 v[84:85], v91 offset0:144 offset1:146
	v_exp_f32_e32 v82, v82
	v_exp_f32_e32 v83, v83
	v_exp_f32_e32 v98, v75
	v_exp_f32_e32 v99, v76
	v_exp_f32_e32 v102, v73
	v_exp_f32_e32 v103, v74
	s_waitcnt lgkmcnt(1)
	v_add_f32_e32 v106, 0, v78
	v_cndmask_b32_e64 v91, 0, v79, s[8:9]
	v_exp_f32_e32 v75, v72
	v_pk_add_f32 v[72:73], v[82:83], 1.0 op_sel_hi:[1,0] neg_lo:[1,0] neg_hi:[1,0]
	v_pk_add_f32 v[82:83], v[98:99], 1.0 op_sel_hi:[1,0] neg_lo:[1,0] neg_hi:[1,0]
	v_pk_add_f32 v[98:99], v[102:103], 1.0 op_sel_hi:[1,0] neg_lo:[1,0] neg_hi:[1,0]
	v_exp_f32_e32 v102, v69
	v_cndmask_b32_e64 v69, 0, v106, s[6:7]
	s_waitcnt lgkmcnt(0)
	v_cndmask_b32_e64 v77, 0, v84, s[12:13]
	v_add_f32_e32 v107, v69, v91
	v_mov_b32_e32 v76, v79
	v_exp_f32_e32 v86, v96
	v_exp_f32_e32 v87, v97
	v_cndmask_b32_e64 v97, 0, v85, s[10:11]
	v_pk_add_f32 v[76:77], v[106:107], v[76:77]
	v_mov_b32_e32 v96, v84
	v_pk_add_f32 v[76:77], v[76:77], v[96:97]
	v_exp_f32_e32 v103, v57
	v_add_f32_e32 v69, v48, v77
	v_mov_b32_e32 v48, v85
	v_pk_add_f32 v[48:49], v[76:77], v[48:49]
	v_add_f32_e32 v68, v68, v77
	v_sub_f32_e32 v69, v48, v69
	v_exp_f32_e32 v78, v69
	v_add_f32_e32 v69, v70, v77
	v_sub_f32_e32 v69, v48, v69
	v_exp_f32_e32 v79, v69
	v_add_f32_e32 v57, v63, v77
	v_pk_add_f32 v[86:87], v[86:87], 1.0 op_sel_hi:[1,0] neg_lo:[1,0] neg_hi:[1,0]
	v_sub_f32_e32 v68, v48, v68
	v_sub_f32_e32 v57, v48, v57
	v_exp_f32_e32 v70, v68
	v_pk_mul_f32 v[68:69], v[86:87], v[78:79]
	v_exp_f32_e32 v78, v57
	v_add_f32_e32 v57, v62, v77
	v_sub_f32_e32 v57, v48, v57
	v_exp_f32_e32 v79, v57
	v_add_f32_e32 v57, v59, v77
	v_add_f32_e32 v67, v67, v77
	v_sub_f32_e32 v57, v48, v57
	v_exp_f32_e32 v94, v94
	v_exp_f32_e32 v95, v95
	v_exp_f32_e32 v92, v92
	v_exp_f32_e32 v93, v93
	v_sub_f32_e32 v67, v48, v67
	v_exp_f32_e32 v62, v57
	v_add_f32_e32 v57, v58, v77
	v_exp_f32_e32 v74, v71
	v_exp_f32_e32 v71, v67
	v_sub_f32_e32 v57, v48, v57
	v_exp_f32_e32 v63, v57
	v_pk_add_f32 v[94:95], v[94:95], 1.0 op_sel_hi:[1,0] neg_lo:[1,0] neg_hi:[1,0]
	v_pk_add_f32 v[92:93], v[92:93], 1.0 op_sel_hi:[1,0] neg_lo:[1,0] neg_hi:[1,0]
	v_add_f32_e32 v56, v56, v77
	v_add_f32_e32 v55, v55, v77
	v_add_f32_e32 v54, v54, v77
	v_add_f32_e32 v53, v53, v77
	v_add_f32_e32 v52, v52, v77
	v_add_f32_e32 v51, v51, v77
	v_pk_mul_f32 v[70:71], v[94:95], v[70:71]
	v_pk_mul_f32 v[58:59], v[92:93], v[78:79]
	v_sub_f32_e32 v56, v48, v56
	v_sub_f32_e32 v55, v48, v55
	v_sub_f32_e32 v54, v48, v54
	v_sub_f32_e32 v53, v48, v53
	v_sub_f32_e32 v52, v48, v52
	v_sub_f32_e32 v51, v48, v51
	v_cvt_pk_bf16_f32 v68, v68, v69
	v_cvt_pk_bf16_f32 v69, v70, v71
	v_cvt_pk_bf16_f32 v70, v58, v59
	v_pk_mul_f32 v[58:59], v[72:73], v[62:63]
	v_exp_f32_e32 v56, v56
	v_exp_f32_e32 v57, v55
	v_exp_f32_e32 v62, v54
	v_exp_f32_e32 v63, v53
	v_exp_f32_e32 v52, v52
	v_exp_f32_e32 v53, v51
	v_add_f32_e32 v50, v50, v77
	v_sub_f32_e32 v50, v48, v50
	v_sub_f32_e32 v49, v48, v49
	v_exp_f32_e32 v50, v50
	v_exp_f32_e32 v51, v49
	v_pk_add_f32 v[74:75], v[74:75], 1.0 op_sel_hi:[1,0] neg_lo:[1,0] neg_hi:[1,0]
	v_pk_mul_f32 v[54:55], v[82:83], v[56:57]
	v_pk_mul_f32 v[56:57], v[98:99], v[62:63]
	v_pk_mul_f32 v[52:53], v[74:75], v[52:53]
	v_cvt_pk_bf16_f32 v54, v54, v55
	v_cvt_pk_bf16_f32 v55, v56, v57
	v_cvt_pk_bf16_f32 v56, v52, v53
	v_pk_add_f32 v[52:53], v[102:103], 1.0 op_sel_hi:[1,0] neg_lo:[1,0] neg_hi:[1,0]
	v_cvt_pk_bf16_f32 v71, v58, v59
	v_pk_mul_f32 v[50:51], v[52:53], v[50:51]
	s_nop 0
	v_cvt_pk_bf16_f32 v57, v50, v51
	ds_write_b128 v88, v[68:71] offset:16384
	ds_write_b128 v89, v[54:57] offset:16384
	s_and_saveexec_b64 s[6:7], s[4:5]
	v_exp_f32_e32 v48, v48
	ds_write_b32 v90, v48 offset:33280
	s_or_b64 exec, exec, s[6:7]
	v_mov_b32_e32 v48, v145
	v_cvt_pk_fp8_f32 v48, v32, v33
	v_mov_b32_e32 v32, v145
	v_cvt_pk_fp8_f32 v32, v36, v37
	v_mov_b32_e32 v33, v145
	v_mov_b32_e32 v36, v145
	v_cvt_pk_fp8_f32 v48, v34, v35 op_sel:[0,0,1]
	v_mov_b32_e32 v34, v145
	v_cvt_pk_fp8_f32 v33, v40, v41
	v_cvt_pk_fp8_f32 v36, v44, v45
	v_cvt_pk_fp8_f32 v34, v16, v17
	v_mov_b32_e32 v16, v145
	v_cvt_pk_fp8_f32 v16, v20, v21
	v_mov_b32_e32 v17, v145
	v_mov_b32_e32 v20, v145
	v_cvt_pk_fp8_f32 v17, v24, v25
	v_cvt_pk_fp8_f32 v20, v28, v29
	v_cvt_pk_fp8_f32 v32, v38, v39 op_sel:[0,0,1]
	v_cvt_pk_fp8_f32 v33, v42, v43 op_sel:[0,0,1]
	v_cvt_pk_fp8_f32 v36, v46, v47 op_sel:[0,0,1]
	v_cvt_pk_fp8_f32 v34, v18, v19 op_sel:[0,0,1]
	v_cvt_pk_fp8_f32 v16, v22, v23 op_sel:[0,0,1]
	v_cvt_pk_fp8_f32 v17, v26, v27 op_sel:[0,0,1]
	v_cvt_pk_fp8_f32 v20, v30, v31 op_sel:[0,0,1]
	ds_write2_b32 v64, v48, v32 offset1:2
	ds_write2_b32 v65, v33, v36 offset1:2
	ds_write2_b32 v104, v34, v16 offset1:2
	ds_write2_b32 v101, v17, v20 offset1:2
	s_waitcnt lgkmcnt(0)
	s_barrier
	ds_read_b128 v[16:19], v60 offset:40960
	ds_read_b128 v[20:23], v61 offset:40960
	s_add_i32 s34, s97, s56
	s_lshl_b64 s[4:5], s[34:35], 14
	v_lshl_add_u64 v[24:25], v[80:81], 0, s[4:5]
	v_lshl_add_u64 v[24:25], v[24:25], 0, v[144:145]
	s_waitcnt lgkmcnt(1)
	global_store_dwordx4 v[24:25], v[16:19], off
	s_waitcnt lgkmcnt(0)
	global_store_dwordx4 v[24:25], v[20:23], off offset:16
	s_and_saveexec_b64 s[4:5], s[18:19]
	v_mov_b32_e32 v16, s89
	ds_write_b32 v16, v66
	s_or_b64 exec, exec, s[4:5]
	s_waitcnt vmcnt(0) lgkmcnt(0)
	s_barrier
	s_andn2_b64 vcc, exec, s[44:45]
	s_cbranch_vccnz .LBB0_643
	v_mov_b32_e32 v16, v244
	s_nop 0
	v_cmp_eq_u32_e32 vcc, 0, v16
	s_and_saveexec_b64 s[4:5], vcc
	s_cbranch_execz .LBB0_696
	s_mov_b64 s[6:7], s[0:1]
	buffer_wbl2 sc1
	s_waitcnt vmcnt(0) lgkmcnt(0)
	s_waitcnt vmcnt(0)
	s_mov_b64 s[6:7], s[100:101]
	s_lshl_b32 s8, s96, 6
	s_ashr_i32 s9, s8, 31
	s_lshl_b64 s[8:9], s[8:9], 2
	s_waitcnt lgkmcnt(0)
	s_add_u32 s6, s6, s8
	s_addc_u32 s7, s7, s9
	global_store_dword v151, v147, s[6:7] sc1

.LBB0_697:
	s_mov_b64 s[84:85], s[24:25]
	v_readlane_b32 s24, v252, 5
	s_cmpk_gt_u32 s63, 0xc7
	v_readlane_b32 s25, v252, 6
	s_cbranch_scc1 .LBB0_731
	s_mov_b64 s[4:5], s[0:1]
	s_mov_b64 s[4:5], s[100:101]
	s_mul_i32 s29, s28, 0x900
	s_cmpk_gt_u32 s74, 0x7f
	v_mov_b32_e32 v201, 0
	v_mov_b32_e32 v32, 0
	s_mov_b64 s[6:7], s[0:1]
	s_cbranch_scc1 .LBB0_700
	s_load_dwordx2 s[6:7], s[6:7], 0x68
	v_mov_b32_e32 v0, v244
	s_nop 0
	v_add_u32_e32 v0, s76, v0
	v_ashrrev_i32_e32 v1, 31, v0
	s_waitcnt lgkmcnt(0)
	v_lshl_add_u64 v[0:1], v[0:1], 2, s[6:7]
	global_load_dword v0, v[0:1], off
	s_lshl_b32 s6, s76, 2
	v_mov_b32_e32 v1, v244
	s_add_i32 s6, s6, 0
	s_nop 0
	v_lshl_add_u32 v1, v1, 2, s6
	v_add_u32_e32 v1, 0x26400, v1
	s_waitcnt vmcnt(0)
	ds_write_b32 v1, v0

.LBB0_702:
	s_add_i32 s10, s63, 0xffffffb8
	s_ashr_i32 s63, s10, 5
	s_lshl_b32 s26, 1, s63
	s_and_b32 s6, s26, s70
	s_cmp_lg_u32 s6, 0
	s_cbranch_scc1 .LBB0_714
	s_and_b64 vcc, exec, s[4:5]
	s_cbranch_vccnz .LBB0_713
	s_mov_b64 s[6:7], s[0:1]
	s_mov_b64 s[6:7], s[100:101]
	s_lshl_b32 s8, s63, 7
	s_add_i32 s8, s8, s51
	s_ashr_i32 s9, s8, 31
	s_lshl_b64 s[8:9], s[8:9], 2
	s_waitcnt lgkmcnt(0)
	s_add_u32 s6, s6, s8
	s_addc_u32 s7, s7, s9
	s_add_u32 s6, s6, 0x20000
	s_addc_u32 s7, s7, 0
	s_mov_b32 s27, 0x3fffff
	s_branch .LBB0_706

.LBB0_714:
	s_xor_b64 s[6:7], s[40:41], -1
	s_and_b32 s9, s10, 31
	v_mov_b32_e32 v209, v244
	s_andn2_b64 vcc, exec, s[6:7]
	s_lshl_b32 s8, s9, 6
	s_cbranch_vccnz .LBB0_716
	s_mov_b64 s[6:7], s[0:1]
	s_mov_b64 s[6:7], s[100:101]
	v_mov_b32_e32 v14, v244
	s_waitcnt lgkmcnt(0)
	s_add_u32 s26, s6, s28
	v_and_b32_e32 v1, 7, v14
	s_addc_u32 s27, s7, 0
	s_lshl_b32 s10, s63, 6
	s_or_b32 s40, s10, s9
	v_lshlrev_b32_e32 v200, 4, v1
	v_lshl_add_u64 v[2:3], s[26:27], 0, v[200:201]
	s_ashr_i32 s41, s40, 31
	v_lshl_add_u64 v[2:3], v[2:3], 0, s[18:19]
	s_lshl_b64 s[26:27], s[40:41], 14
	v_lshl_add_u64 v[6:7], v[2:3], 0, s[26:27]
	s_or_b32 s26, s40, 32
	s_ashr_i32 s27, s26, 31
	v_add_u32_e32 v0, s76, v14
	s_lshl_b64 s[26:27], s[26:27], 14
	s_add_i32 s10, s63, s50
	v_ashrrev_i32_e32 v0, 3, v0
	v_lshl_add_u64 v[2:3], v[2:3], 0, s[26:27]
	s_add_i32 s9, s8, 0x100
	s_mul_hi_i32 s26, s10, 0x90000
	s_mul_i32 s10, s10, 0x90000
	v_add_u32_e32 v10, 64, v0
	s_add_u32 s10, s6, s10
	v_ashrrev_i32_e32 v1, 31, v0
	v_ashrrev_i32_e32 v11, 31, v10
	s_addc_u32 s27, s7, s26
	s_lshl_b32 s26, s8, 1
	v_lshlrev_b64 v[4:5], 7, v[0:1]
	v_lshlrev_b64 v[12:13], 7, v[10:11]
	s_add_u32 s26, s10, s26
	v_lshl_add_u64 v[8:9], v[6:7], 0, v[4:5]
	v_lshl_add_u64 v[4:5], v[2:3], 0, v[4:5]
	v_lshl_add_u64 v[2:3], v[2:3], 0, v[12:13]
	s_addc_u32 s27, s27, 0
	v_lshl_add_u64 v[6:7], v[6:7], 0, v[12:13]
	global_load_dwordx4 v[36:39], v[8:9], off nt
	global_load_dwordx4 v[40:43], v[6:7], off nt
	global_load_dwordx4 v[44:47], v[4:5], off nt
	global_load_dwordx4 v[48:51], v[2:3], off nt
	v_lshl_add_u64 v[2:3], s[26:27], 0, v[200:201]
	v_lshl_add_u64 v[2:3], v[2:3], 0, s[34:35]
	v_mad_i64_i32 v[4:5], s[26:27], v0, s44, v[2:3]
	v_mad_i64_i32 v[2:3], s[26:27], v10, s44, v[2:3]
	s_add_u32 s26, s6, 0xbe00000
	v_and_b32_e32 v0, -8, v0
	s_addc_u32 s27, s7, 0
	s_add_i32 s10, s29, s9
	v_ashrrev_i32_e32 v1, 31, v0
	global_load_dwordx4 v[52:55], v[4:5], off offset:512
	global_load_dwordx4 v[32:35], v[2:3], off offset:512
	s_or_b32 s40, s62, s8
	s_mov_b32 s41, s46
	v_lshl_add_u64 v[2:3], s[10:11], 0, v[0:1]
	v_lshlrev_b32_e32 v4, 2, v14
	s_add_i32 s10, s52, s9
	s_lshl_b32 s42, s63, 7
	v_and_b32_e32 v200, 0xfc, v4
	v_lshl_add_u64 v[4:5], v[0:1], 0, s[10:11]
	v_lshl_add_u64 v[0:1], s[40:41], 0, v[0:1]
	s_ashr_i32 s43, s42, 31
	v_lshlrev_b64 v[0:1], 11, v[0:1]
	s_lshl_b64 s[42:43], s[42:43], 1
	v_lshl_add_u64 v[0:1], s[6:7], 0, v[0:1]
	v_lshl_add_u64 v[0:1], v[0:1], 0, s[42:43]
	v_lshl_add_u64 v[0:1], v[0:1], 0, v[200:201]
	v_lshlrev_b64 v[2:3], 10, v[2:3]
	v_add_co_u32_e32 v8, vcc, s45, v0
	v_lshl_add_u64 v[2:3], s[26:27], 0, v[2:3]
	s_nop 0
	v_addc_co_u32_e32 v9, vcc, 0, v1, vcc
	v_lshl_add_u64 v[2:3], v[2:3], 0, s[42:43]
	v_lshlrev_b64 v[4:5], 10, v[4:5]
	v_add_co_u32_e32 v10, vcc, s55, v0
	v_lshl_add_u64 v[2:3], v[2:3], 0, v[200:201]
	v_lshl_add_u64 v[4:5], s[26:27], 0, v[4:5]
	v_addc_co_u32_e32 v11, vcc, 0, v1, vcc
	v_lshl_add_u64 v[4:5], v[4:5], 0, s[42:43]
	v_add_co_u32_e32 v12, vcc, s56, v2
	v_lshl_add_u64 v[4:5], v[4:5], 0, v[200:201]
	s_nop 0
	v_addc_co_u32_e32 v13, vcc, 0, v3, vcc
	v_lshl_add_u64 v[6:7], v[0:1], 0, s[36:37]
	global_load_dword v58, v[8:9], off offset:1024
	global_load_dword v60, v[10:11], off offset:1024
	global_load_dword v57, v[10:11], off offset:3072
	global_load_dword v56, v[12:13], off
	global_load_dword v59, v[12:13], off offset:1024
	global_load_dword v62, v[12:13], off offset:2048
	global_load_dword v61, v[12:13], off offset:3072
	global_load_dword v67, v[6:7], off offset:2048
	global_load_dword v64, v[2:3], off
	global_load_dword v66, v[4:5], off
	global_load_dword v63, v[2:3], off offset:1024
	global_load_dword v65, v[4:5], off offset:1024
	global_load_dword v68, v[2:3], off offset:2048
	global_load_dword v70, v[4:5], off offset:2048
	global_load_dword v71, v[4:5], off offset:3072
	global_load_dword v69, v[2:3], off offset:3072
	v_add_co_u32_e32 v2, vcc, s56, v4
	s_nop 1
	v_addc_co_u32_e32 v3, vcc, 0, v5, vcc
	v_add_co_u32_e32 v4, vcc, s57, v0
	s_nop 1
	v_addc_co_u32_e32 v5, vcc, 0, v1, vcc
	v_add_co_u32_e32 v0, vcc, s58, v0
	s_nop 1
	v_addc_co_u32_e32 v1, vcc, 0, v1, vcc
	global_load_dword v72, v[2:3], off
	global_load_dword v74, v[4:5], off offset:1024
	global_load_dword v73, v[2:3], off offset:1024
	global_load_dword v75, v[4:5], off offset:3072
	global_load_dword v76, v[2:3], off offset:2048
	global_load_dword v78, v[0:1], off offset:1024
	global_load_dword v79, v[0:1], off offset:3072
	global_load_dword v77, v[2:3], off offset:3072
	s_waitcnt vmcnt(0)
	s_waitcnt vmcnt(29)
	s_waitcnt vmcnt(28)
	s_waitcnt vmcnt(27)
	s_waitcnt vmcnt(26)
	s_waitcnt vmcnt(24)
	s_waitcnt vmcnt(14)
	s_waitcnt vmcnt(12)
	s_waitcnt vmcnt(10)
	s_waitcnt vmcnt(8)
	s_waitcnt vmcnt(6)
	s_waitcnt vmcnt(4)
	s_waitcnt vmcnt(2)
	s_waitcnt vmcnt(0)

.LBB0_720:
	s_or_b64 exec, exec, s[6:7]
	s_or_b32 s10, s8, s62
	s_mov_b64 s[8:9], s[0:1]
	s_waitcnt lgkmcnt(0)
	s_barrier
	s_mov_b64 s[8:9], s[100:101]
	v_ashrrev_i32_e32 v202, 4, v113
	v_ashrrev_i32_e32 v203, 31, v202
	v_lshl_add_u64 v[204:205], v[202:203], 0, s[10:11]
	s_lshl_b32 s6, s63, 7
	v_lshlrev_b32_e32 v0, 3, v209
	s_ashr_i32 s7, s6, 31
	v_and_b32_e32 v203, 0x78, v0
	v_lshlrev_b64 v[0:1], 10, v[204:205]
	s_waitcnt lgkmcnt(0)
	v_lshl_add_u64 v[2:3], s[8:9], 0, v[0:1]
	s_lshl_b64 s[42:43], s[6:7], 1
	v_lshl_add_u64 v[2:3], v[2:3], 0, s[42:43]
	v_lshlrev_b32_e32 v200, 1, v203
	v_lshl_add_u64 v[2:3], v[2:3], 0, v[200:201]
	v_add_co_u32_e32 v2, vcc, s67, v2
	s_mov_b64 s[6:7], s[0:1]
	s_nop 0
	v_addc_co_u32_e32 v3, vcc, 0, v3, vcc
	global_load_dwordx4 v[84:87], v[2:3], off
	s_mov_b64 s[6:7], s[100:101]
	s_mov_b64 s[40:41], 0
	s_waitcnt lgkmcnt(0)
	v_lshl_add_u64 v[0:1], s[6:7], 0, v[0:1]
	v_lshl_add_u64 v[0:1], v[0:1], 0, s[42:43]
	v_lshl_add_u64 v[0:1], v[0:1], 0, v[200:201]
	v_add_co_u32_e32 v0, vcc, 0xe208000, v0
	s_nop 1
	v_addc_co_u32_e32 v1, vcc, 0, v1, vcc
	global_load_dwordx4 v[80:83], v[0:1], off
	v_mov_b32_e32 v0, s66
	ds_read_b32 v0, v0
	s_waitcnt lgkmcnt(0)
	v_readfirstlane_b32 s6, v0
	s_add_i32 s63, s6, s3
	s_add_i32 s7, s63, 0xffffffb8
	s_cmpk_gt_u32 s7, 0x7f
	s_cbranch_scc1 .LBB0_723
	s_lshr_b32 s6, s7, 5
	s_lshr_b32 s8, s70, s6
	s_bitcmp0_b32 s8, 0
	s_cbranch_scc1 .LBB0_723
	s_mov_b64 s[8:9], s[0:1]
	s_mov_b64 s[8:9], s[100:101]
	s_and_b32 s7, s7, 31
	v_mov_b32_e32 v16, v244
	s_lshl_b32 s40, s7, 6
	s_waitcnt lgkmcnt(0)
	s_add_u32 s26, s8, s28
	v_and_b32_e32 v1, 7, v16
	s_addc_u32 s27, s9, 0
	v_lshlrev_b32_e32 v2, 4, v1
	v_mov_b32_e32 v3, v201
	v_lshl_add_u64 v[4:5], s[26:27], 0, v[2:3]
	s_lshl_b32 s26, s6, 20
	s_lshl_b32 s27, s7, 14
	s_or_b32 s26, s26, s27
	s_mov_b32 s27, s11
	v_lshl_add_u64 v[4:5], v[4:5], 0, s[26:27]
	s_or_b32 s26, s6, s50
	s_add_i32 s71, s40, 0x100
	s_mul_i32 s26, s26, 0x90000
	v_add_u32_e32 v0, s76, v16
	s_add_u32 s26, s8, s26
	v_ashrrev_i32_e32 v0, 3, v0
	s_addc_u32 s27, s9, 0
	s_lshl_b32 s7, s7, 7
	v_add_u32_e32 v12, 64, v0
	s_add_u32 s26, s26, s7
	v_ashrrev_i32_e32 v1, 31, v0
	v_ashrrev_i32_e32 v13, 31, v12
	s_addc_u32 s27, s27, 0
	v_lshlrev_b64 v[6:7], 7, v[0:1]
	v_lshl_add_u64 v[8:9], v[4:5], 0, s[18:19]
	v_lshlrev_b64 v[14:15], 7, v[12:13]
	v_lshl_add_u64 v[4:5], v[4:5], 0, s[38:39]
	v_lshl_add_u64 v[2:3], s[26:27], 0, v[2:3]
	v_lshl_add_u64 v[10:11], v[8:9], 0, v[6:7]
	v_lshl_add_u64 v[6:7], v[4:5], 0, v[6:7]
	v_lshl_add_u64 v[4:5], v[4:5], 0, v[14:15]
	v_lshl_add_u64 v[2:3], v[2:3], 0, s[34:35]
	v_lshl_add_u64 v[8:9], v[8:9], 0, v[14:15]
	global_load_dwordx4 v[36:39], v[10:11], off nt
	global_load_dwordx4 v[40:43], v[8:9], off nt
	global_load_dwordx4 v[44:47], v[6:7], off nt
	global_load_dwordx4 v[48:51], v[4:5], off nt
	v_mad_i64_i32 v[4:5], s[26:27], v0, s44, v[2:3]
	v_mad_i64_i32 v[2:3], s[26:27], v12, s44, v[2:3]
	s_add_u32 s26, s8, 0xbe00000
	v_and_b32_e32 v0, -8, v0
	s_addc_u32 s27, s9, 0
	s_add_i32 s72, s29, s71
	s_mov_b32 s73, s11
	v_ashrrev_i32_e32 v1, 31, v0
	global_load_dwordx4 v[52:55], v[4:5], off offset:512
	global_load_dwordx4 v[32:35], v[2:3], off offset:512
	s_or_b32 s40, s62, s40
	s_mov_b32 s41, s46
	v_lshl_add_u64 v[2:3], s[72:73], 0, v[0:1]
	s_add_i32 s72, s52, s71
	v_lshl_add_u64 v[6:7], v[0:1], 0, s[72:73]
	v_lshl_add_u64 v[0:1], s[40:41], 0, v[0:1]
	v_lshlrev_b64 v[0:1], 11, v[0:1]
	s_lshl_b32 s6, s6, 8
	s_mov_b32 s7, s11
	v_lshlrev_b32_e32 v4, 2, v16
	v_lshl_add_u64 v[0:1], s[8:9], 0, v[0:1]
	v_and_b32_e32 v4, 0xfc, v4
	v_mov_b32_e32 v5, v201
	v_lshl_add_u64 v[0:1], v[0:1], 0, s[6:7]
	v_lshl_add_u64 v[0:1], v[0:1], 0, v[4:5]
	v_lshlrev_b64 v[2:3], 10, v[2:3]
	v_add_co_u32_e32 v8, vcc, s45, v0
	v_lshl_add_u64 v[2:3], s[26:27], 0, v[2:3]
	s_nop 0
	v_addc_co_u32_e32 v9, vcc, 0, v1, vcc
	v_lshl_add_u64 v[2:3], v[2:3], 0, s[6:7]
	v_lshlrev_b64 v[6:7], 10, v[6:7]
	v_add_co_u32_e32 v10, vcc, s55, v0
	v_lshl_add_u64 v[2:3], v[2:3], 0, v[4:5]
	v_lshl_add_u64 v[6:7], s[26:27], 0, v[6:7]
	v_addc_co_u32_e32 v11, vcc, 0, v1, vcc
	v_lshl_add_u64 v[6:7], v[6:7], 0, s[6:7]
	v_add_co_u32_e32 v12, vcc, s56, v2
	v_lshl_add_u64 v[6:7], v[6:7], 0, v[4:5]
	v_lshl_add_u64 v[4:5], v[0:1], 0, s[36:37]
	v_addc_co_u32_e32 v13, vcc, 0, v3, vcc
	global_load_dword v58, v[8:9], off offset:1024
	global_load_dword v60, v[10:11], off offset:1024
	global_load_dword v57, v[10:11], off offset:3072
	global_load_dword v56, v[12:13], off
	global_load_dword v59, v[12:13], off offset:1024
	global_load_dword v62, v[12:13], off offset:2048
	global_load_dword v61, v[12:13], off offset:3072
	global_load_dword v67, v[4:5], off offset:2048
	global_load_dword v64, v[2:3], off
	global_load_dword v66, v[6:7], off
	global_load_dword v63, v[2:3], off offset:1024
	global_load_dword v65, v[6:7], off offset:1024
	global_load_dword v68, v[2:3], off offset:2048
	global_load_dword v70, v[6:7], off offset:2048
	global_load_dword v71, v[6:7], off offset:3072
	global_load_dword v69, v[2:3], off offset:3072
	v_add_co_u32_e32 v2, vcc, s56, v6
	s_mov_b64 s[40:41], -1
	s_nop 0
	v_addc_co_u32_e32 v3, vcc, 0, v7, vcc
	v_add_co_u32_e32 v4, vcc, s57, v0
	s_nop 1
	v_addc_co_u32_e32 v5, vcc, 0, v1, vcc
	v_add_co_u32_e32 v0, vcc, 0x5803000, v0
	s_nop 1
	v_addc_co_u32_e32 v1, vcc, 0, v1, vcc
	global_load_dword v72, v[2:3], off
	global_load_dword v74, v[4:5], off offset:1024
	global_load_dword v73, v[2:3], off offset:1024
	global_load_dword v75, v[4:5], off offset:3072
	global_load_dword v76, v[2:3], off offset:2048
	global_load_dword v78, v[0:1], off offset:1024
	global_load_dword v79, v[0:1], off offset:3072
	global_load_dword v77, v[2:3], off offset:3072

.LBB0_729:
	s_or_b64 exec, exec, s[6:7]
	v_lshl_add_u32 v16, v211, 2, 0
	s_waitcnt lgkmcnt(0)
	s_barrier
	v_add_u32_e32 v18, 0x26000, v16
	s_waitcnt lgkmcnt(0)
	ds_read2st64_b32 v[16:17], v18 offset1:1
	ds_read2st64_b32 v[18:19], v18 offset0:2 offset1:3
	v_lshl_add_u32 v20, v212, 2, s47
	v_lshl_add_u32 v22, v20, 2, 0
	v_add_u32_e32 v23, 0x26400, v22
	s_waitcnt lgkmcnt(1)
	v_add_f32_e32 v16, v16, v17
	s_waitcnt lgkmcnt(0)
	v_add_f32_e32 v16, v16, v18
	v_add_f32_e32 v16, v16, v19
	v_fmamk_f32 v16, v16, 0x3c000000, v207
	v_mul_f32_e32 v17, 0x4b800000, v16
	v_cmp_gt_f32_e32 vcc, s68, v16
	s_mov_b64 s[6:7], s[0:1]
	s_nop 0
	v_cndmask_b32_e32 v16, v16, v17, vcc
	v_rsq_f32_e32 v21, v16
	ds_read_b128 v[16:19], v23
	v_mul_f32_e32 v20, 0x45800000, v21
	v_cndmask_b32_e32 v20, v21, v20, vcc
	v_pk_mul_f32 v[0:1], v[0:1], v[20:21] op_sel_hi:[1,0]
	v_pk_mul_f32 v[2:3], v[2:3], v[20:21] op_sel_hi:[1,0]
	s_waitcnt lgkmcnt(0)
	v_pk_mul_f32 v[0:1], v[16:17], v[0:1]
	v_pk_mul_f32 v[2:3], v[18:19], v[2:3]
	v_mad_u32_u24 v16, v211, s69, v22
	ds_write_b128 v16, v[0:3]
	ds_read_b128 v[0:3], v23 offset:32
	v_pk_mul_f32 v[4:5], v[4:5], v[20:21] op_sel_hi:[1,0]
	s_waitcnt lgkmcnt(0)
	v_pk_mul_f32 v[0:1], v[0:1], v[4:5]
	v_pk_mul_f32 v[4:5], v[6:7], v[20:21] op_sel_hi:[1,0]
	v_pk_mul_f32 v[6:7], v[10:11], v[20:21] op_sel_hi:[1,0]
	v_pk_mul_f32 v[2:3], v[2:3], v[4:5]
	ds_write_b128 v16, v[0:3] offset:32
	ds_read_b128 v[0:3], v23 offset:64
	v_pk_mul_f32 v[4:5], v[8:9], v[20:21] op_sel_hi:[1,0]
	s_waitcnt vmcnt(1)
	v_lshlrev_b32_e32 v8, 16, v84
	v_and_b32_e32 v9, 0xffff0000, v84
	s_waitcnt vmcnt(0)
	v_and_b32_e32 v11, 0xffff0000, v80
	s_waitcnt lgkmcnt(0)
	v_pk_mul_f32 v[0:1], v[0:1], v[4:5]
	v_pk_mul_f32 v[2:3], v[2:3], v[6:7]
	ds_write_b128 v16, v[0:3] offset:64
	ds_read_b128 v[0:3], v23 offset:96
	v_pk_mul_f32 v[4:5], v[12:13], v[20:21] op_sel_hi:[1,0]
	v_pk_mul_f32 v[6:7], v[14:15], v[20:21] op_sel_hi:[1,0]
	s_waitcnt lgkmcnt(0)
	v_pk_mul_f32 v[0:1], v[0:1], v[4:5]
	v_pk_mul_f32 v[2:3], v[2:3], v[6:7]
	ds_write_b128 v16, v[0:3] offset:96
	v_lshlrev_b32_e32 v0, 2, v203
	v_mul_lo_u32 v1, v202, s69
	s_waitcnt lgkmcnt(0)
	s_barrier
	v_add3_u32 v10, 0, v0, v1
	ds_read_b128 v[0:3], v10
	ds_read_b128 v[4:7], v10 offset:16
	s_mov_b64 s[6:7], s[100:101]
	s_waitcnt lgkmcnt(0)
	v_pk_mul_f32 v[0:1], v[0:1], v[8:9]
	v_lshlrev_b32_e32 v8, 16, v85
	v_and_b32_e32 v9, 0xffff0000, v85
	v_pk_mul_f32 v[2:3], v[2:3], v[8:9]
	v_cvt_pk_bf16_f32 v0, v0, v1
	v_cvt_pk_bf16_f32 v1, v2, v3
	v_lshlrev_b32_e32 v2, 16, v86
	v_and_b32_e32 v3, 0xffff0000, v86
	v_pk_mul_f32 v[2:3], v[4:5], v[2:3]
	v_lshlrev_b32_e32 v4, 16, v87
	v_and_b32_e32 v5, 0xffff0000, v87
	v_pk_mul_f32 v[4:5], v[6:7], v[4:5]
	v_cvt_pk_bf16_f32 v2, v2, v3
	v_cvt_pk_bf16_f32 v3, v4, v5
	v_lshlrev_b64 v[4:5], 11, v[204:205]
	v_lshl_add_u64 v[4:5], s[6:7], 0, v[4:5]
	v_lshl_add_u64 v[4:5], v[4:5], 0, s[42:43]
	v_lshl_add_u64 v[4:5], v[4:5], 0, v[200:201]
	v_add_co_u32_e32 v4, vcc, s45, v4
	s_mov_b64 s[6:7], s[0:1]
	s_nop 0
	v_addc_co_u32_e32 v5, vcc, 0, v5, vcc
	global_store_dwordx4 v[4:5], v[0:3], off offset:1024
	ds_read_b128 v[0:3], v10 offset:16896
	ds_read_b128 v[4:7], v10 offset:16912
	v_lshlrev_b32_e32 v10, 16, v80
	s_mov_b64 s[6:7], s[100:101]
	s_waitcnt lgkmcnt(0)
	v_pk_mul_f32 v[0:1], v[0:1], v[10:11]
	v_lshlrev_b32_e32 v10, 16, v81
	v_and_b32_e32 v11, 0xffff0000, v81
	v_pk_mul_f32 v[2:3], v[2:3], v[10:11]
	v_cvt_pk_bf16_f32 v0, v0, v1
	v_cvt_pk_bf16_f32 v1, v2, v3
	v_lshlrev_b32_e32 v2, 16, v82
	v_and_b32_e32 v3, 0xffff0000, v82
	v_add_u32_e32 v8, 32, v202
	v_pk_mul_f32 v[2:3], v[4:5], v[2:3]
	v_lshlrev_b32_e32 v4, 16, v83
	v_and_b32_e32 v5, 0xffff0000, v83
	v_pk_mul_f32 v[4:5], v[6:7], v[4:5]
	v_ashrrev_i32_e32 v9, 31, v8
	v_cvt_pk_bf16_f32 v2, v2, v3
	v_cvt_pk_bf16_f32 v3, v4, v5
	v_lshl_add_u64 v[4:5], v[8:9], 0, s[10:11]
	v_lshlrev_b64 v[4:5], 11, v[4:5]
	v_lshl_add_u64 v[4:5], s[6:7], 0, v[4:5]
	v_lshl_add_u64 v[4:5], v[4:5], 0, s[42:43]
	v_lshl_add_u64 v[4:5], v[4:5], 0, v[200:201]
	v_add_co_u32_e32 v4, vcc, 0x5800000, v4
	s_nop 1
	v_addc_co_u32_e32 v5, vcc, 0, v5, vcc
	global_store_dwordx4 v[4:5], v[0:3], off offset:1024
	s_waitcnt vmcnt(2)
	s_andn2_b64 vcc, exec, s[40:41]
	s_cbranch_vccnz .LBB0_701
	s_branch .LBB0_701

.LBB0_796:
	s_and_b64 vcc, exec, s[4:5]
	s_cbranch_vccz .LBB0_806
	s_mov_b64 s[6:7], s[0:1]
	v_mov_b32_e32 v0, v244
	s_waitcnt vmcnt(0)
	s_waitcnt lgkmcnt(0)
	v_sub_u32_e32 v0, 0, v0
	v_cmp_eq_u32_e32 vcc, s76, v0
	s_barrier
	s_and_saveexec_b64 s[4:5], vcc
	s_cbranch_execz .LBB0_805
	s_mov_b64 s[6:7], s[100:101]
	s_mov_b64 s[8:9], exec
	s_lshl_b32 s3, s2, 9
	s_and_b32 s3, s3, 0xe00
	v_mbcnt_lo_u32_b32 v0, s8, 0
	s_waitcnt lgkmcnt(0)
	s_add_u32 s6, s6, s3
	v_mbcnt_hi_u32_b32 v0, s9, v0
	s_addc_u32 s7, s7, 0
	v_cmp_eq_u32_e32 vcc, 0, v0
	s_and_saveexec_b64 s[10:11], vcc
	s_cbranch_execz .LBB0_800
	s_bcnt1_i32_b64 s3, s[8:9]
	v_mov_b32_e32 v1, 0x35000
	v_mov_b32_e32 v2, s3
	global_atomic_add v1, v1, v2, s[6:7] sc0

.LBB0_807:
	s_cmp_lt_i32 s20, 6
	s_cselect_b64 s[4:5], -1, 0
	s_cmp_gt_i32 s21, 5
	s_cselect_b64 s[6:7], -1, 0
	s_and_b64 s[4:5], s[4:5], s[6:7]
	s_andn2_b64 vcc, exec, s[4:5]
	s_cbranch_vccnz .LBB0_918
	s_cmpk_lt_i32 s2, 0x100
	s_mov_b64 s[4:5], s[0:1]
	v_mov_b32_e32 v0, v244
	s_cselect_b64 s[6:7], -1, 0
	s_cmpk_gt_i32 s2, 0xff
	s_waitcnt vmcnt(0)
	v_mov_b32_e32 v8, v244
	s_cbranch_scc1 .LBB0_810
	s_ashr_i32 s3, s2, 31
	s_lshr_b32 s3, s3, 29
	s_add_i32 s3, s2, s3
	s_and_b32 s4, s3, -8
	s_sub_i32 s10, s2, s4
	s_lshl_b32 s4, s10, 5
	s_ashr_i32 s3, s3, 3
	s_add_i32 s3, s4, s3
	s_ashr_i32 s4, s3, 31
	s_lshr_b32 s4, s4, 27
	s_add_i32 s4, s3, s4
	s_and_b32 s4, s4, 0xffe0
	s_sub_i32 s3, s3, s4
	s_bfe_i32 s4, s3, 0x80000
	s_bfe_u32 s4, s4, 0x3000c
	s_add_i32 s11, s3, s4
	s_bfe_i32 s4, s11, 0x80000
	s_sext_i32_i16 s14, s4
	s_lshr_b32 s4, s14, 3
	s_bfe_i64 s[4:5], s[4:5], 0x100000
	s_lshl_b64 s[8:9], s[4:5], 19
	s_and_b32 s4, s11, 0xf8
	s_sub_i32 s3, s3, s4
	s_mov_b64 s[4:5], s[0:1]
	s_lshl_b32 s12, s10, 3
	s_mov_b64 s[10:11], s[100:101]
	s_sext_i32_i8 s3, s3
	s_add_i32 s4, s12, s3
	s_ashr_i32 s5, s4, 31
	s_lshl_b64 s[12:13], s[4:5], 19
	s_ashr_i32 s90, s14, 3
	s_waitcnt lgkmcnt(0)
	s_add_u32 s3, s10, s12
	s_addc_u32 s5, s11, s13
	s_add_u32 s68, s3, 0x5800000
	s_addc_u32 s69, s5, 0
	s_add_u32 s3, s10, s8
	s_addc_u32 s5, s11, s9
	s_add_u32 s70, s3, 0xb00000
	s_addc_u32 s71, s5, 0
	s_andn2_b64 vcc, exec, s[6:7]
	s_cbranch_vccz .LBB0_811
	s_branch .LBB0_842

.LBB0_816:
	s_add_i32 s78, s78, 1
	s_mul_i32 s5, s78, s33
	s_add_i32 s5, s5, s2
	s_cmpk_lt_i32 s5, 0x100
	s_cselect_b64 s[66:67], -1, 0
	s_cmpk_gt_i32 s5, 0xff
	s_cbranch_scc1 .LBB0_818
	s_ashr_i32 s60, s5, 31
	s_lshr_b32 s60, s60, 29
	s_add_i32 s60, s5, s60
	s_ashr_i32 s61, s60, 3
	s_and_b32 s60, s60, -8
	s_sub_i32 s5, s5, s60
	s_lshl_b32 s60, s5, 5
	s_add_i32 s60, s60, s61
	s_ashr_i32 s61, s60, 31
	s_lshr_b32 s61, s61, 27
	s_add_i32 s61, s60, s61
	s_andn2_b32 s61, s61, 31
	s_sub_i32 s60, s60, s61
	s_bfe_i32 s61, s60, 0x80000
	s_bfe_u32 s61, s61, 0x3000c
	s_mov_b64 s[26:27], s[0:1]
	s_add_i32 s61, s60, s61
	s_bfe_i32 s62, s61, 0x80000
	s_and_b32 s61, s61, 0xf8
	s_mov_b64 s[26:27], s[100:101]
	s_sub_i32 s60, s60, s61
	s_lshl_b32 s5, s5, 3
	s_sext_i32_i8 s60, s60
	s_add_i32 s60, s5, s60
	s_sext_i32_i16 s62, s62
	s_ashr_i32 s61, s60, 31
	s_lshr_b32 s64, s62, 3
	s_ashr_i32 s89, s62, 3
	s_lshl_b64 s[62:63], s[60:61], 19
	s_waitcnt lgkmcnt(0)
	s_add_u32 s5, s26, s62
	s_addc_u32 s61, s27, s63
	s_add_u32 s62, s5, 0x5800000
	s_addc_u32 s63, s61, 0
	s_bfe_i64 s[64:65], s[64:65], 0x100000
	s_lshl_b64 s[64:65], s[64:65], 19
	s_add_u32 s5, s26, s64
	s_addc_u32 s26, s27, s65
	s_add_u32 s64, s5, 0xb00000
	s_addc_u32 s65, s26, 0

.LBB0_822:
	v_mov_b32_e32 v233, v244
	s_mov_b64 s[26:27], s[0:1]
	s_mov_b64 s[68:69], s[100:101]
	s_load_dwordx2 s[72:73], s[26:27], 0x0
	s_nop 0
	s_load_dwordx2 s[26:27], s[26:27], 0x20
	s_ashr_i32 s92, s4, 3
	s_ashr_i32 s93, s92, 31
	s_lshl_b64 s[70:71], s[92:93], 22
	s_waitcnt lgkmcnt(0)
	s_add_u32 s70, s68, s70
	s_addc_u32 s71, s69, s71
	s_add_u32 s5, s68, 0x100000
	s_mulk_i32 s92, 0xc00
	s_addc_u32 s61, s69, 0
	s_lshl_b32 s77, s90, 8
	s_ashr_i32 s93, s92, 31
	s_or_b32 s77, s77, s80
	v_ashrrev_i32_e32 v104, 1, v233
	s_lshl_b64 s[94:95], s[92:93], 2
	v_and_b32_e32 v104, -8, v104
	s_add_u32 s94, s5, s94
	v_add_u32_e32 v144, s77, v104
	s_addc_u32 s95, s61, s95
	s_addk_i32 s92, 0x6c00
	s_ashr_i32 s93, s92, 31
	v_ashrrev_i32_e32 v145, 31, v144
	s_lshl_b64 s[92:93], s[92:93], 2
	v_lshlrev_b64 v[146:147], 2, v[144:145]
	s_add_u32 s92, s5, s92
	v_lshl_add_u64 v[104:105], s[94:95], 0, v[146:147]
	s_movk_i32 s5, 0x2000
	v_lshl_add_u64 v[156:157], v[104:105], 0, s[12:13]
	v_add_co_u32_e32 v104, vcc, s5, v104
	v_lshl_add_u64 v[128:129], s[26:27], 0, v[146:147]
	s_nop 0
	v_addc_co_u32_e32 v105, vcc, 0, v105, vcc
	s_addc_u32 s93, s61, s93
	v_lshl_add_u64 v[158:159], v[128:129], 0, s[14:15]
	v_add_co_u32_e32 v128, vcc, s85, v128
	v_lshl_add_u64 v[148:149], s[92:93], 0, v[146:147]
	s_nop 0
	v_addc_co_u32_e32 v129, vcc, 0, v129, vcc
	v_lshl_add_u64 v[160:161], v[148:149], 0, s[14:15]
	v_add_co_u32_e32 v148, vcc, s85, v148
	global_load_dwordx4 v[108:111], v[104:105], off
	s_nop 0
	global_load_dwordx4 v[104:107], v[156:157], off offset:16
	v_addc_co_u32_e32 v149, vcc, 0, v149, vcc
	global_load_dwordx4 v[128:131], v[128:129], off
	s_nop 0
	global_load_dwordx4 v[132:135], v[158:159], off offset:16
	s_nop 0
	global_load_dwordx4 v[148:151], v[148:149], off
	s_nop 0
	global_load_dwordx4 v[152:155], v[160:161], off offset:16
	s_ashr_i32 s5, s4, 31
	s_lshl_b64 s[4:5], s[4:5], 8
	s_add_u32 s4, s4, s79
	s_addc_u32 s5, s5, 0
	v_and_or_b32 v224, v233, 15, s4
	v_mov_b32_e32 v225, s5
	s_mov_b32 s4, 0x10000
	v_lshl_add_u64 v[144:145], v[144:145], 1, s[70:71]
	v_lshl_add_u64 v[220:221], v[144:145], 0, s[34:35]
	s_lshl_b32 s26, s90, 2
	s_ashr_i32 s27, s26, 31
	s_lshl_b64 s[26:27], s[26:27], 2
	s_add_u32 s26, s68, s26
	s_addc_u32 s27, s69, s27
	s_add_u32 s26, s26, s87
	s_addc_u32 s27, s27, 0
	s_add_u32 s68, s26, 0x1700000
	s_addc_u32 s69, s27, 0
	s_waitcnt vmcnt(0)
	v_pk_add_f32 v[148:149], v[148:149], 1.0 op_sel_hi:[1,0]
	s_nop 0
	v_pk_mul_f32 v[128:129], v[128:129], v[148:149]
	v_pk_add_f32 v[150:151], v[150:151], 1.0 op_sel_hi:[1,0]
	v_cmp_nlt_f32_e64 vcc, |v128|, s86
	v_pk_mul_f32 v[130:131], v[130:131], v[150:151]
	s_nop 0
	v_cndmask_b32_e32 v204, v232, v128, vcc
	v_cmp_nlt_f32_e64 vcc, |v129|, s86
	s_nop 1
	v_cndmask_b32_e32 v205, v232, v129, vcc
	v_cmp_nlt_f32_e64 vcc, |v130|, s86
	v_pk_add_f32 v[128:129], v[154:155], 1.0 op_sel_hi:[1,0]
	s_nop 0
	v_cndmask_b32_e32 v206, v232, v130, vcc
	v_cmp_nlt_f32_e64 vcc, |v131|, s86
	v_pk_mul_f32 v[128:129], v[134:135], v[128:129]
	s_nop 0
	v_cndmask_b32_e32 v207, v232, v131, vcc
	v_pk_add_f32 v[130:131], v[152:153], 1.0 op_sel_hi:[1,0]
	s_nop 0
	v_pk_mul_f32 v[130:131], v[132:133], v[130:131]
	s_nop 0
	v_cmp_nlt_f32_e64 vcc, |v130|, s86
	s_nop 1
	v_cndmask_b32_e32 v208, v232, v130, vcc
	v_cmp_nlt_f32_e64 vcc, |v131|, s86
	s_nop 1
	v_cndmask_b32_e32 v209, v232, v131, vcc
	v_cmp_nlt_f32_e64 vcc, |v128|, s86
	s_nop 1
	v_cndmask_b32_e32 v210, v232, v128, vcc
	v_cmp_nlt_f32_e64 vcc, |v129|, s86
	s_nop 1
	v_cndmask_b32_e32 v211, v232, v129, vcc
	global_load_dwordx4 v[128:131], v[156:157], off offset:528
	global_load_dwordx4 v[132:135], v[156:157], off offset:512
	global_load_dwordx4 v[148:151], v[158:159], off offset:528
	global_load_dwordx4 v[152:155], v[158:159], off offset:512
	s_nop 0
	global_load_dwordx4 v[156:159], v[160:161], off offset:528
	s_nop 0
	global_load_dwordx4 v[160:163], v[160:161], off offset:512
	s_waitcnt vmcnt(0)
	v_pk_add_f32 v[160:161], v[160:161], 1.0 op_sel_hi:[1,0]
	s_nop 0
	v_pk_mul_f32 v[152:153], v[152:153], v[160:161]
	v_pk_add_f32 v[162:163], v[162:163], 1.0 op_sel_hi:[1,0]
	v_cmp_nlt_f32_e64 vcc, |v152|, s86
	v_pk_mul_f32 v[154:155], v[154:155], v[162:163]
	s_nop 0
	v_cndmask_b32_e32 v212, v232, v152, vcc
	v_cmp_nlt_f32_e64 vcc, |v153|, s86
	s_nop 1
	v_cndmask_b32_e32 v213, v232, v153, vcc
	v_cmp_nlt_f32_e64 vcc, |v154|, s86
	v_pk_add_f32 v[152:153], v[158:159], 1.0 op_sel_hi:[1,0]
	s_nop 0
	v_cndmask_b32_e32 v218, v232, v154, vcc
	v_cmp_nlt_f32_e64 vcc, |v155|, s86
	v_pk_mul_f32 v[150:151], v[150:151], v[152:153]
	s_nop 0
	v_cndmask_b32_e32 v219, v232, v155, vcc
	v_pk_add_f32 v[154:155], v[156:157], 1.0 op_sel_hi:[1,0]
	s_nop 0
	v_pk_mul_f32 v[148:149], v[148:149], v[154:155]
	s_nop 0
	v_cmp_nlt_f32_e64 vcc, |v148|, s86
	s_nop 1
	v_cndmask_b32_e32 v214, v232, v148, vcc
	v_cmp_nlt_f32_e64 vcc, |v149|, s86
	s_nop 1
	v_cndmask_b32_e32 v215, v232, v149, vcc
	v_lshlrev_b64 v[148:149], 12, v[224:225]
	v_cmp_nlt_f32_e64 vcc, |v150|, s86
	v_lshl_add_u64 v[148:149], s[72:73], 0, v[148:149]
	v_lshl_add_u64 v[222:223], v[148:149], 0, v[146:147]
	v_cndmask_b32_e32 v216, v232, v150, vcc
	v_cmp_nlt_f32_e64 vcc, |v151|, s86
	v_lshl_add_u64 v[146:147], v[222:223], 0, s[16:17]
	global_load_dwordx4 v[184:187], v[222:223], off offset:16 nt
	global_load_dwordx4 v[188:191], v[222:223], off nt
	global_load_dwordx4 v[176:179], v[222:223], off offset:528 nt
	global_load_dwordx4 v[180:183], v[222:223], off offset:512 nt
	v_cndmask_b32_e32 v217, v232, v151, vcc
	v_add_co_u32_e32 v148, vcc, s4, v222
	v_lshl_add_u64 v[144:145], v[222:223], 0, s[36:37]
	s_nop 0
	v_addc_co_u32_e32 v149, vcc, 0, v223, vcc
	global_load_dwordx4 v[172:175], v[148:149], off nt
	global_load_dwordx4 v[168:171], v[146:147], off offset:16 nt
	v_lshl_add_u64 v[146:147], v[222:223], 0, s[18:19]
	global_load_dwordx4 v[164:167], v[148:149], off offset:512 nt
	global_load_dwordx4 v[160:163], v[146:147], off offset:16 nt
	v_add_co_u32_e32 v146, vcc, s88, v222
	v_cmp_gt_u32_e64 s[4:5], 16, v233
	s_nop 0
	v_addc_co_u32_e32 v147, vcc, 0, v223, vcc
	global_load_dwordx4 v[156:159], v[146:147], off nt
	global_load_dwordx4 v[152:155], v[144:145], off offset:16 nt
	v_lshl_add_u64 v[144:145], v[222:223], 0, s[38:39]
	global_load_dwordx4 v[148:151], v[146:147], off offset:512 nt
	s_nop 0
	global_load_dwordx4 v[144:147], v[144:145], off offset:16 nt
	s_waitcnt vmcnt(10)
	v_pk_fma_f32 v[142:143], v[142:143], v[110:111], v[190:191]
	v_pk_fma_f32 v[140:141], v[140:141], v[108:109], v[188:189]
	v_pk_fma_f32 v[136:137], v[136:137], v[104:105], v[184:185]
	v_mul_f32_e32 v184, v141, v141
	v_mul_f32_e32 v185, v143, v143
	v_fmac_f32_e32 v184, v140, v140
	v_fmac_f32_e32 v185, v142, v142
	v_add_f32_e32 v184, v184, v185
	v_mul_f32_e32 v185, v137, v137
	v_pk_fma_f32 v[138:139], v[138:139], v[106:107], v[186:187]
	v_fmac_f32_e32 v185, v136, v136
	v_add_f32_e32 v184, v184, v185
	v_mul_f32_e32 v185, v139, v139
	v_fmac_f32_e32 v185, v138, v138
	v_lshlrev_b64 v[234:235], 11, v[224:225]
	v_add_f32_e32 v186, v185, v184
	v_pk_mul_f32 v[142:143], v[206:207], v[142:143]
	v_pk_mul_f32 v[140:141], v[204:205], v[140:141]
	v_pk_mul_f32 v[184:185], v[210:211], v[138:139]
	v_pk_mul_f32 v[138:139], v[208:209], v[136:137]
	v_lshl_add_u64 v[234:235], v[220:221], 0, v[234:235]
	v_cvt_pk_bf16_f32 v136, v140, v141
	v_cvt_pk_bf16_f32 v137, v142, v143
	v_cvt_pk_bf16_f32 v138, v138, v139
	v_cvt_pk_bf16_f32 v139, v184, v185
	s_waitcnt vmcnt(8)
	v_pk_fma_f32 v[126:127], v[126:127], v[134:135], v[182:183]
	v_pk_fma_f32 v[124:125], v[124:125], v[132:133], v[180:181]
	global_store_dwordx4 v[234:235], v[136:139], off
	v_pk_fma_f32 v[120:121], v[120:121], v[128:129], v[176:177]
	v_pk_fma_f32 v[122:123], v[122:123], v[130:131], v[178:179]
	v_mul_f32_e32 v136, v125, v125
	v_mul_f32_e32 v137, v127, v127
	v_fmac_f32_e32 v136, v124, v124
	v_fmac_f32_e32 v137, v126, v126
	v_add_f32_e32 v136, v136, v137
	v_mul_f32_e32 v137, v121, v121
	v_fmac_f32_e32 v137, v120, v120
	v_add_f32_e32 v136, v136, v137
	v_mul_f32_e32 v137, v123, v123
	v_fmac_f32_e32 v137, v122, v122
	v_add_f32_e32 v136, v137, v136
	v_add_f32_e32 v140, v186, v136
	ds_bpermute_b32 v141, v226, v140
	v_pk_mul_f32 v[138:139], v[120:121], v[214:215]
	v_pk_mul_f32 v[126:127], v[126:127], v[218:219]
	v_pk_mul_f32 v[124:125], v[124:125], v[212:213]
	v_pk_mul_f32 v[136:137], v[122:123], v[216:217]
	s_waitcnt lgkmcnt(0)
	v_add_f32_e32 v120, v140, v141
	ds_bpermute_b32 v121, v227, v120
	v_cvt_pk_bf16_f32 v122, v124, v125
	v_cvt_pk_bf16_f32 v123, v126, v127
	v_cvt_pk_bf16_f32 v124, v138, v139
	v_cvt_pk_bf16_f32 v125, v136, v137
	global_store_dwordx4 v[234:235], v[122:125], off offset:256
	s_and_saveexec_b64 s[70:71], s[4:5]
	s_cbranch_execz .LBB0_824
	v_lshlrev_b64 v[122:123], 6, v[224:225]
	v_lshl_add_u64 v[122:123], s[68:69], 0, v[122:123]
	s_waitcnt lgkmcnt(0)
	v_add_f32_e32 v120, v120, v121
	global_store_dword v[122:123], v120, off

.LBB0_907:
	s_and_b64 vcc, exec, s[4:5]
	s_cbranch_vccz .LBB0_917
	s_mov_b64 s[6:7], s[0:1]
	v_mov_b32_e32 v0, v244
	s_waitcnt vmcnt(0)
	s_waitcnt lgkmcnt(0)
	v_sub_u32_e32 v0, 0, v0
	v_cmp_eq_u32_e32 vcc, s76, v0
	s_barrier
	s_and_saveexec_b64 s[4:5], vcc
	s_cbranch_execz .LBB0_916
	s_mov_b64 s[6:7], s[100:101]
	s_lshl_b32 s3, s2, 9
	s_and_b32 s3, s3, 0xe00
	s_mov_b64 s[8:9], exec
	v_mbcnt_lo_u32_b32 v0, s8, 0
	s_waitcnt lgkmcnt(0)
	s_add_u32 s3, s6, s3
	s_addc_u32 s7, s7, 0
	s_add_u32 s6, s3, 0x30000
	v_mbcnt_hi_u32_b32 v0, s9, v0
	s_addc_u32 s7, s7, 0
	v_cmp_eq_u32_e32 vcc, 0, v0
	s_and_saveexec_b64 s[10:11], vcc
	s_cbranch_execz .LBB0_911
	s_bcnt1_i32_b64 s3, s[8:9]
	v_mov_b32_e32 v1, 0
	v_mov_b32_e32 v2, s3
	global_atomic_add v1, v1, v2, s[6:7] sc0

.LBB0_918:
	s_cmp_lt_i32 s20, 7
	s_cselect_b64 s[4:5], -1, 0
	s_cmp_gt_i32 s21, 6
	s_cselect_b64 s[6:7], -1, 0
	s_and_b64 s[4:5], s[4:5], s[6:7]
	s_andn2_b64 vcc, exec, s[4:5]
	s_cbranch_vccnz .LBB0_1426
	s_mov_b64 s[4:5], s[0:1]
	v_mov_b32_e32 v0, v244
	s_mov_b64 s[10:11], s[100:101]
	s_cmp_gt_u32 s74, 63
	s_cbranch_scc1 .LBB0_929
	s_waitcnt lgkmcnt(0)
	s_add_u32 s4, s10, 0x28300
	s_addc_u32 s5, s11, 0
	s_add_u32 s6, s10, 0x28200
	s_addc_u32 s7, s11, 0
	s_mov_b32 s3, 0x3fffff
	s_waitcnt vmcnt(0)
	v_mov_b32_e32 v1, 0
	s_movk_i32 s14, 0x80
	s_branch .LBB0_922

.LBB0_941:
	s_or_b64 exec, exec, s[6:7]
	s_ashr_i32 s81, s2, 31
	s_lshr_b32 s4, s81, 29
	s_add_i32 s4, s2, s4
	s_and_b32 s5, s4, -8
	v_cndmask_b32_e64 v0, 0, 1, s[8:9]
	s_sub_i32 s82, s2, s5
	s_ashr_i32 s83, s4, 3
	v_mov_b32_e32 v8, v244
	v_cmp_ne_u32_e64 s[4:5], 1, v0
	s_andn2_b64 vcc, exec, s[8:9]
	s_waitcnt lgkmcnt(0)
	s_barrier
	s_cbranch_vccnz .LBB0_943
	s_mul_i32 s6, s82, 0x60
	s_add_i32 s6, s6, s83
	s_mul_hi_i32 s7, s6, 0x2aaaaaab
	s_lshr_b32 s8, s7, 31
	s_lshr_b32 s7, s7, 4
	s_add_i32 s7, s7, s8
	s_mulk_i32 s7, 0x60
	s_sub_i32 s8, s6, s7
	s_bfe_i32 s6, s8, 0x80000
	s_bfe_u32 s6, s6, 0x3000c
	s_add_i32 s9, s8, s6
	s_bfe_i32 s6, s9, 0x80000
	s_sext_i32_i16 s18, s6
	s_lshr_b32 s6, s18, 3
	s_bfe_i64 s[6:7], s[6:7], 0x100000
	s_lshl_b64 s[10:11], s[6:7], 19
	s_and_b32 s7, s9, 0xf8
	s_mov_b64 s[12:13], s[0:1]
	s_sub_i32 s7, s8, s7
	s_lshl_b32 s6, s82, 3
	s_sext_i32_i8 s7, s7
	s_mov_b64 s[12:13], s[100:101]
	s_add_i32 s6, s6, s7
	s_ashr_i32 s8, s6, 3
	s_ashr_i32 s9, s8, 31
	s_ashr_i32 s7, s6, 31
	s_lshl_b64 s[8:9], s[8:9], 22
	s_lshl_b64 s[14:15], s[6:7], 19
	s_ashr_i32 s29, s18, 3
	s_waitcnt lgkmcnt(0)
	s_add_u32 s7, s12, s14
	s_addc_u32 s14, s13, s15
	s_add_u32 s7, s7, s8
	s_addc_u32 s9, s14, s9
	s_add_u32 s8, s7, 0x1800000
	s_addc_u32 s9, s9, 0
	s_add_u32 s7, s12, s10
	s_addc_u32 s11, s13, s11
	s_add_u32 s10, s7, 0xd00000
	s_addc_u32 s11, s11, 0
	s_branch .LBB0_944

.LBB0_950:
	s_add_i32 s93, s93, 1
	s_mul_i32 s7, s93, s33
	s_add_i32 s7, s7, s2
	s_cmpk_lt_i32 s7, 0x300
	s_cselect_b64 s[54:55], -1, 0
	s_cmpk_gt_i32 s7, 0x2ff
	s_cbranch_scc1 .LBB0_952
	s_ashr_i32 s30, s7, 31
	s_lshr_b32 s30, s30, 29
	s_add_i32 s30, s7, s30
	s_ashr_i32 s31, s30, 3
	s_and_b32 s30, s30, -8
	s_sub_i32 s7, s7, s30
	s_mul_i32 s30, s7, 0x60
	s_add_i32 s30, s30, s31
	s_mul_hi_i32 s31, s30, 0x2aaaaaab
	s_lshr_b32 s50, s31, 31
	s_lshr_b32 s31, s31, 4
	s_add_i32 s31, s31, s50
	s_mulk_i32 s31, 0x60
	s_sub_i32 s30, s30, s31
	s_bfe_i32 s31, s30, 0x80000
	s_bfe_u32 s31, s31, 0x3000c
	s_mov_b64 s[26:27], s[0:1]
	s_add_i32 s31, s30, s31
	s_bfe_i32 s50, s31, 0x80000
	s_and_b32 s31, s31, 0xf8
	s_mov_b64 s[26:27], s[100:101]
	s_sub_i32 s30, s30, s31
	s_lshl_b32 s7, s7, 3
	s_sext_i32_i8 s30, s30
	s_sext_i32_i16 s51, s50
	s_add_i32 s50, s7, s30
	s_lshr_b32 s56, s51, 3
	s_ashr_i32 s30, s51, 3
	s_ashr_i32 s51, s50, 31
	s_lshl_b64 s[52:53], s[50:51], 19
	s_waitcnt lgkmcnt(0)
	s_add_u32 s7, s26, s52
	s_addc_u32 s31, s27, s53
	s_ashr_i32 s52, s50, 3
	s_ashr_i32 s53, s52, 31
	s_lshl_b64 s[52:53], s[52:53], 22
	s_add_u32 s7, s7, s52
	s_addc_u32 s31, s31, s53
	s_add_u32 s52, s7, 0x1800000
	s_addc_u32 s53, s31, 0
	s_bfe_i64 s[56:57], s[56:57], 0x100000
	s_lshl_b64 s[56:57], s[56:57], 19
	s_add_u32 s7, s26, s56
	s_addc_u32 s26, s27, s57
	s_add_u32 s56, s7, 0xd00000
	s_addc_u32 s57, s26, 0

.LBB0_956:
	v_mov_b32_e32 v1, v244
	s_mov_b64 s[8:9], s[0:1]
	s_mov_b64 s[10:11], s[100:101]
	v_and_b32_e32 v172, 15, v1
	v_or_b32_e32 v154, s41, v172
	s_waitcnt lgkmcnt(0)
	s_add_u32 s58, s10, 0x1700000
	s_addc_u32 s59, s11, 0
	s_ashr_i32 s7, s6, 31
	s_lshl_b64 s[8:9], s[6:7], 8
	s_cmp_lg_u32 s6, s78
	s_cselect_b64 s[60:61], -1, 0
	v_lshl_add_u64 v[162:163], s[8:9], 0, v[154:155]
	s_mov_b64 s[8:9], -1
	s_and_b64 vcc, exec, s[60:61]
	s_cbranch_vccz .LBB0_958
	v_lshlrev_b64 v[130:131], 6, v[162:163]
	v_lshl_add_u64 v[142:143], s[58:59], 0, v[130:131]
	global_load_dwordx4 v[130:133], v[142:143], off
	global_load_dwordx4 v[134:137], v[142:143], off offset:16
	global_load_dwordx4 v[138:141], v[142:143], off offset:32
	s_nop 0
	global_load_dwordx4 v[142:145], v[142:143], off offset:48
	s_mov_b64 s[8:9], 0
	s_waitcnt vmcnt(0)
	v_mov_b32_e32 v160, v131
	v_mov_b32_e32 v161, v132
	v_mov_b32_e32 v131, v133
	v_mov_b32_e32 v132, v135
	v_mov_b32_e32 v133, v136
	v_mov_b32_e32 v135, v137
	v_pk_add_f32 v[130:131], v[160:161], v[130:131]
	v_pk_add_f32 v[132:133], v[132:133], v[134:135]
	v_pk_add_f32 v[130:131], v[130:131], v[130:131] op_sel:[0,1] op_sel_hi:[1,0]
	v_pk_add_f32 v[132:133], v[132:133], v[132:133] op_sel:[0,1] op_sel_hi:[1,0]
	v_add_f32_e32 v136, v138, v139
	v_add_f32_e32 v138, v140, v141
	v_mov_b32_e32 v137, v144
	v_mov_b32_e32 v139, v145
	v_mov_b32_e32 v131, v142
	v_mov_b32_e32 v133, v143
	v_pk_add_f32 v[134:135], v[136:137], v[138:139]
	v_pk_add_f32 v[130:131], v[130:131], v[132:133]
	s_nop 0
	v_pk_add_f32 v[130:131], v[130:131], v[134:135]
	s_nop 0
	v_add_f32_e32 v130, v130, v131
	v_fmamk_f32 v130, v130, 0x3a800000, v170
	v_mul_f32_e32 v131, 0x4b800000, v130
	v_cmp_gt_f32_e32 vcc, s96, v130
	s_nop 1
	v_cndmask_b32_e32 v130, v130, v131, vcc
	v_rsq_f32_e32 v130, v130
	s_nop 0
	v_mul_f32_e32 v131, 0x45800000, v130
	v_cndmask_b32_e32 v154, v130, v131, vcc

.LBB0_1280:
	s_lshr_b32 s6, s83, 31
	s_add_i32 s6, s83, s6
	s_and_b32 s6, s6, -2
	v_cndmask_b32_e64 v0, 0, 1, s[16:17]
	s_sub_i32 s35, s83, s6
	v_mov_b32_e32 v8, v244
	v_cmp_ne_u32_e64 s[6:7], 1, v0
	s_andn2_b64 vcc, exec, s[16:17]
	s_cbranch_vccnz .LBB0_1282
	s_lshr_b32 s9, s81, 28
	s_mov_b64 s[10:11], s[0:1]
	s_add_i32 s9, s2, s9
	s_lshl_b32 s8, s82, 4
	s_ashr_i32 s9, s9, 4
	s_mov_b64 s[10:11], s[100:101]
	s_add_i32 s54, s8, s9
	s_ashr_i32 s18, s54, 4
	s_add_i32 s8, s35, 12
	s_mov_b32 s9, 0
	s_ashr_i32 s55, s54, 31
	s_ashr_i32 s19, s18, 31
	s_lshl_b64 s[8:9], s[8:9], 19
	s_lshl_b64 s[16:17], s[54:55], 18
	s_lshl_b64 s[18:19], s[18:19], 22
	s_waitcnt lgkmcnt(0)
	s_add_u32 s8, s10, s8
	s_addc_u32 s9, s11, s9
	s_add_u32 s52, s8, 0xd00000
	s_addc_u32 s53, s9, 0
	s_add_u32 s8, s10, s16
	s_addc_u32 s9, s11, s17
	s_add_u32 s8, s8, s18
	s_addc_u32 s9, s9, s19
	s_add_u32 s56, s8, 0x1800000
	s_addc_u32 s57, s9, 0
	s_and_b64 vcc, exec, s[6:7]
	s_cbranch_vccz .LBB0_1283
	s_branch .LBB0_1350

.LBB0_1288:
	s_add_i32 s73, s73, 1
	s_mul_i32 s6, s73, s33
	s_add_i32 s6, s6, s2
	s_cmpk_lt_i32 s6, 0x100
	s_cselect_b64 s[50:51], -1, 0
	s_cmpk_gt_i32 s6, 0xff
	s_cbranch_scc1 .LBB0_1290
	s_ashr_i32 s7, s6, 31
	s_lshr_b32 s8, s7, 29
	s_add_i32 s8, s6, s8
	s_and_b32 s44, s8, 0xffffff8
	s_lshr_b32 s7, s7, 28
	s_sub_i32 s44, s6, s44
	s_add_i32 s6, s6, s7
	s_mov_b64 s[26:27], s[0:1]
	s_lshl_b32 s44, s44, 4
	s_ashr_i32 s6, s6, 4
	s_ashr_i32 s45, s8, 3
	s_add_i32 s44, s44, s6
	s_lshr_b32 s6, s8, 31
	s_mov_b64 s[26:27], s[100:101]
	s_add_i32 s6, s45, s6
	s_and_b32 s6, s6, -2
	s_sub_i32 s78, s45, s6
	s_add_i32 s8, s78, 12
	s_lshl_b64 s[6:7], s[8:9], 19
	s_waitcnt lgkmcnt(0)
	s_add_u32 s6, s26, s6
	s_addc_u32 s7, s27, s7
	s_add_u32 s46, s6, 0xd00000
	s_addc_u32 s47, s7, 0
	s_ashr_i32 s45, s44, 31
	s_lshl_b64 s[6:7], s[44:45], 18
	s_add_u32 s8, s26, s6
	s_addc_u32 s26, s27, s7
	s_ashr_i32 s6, s44, 4
	s_ashr_i32 s7, s6, 31
	s_lshl_b64 s[6:7], s[6:7], 22
	s_add_u32 s6, s8, s6
	s_addc_u32 s7, s26, s7
	s_add_u32 s48, s6, 0x1800000
	s_addc_u32 s49, s7, 0

.LBB0_1294:
	v_mov_b32_e32 v90, v244
	s_mov_b64 s[6:7], s[0:1]
	s_ashr_i32 s55, s54, 31
	s_mov_b64 s[52:53], s[100:101]
	s_mov_b32 s79, 0
	s_lshl_b64 s[6:7], s[54:55], 7
	s_or_b64 s[6:7], s[6:7], s[12:13]
	s_ashr_i32 s8, s79, 31
	v_ashrrev_i32_e32 v0, 1, v90
	s_add_u32 s6, s79, s6
	v_and_b32_e32 v86, -8, v0
	s_addc_u32 s7, s8, s7
	v_ashrrev_i32_e32 v87, 31, v86
	s_cmp_eq_u32 s54, s37
	v_lshl_add_u64 v[84:85], s[6:7], 0, v[86:87]
	s_cselect_b64 s[6:7], -1, 0
	s_mov_b64 s[56:57], -1
	s_and_b64 vcc, exec, s[6:7]
	s_cbranch_vccnz .LBB0_1296
	v_lshlrev_b64 v[0:1], 6, v[84:85]
	s_waitcnt lgkmcnt(0)
	v_lshl_add_u64 v[100:101], s[52:53], 0, v[0:1]
	v_lshl_add_u64 v[88:89], v[100:101], 0, s[16:17]
	v_add_co_u32_e32 v100, vcc, 0x1700000, v100
	global_load_dwordx4 v[0:3], v[88:89], off offset:32
	global_load_dwordx4 v[4:7], v[88:89], off offset:16
	v_addc_co_u32_e32 v101, vcc, 0, v101, vcc
	global_load_dwordx4 v[100:103], v[100:101], off
	s_nop 0
	global_load_dwordx4 v[104:107], v[88:89], off offset:48
	s_waitcnt vmcnt(0)
	v_add_f32_e32 v0, v0, v1
	v_mov_b32_e32 v108, v5
	v_mov_b32_e32 v109, v6
	v_mov_b32_e32 v5, v7
	v_mov_b32_e32 v6, v101
	v_mov_b32_e32 v7, v102
	v_mov_b32_e32 v101, v103
	v_add_f32_e32 v2, v2, v3
	v_pk_add_f32 v[4:5], v[108:109], v[4:5]
	v_mov_b32_e32 v1, v106
	v_mov_b32_e32 v3, v107
	v_pk_add_f32 v[6:7], v[6:7], v[100:101]
	v_pk_add_f32 v[4:5], v[4:5], v[4:5] op_sel:[0,1] op_sel_hi:[1,0]
	v_pk_add_f32 v[0:1], v[0:1], v[2:3]
	v_pk_add_f32 v[2:3], v[6:7], v[6:7] op_sel:[0,1] op_sel_hi:[1,0]
	v_mov_b32_e32 v5, v105
	v_mov_b32_e32 v3, v104
	v_pk_add_f32 v[2:3], v[2:3], v[4:5]
	s_nop 0
	v_pk_add_f32 v[0:1], v[2:3], v[0:1]
	s_nop 0
	v_add_f32_e32 v0, v0, v1
	v_fmamk_f32 v0, v0, 0x3a800000, v98
	v_mul_f32_e32 v1, 0x4b800000, v0
	v_cmp_gt_f32_e32 vcc, s69, v0
	s_nop 1
	v_cndmask_b32_e32 v0, v0, v1, vcc
	v_rsq_f32_e32 v0, v0
	s_nop 0
	v_mul_f32_e32 v1, 0x45800000, v0
	v_cndmask_b32_e32 v0, v0, v1, vcc
	global_load_dwordx4 v[2:5], v[88:89], off offset:64
	global_load_dwordx4 v[100:103], v[88:89], off offset:80
	global_load_dwordx4 v[104:107], v[88:89], off offset:96
	global_load_dwordx4 v[108:111], v[88:89], off offset:112
	s_waitcnt vmcnt(3)
	v_mov_b32_e32 v6, v3
	v_mov_b32_e32 v7, v4
	v_mov_b32_e32 v3, v5
	s_waitcnt vmcnt(2)
	v_mov_b32_e32 v4, v101
	v_mov_b32_e32 v5, v102
	v_mov_b32_e32 v101, v103
	v_pk_add_f32 v[2:3], v[6:7], v[2:3]
	v_pk_add_f32 v[4:5], v[4:5], v[100:101]
	v_pk_add_f32 v[2:3], v[2:3], v[2:3] op_sel:[0,1] op_sel_hi:[1,0]
	v_pk_add_f32 v[4:5], v[4:5], v[4:5] op_sel:[0,1] op_sel_hi:[1,0]
	s_waitcnt vmcnt(1)
	v_add_f32_e32 v102, v104, v105
	v_add_f32_e32 v104, v106, v107
	s_waitcnt vmcnt(0)
	v_mov_b32_e32 v103, v110
	v_mov_b32_e32 v105, v111
	v_mov_b32_e32 v3, v108
	v_mov_b32_e32 v5, v109
	v_pk_add_f32 v[6:7], v[102:103], v[104:105]
	v_pk_add_f32 v[2:3], v[2:3], v[4:5]
	s_nop 0
	v_pk_add_f32 v[2:3], v[2:3], v[6:7]
	s_nop 0
	v_add_f32_e32 v1, v2, v3
	v_fmamk_f32 v1, v1, 0x3a800000, v98
	v_mul_f32_e32 v2, 0x4b800000, v1
	v_cmp_gt_f32_e32 vcc, s69, v1
	s_nop 1
	v_cndmask_b32_e32 v1, v1, v2, vcc
	v_rsq_f32_e32 v1, v1
	s_nop 0
	v_mul_f32_e32 v2, 0x45800000, v1
	v_cndmask_b32_e32 v1, v1, v2, vcc
	global_load_dwordx4 v[2:5], v[88:89], off offset:128
	global_load_dwordx4 v[100:103], v[88:89], off offset:144
	global_load_dwordx4 v[104:107], v[88:89], off offset:160
	global_load_dwordx4 v[108:111], v[88:89], off offset:176
	s_waitcnt vmcnt(3)
	v_mov_b32_e32 v6, v3
	v_mov_b32_e32 v7, v4
	v_mov_b32_e32 v3, v5
	s_waitcnt vmcnt(2)
	v_mov_b32_e32 v4, v101
	v_mov_b32_e32 v5, v102
	v_mov_b32_e32 v101, v103
	v_pk_add_f32 v[2:3], v[6:7], v[2:3]
	v_pk_add_f32 v[4:5], v[4:5], v[100:101]
	v_pk_add_f32 v[2:3], v[2:3], v[2:3] op_sel:[0,1] op_sel_hi:[1,0]
	v_pk_add_f32 v[4:5], v[4:5], v[4:5] op_sel:[0,1] op_sel_hi:[1,0]
	s_waitcnt vmcnt(1)
	v_add_f32_e32 v102, v104, v105
	v_add_f32_e32 v104, v106, v107
	s_waitcnt vmcnt(0)
	v_mov_b32_e32 v103, v110
	v_mov_b32_e32 v105, v111
	v_mov_b32_e32 v3, v108
	v_mov_b32_e32 v5, v109
	v_pk_add_f32 v[6:7], v[102:103], v[104:105]
	v_pk_add_f32 v[2:3], v[2:3], v[4:5]
	s_nop 0
	v_pk_add_f32 v[2:3], v[2:3], v[6:7]
	s_nop 0
	v_add_f32_e32 v2, v2, v3
	v_fmamk_f32 v2, v2, 0x3a800000, v98
	v_mul_f32_e32 v3, 0x4b800000, v2
	v_cmp_gt_f32_e32 vcc, s69, v2
	s_nop 1
	v_cndmask_b32_e32 v2, v2, v3, vcc
	v_rsq_f32_e32 v2, v2
	s_nop 0
	v_mul_f32_e32 v3, 0x45800000, v2
	v_cndmask_b32_e32 v2, v2, v3, vcc
	global_load_dwordx4 v[4:7], v[88:89], off offset:192
	global_load_dwordx4 v[100:103], v[88:89], off offset:208
	global_load_dwordx4 v[104:107], v[88:89], off offset:224
	global_load_dwordx4 v[108:111], v[88:89], off offset:240
	s_waitcnt vmcnt(3)
	v_mov_b32_e32 v112, v5
	v_mov_b32_e32 v113, v6
	v_mov_b32_e32 v5, v7
	s_waitcnt vmcnt(2)
	v_mov_b32_e32 v6, v101
	v_mov_b32_e32 v7, v102
	v_mov_b32_e32 v101, v103
	v_pk_add_f32 v[4:5], v[112:113], v[4:5]
	v_pk_add_f32 v[6:7], v[6:7], v[100:101]
	v_pk_add_f32 v[4:5], v[4:5], v[4:5] op_sel:[0,1] op_sel_hi:[1,0]
	v_pk_add_f32 v[6:7], v[6:7], v[6:7] op_sel:[0,1] op_sel_hi:[1,0]
	s_waitcnt vmcnt(1)
	v_add_f32_e32 v102, v104, v105
	v_add_f32_e32 v104, v106, v107
	s_waitcnt vmcnt(0)
	v_mov_b32_e32 v103, v110
	v_mov_b32_e32 v105, v111
	v_mov_b32_e32 v5, v108
	v_mov_b32_e32 v7, v109
	v_pk_add_f32 v[100:101], v[102:103], v[104:105]
	v_pk_add_f32 v[4:5], v[4:5], v[6:7]
	s_nop 0
	v_pk_add_f32 v[4:5], v[4:5], v[100:101]
	s_nop 0
	v_add_f32_e32 v3, v4, v5
	v_fmamk_f32 v3, v3, 0x3a800000, v98
	v_mul_f32_e32 v4, 0x4b800000, v3
	v_cmp_gt_f32_e32 vcc, s69, v3
	s_nop 1
	v_cndmask_b32_e32 v3, v3, v4, vcc
	v_rsq_f32_e32 v3, v3
	s_nop 0
	v_mul_f32_e32 v4, 0x45800000, v3
	v_cndmask_b32_e32 v3, v3, v4, vcc
	global_load_dwordx4 v[4:7], v[88:89], off offset:256
	global_load_dwordx4 v[100:103], v[88:89], off offset:272
	global_load_dwordx4 v[104:107], v[88:89], off offset:288
	global_load_dwordx4 v[108:111], v[88:89], off offset:304
	s_waitcnt vmcnt(3)
	v_mov_b32_e32 v112, v5
	v_mov_b32_e32 v113, v6
	v_mov_b32_e32 v5, v7
	s_waitcnt vmcnt(2)
	v_mov_b32_e32 v6, v101
	v_mov_b32_e32 v7, v102
	v_mov_b32_e32 v101, v103
	v_pk_add_f32 v[4:5], v[112:113], v[4:5]
	v_pk_add_f32 v[6:7], v[6:7], v[100:101]
	v_pk_add_f32 v[4:5], v[4:5], v[4:5] op_sel:[0,1] op_sel_hi:[1,0]
	v_pk_add_f32 v[6:7], v[6:7], v[6:7] op_sel:[0,1] op_sel_hi:[1,0]
	s_waitcnt vmcnt(1)
	v_add_f32_e32 v102, v104, v105
	v_add_f32_e32 v104, v106, v107
	s_waitcnt vmcnt(0)
	v_mov_b32_e32 v103, v110
	v_mov_b32_e32 v105, v111
	v_mov_b32_e32 v5, v108
	v_mov_b32_e32 v7, v109
	v_pk_add_f32 v[100:101], v[102:103], v[104:105]
	v_pk_add_f32 v[4:5], v[4:5], v[6:7]
	s_nop 0
	v_pk_add_f32 v[4:5], v[4:5], v[100:101]
	s_nop 0
	v_add_f32_e32 v4, v4, v5
	v_fmamk_f32 v4, v4, 0x3a800000, v98
	v_mul_f32_e32 v5, 0x4b800000, v4
	v_cmp_gt_f32_e32 vcc, s69, v4
	s_nop 1
	v_cndmask_b32_e32 v4, v4, v5, vcc
	v_rsq_f32_e32 v4, v4
	s_nop 0
	v_mul_f32_e32 v5, 0x45800000, v4
	v_cndmask_b32_e32 v4, v4, v5, vcc
	global_load_dwordx4 v[100:103], v[88:89], off offset:320
	global_load_dwordx4 v[104:107], v[88:89], off offset:336
	global_load_dwordx4 v[108:111], v[88:89], off offset:352
	global_load_dwordx4 v[112:115], v[88:89], off offset:368
	s_waitcnt vmcnt(3)
	v_mov_b32_e32 v6, v101
	v_mov_b32_e32 v7, v102
	v_mov_b32_e32 v101, v103
	s_waitcnt vmcnt(2)
	v_mov_b32_e32 v102, v105
	v_mov_b32_e32 v103, v106
	v_mov_b32_e32 v105, v107
	v_pk_add_f32 v[6:7], v[6:7], v[100:101]
	v_pk_add_f32 v[100:101], v[102:103], v[104:105]
	v_pk_add_f32 v[6:7], v[6:7], v[6:7] op_sel:[0,1] op_sel_hi:[1,0]
	v_pk_add_f32 v[100:101], v[100:101], v[100:101] op_sel:[0,1] op_sel_hi:[1,0]
	s_waitcnt vmcnt(1)
	v_add_f32_e32 v106, v108, v109
	v_add_f32_e32 v108, v110, v111
	s_waitcnt vmcnt(0)
	v_mov_b32_e32 v107, v114
	v_mov_b32_e32 v109, v115
	v_mov_b32_e32 v7, v112
	v_mov_b32_e32 v101, v113
	v_pk_add_f32 v[102:103], v[106:107], v[108:109]
	v_pk_add_f32 v[6:7], v[6:7], v[100:101]
	s_nop 0
	v_pk_add_f32 v[6:7], v[6:7], v[102:103]
	s_nop 0
	v_add_f32_e32 v5, v6, v7
	v_fmamk_f32 v5, v5, 0x3a800000, v98
	v_mul_f32_e32 v6, 0x4b800000, v5
	v_cmp_gt_f32_e32 vcc, s69, v5
	s_nop 1
	v_cndmask_b32_e32 v5, v5, v6, vcc
	v_rsq_f32_e32 v5, v5
	s_nop 0
	v_mul_f32_e32 v6, 0x45800000, v5
	v_cndmask_b32_e32 v5, v5, v6, vcc
	global_load_dwordx4 v[100:103], v[88:89], off offset:384
	global_load_dwordx4 v[104:107], v[88:89], off offset:400
	global_load_dwordx4 v[108:111], v[88:89], off offset:416
	global_load_dwordx4 v[112:115], v[88:89], off offset:432
	s_waitcnt vmcnt(3)
	v_mov_b32_e32 v6, v101
	v_mov_b32_e32 v7, v102
	v_mov_b32_e32 v101, v103
	s_waitcnt vmcnt(2)
	v_mov_b32_e32 v102, v105
	v_mov_b32_e32 v103, v106
	v_mov_b32_e32 v105, v107
	v_pk_add_f32 v[6:7], v[6:7], v[100:101]
	v_pk_add_f32 v[100:101], v[102:103], v[104:105]
	v_pk_add_f32 v[6:7], v[6:7], v[6:7] op_sel:[0,1] op_sel_hi:[1,0]
	v_pk_add_f32 v[100:101], v[100:101], v[100:101] op_sel:[0,1] op_sel_hi:[1,0]
	s_waitcnt vmcnt(1)
	v_add_f32_e32 v106, v108, v109
	v_add_f32_e32 v108, v110, v111
	s_waitcnt vmcnt(0)
	v_mov_b32_e32 v107, v114
	v_mov_b32_e32 v109, v115
	v_mov_b32_e32 v7, v112
	v_mov_b32_e32 v101, v113
	v_pk_add_f32 v[102:103], v[106:107], v[108:109]
	v_pk_add_f32 v[6:7], v[6:7], v[100:101]
	s_nop 0
	v_pk_add_f32 v[6:7], v[6:7], v[102:103]
	s_nop 0
	v_add_f32_e32 v6, v6, v7
	v_fmamk_f32 v6, v6, 0x3a800000, v98
	v_mul_f32_e32 v7, 0x4b800000, v6
	v_cmp_gt_f32_e32 vcc, s69, v6
	s_nop 1
	v_cndmask_b32_e32 v6, v6, v7, vcc
	v_rsq_f32_e32 v6, v6
	s_nop 0
	v_mul_f32_e32 v7, 0x45800000, v6
	v_cndmask_b32_e32 v6, v6, v7, vcc
	global_load_dwordx4 v[100:103], v[88:89], off offset:448
	global_load_dwordx4 v[104:107], v[88:89], off offset:464
	global_load_dwordx4 v[108:111], v[88:89], off offset:480
	global_load_dwordx4 v[112:115], v[88:89], off offset:496
	s_waitcnt vmcnt(3)
	v_mov_b32_e32 v88, v101
	v_mov_b32_e32 v89, v102
	v_mov_b32_e32 v101, v103
	s_waitcnt vmcnt(2)
	v_mov_b32_e32 v102, v105
	v_mov_b32_e32 v103, v106
	v_mov_b32_e32 v105, v107
	v_pk_add_f32 v[88:89], v[88:89], v[100:101]
	v_pk_add_f32 v[100:101], v[102:103], v[104:105]
	v_pk_add_f32 v[88:89], v[88:89], v[88:89] op_sel:[0,1] op_sel_hi:[1,0]
	v_pk_add_f32 v[100:101], v[100:101], v[100:101] op_sel:[0,1] op_sel_hi:[1,0]
	s_waitcnt vmcnt(1)
	v_add_f32_e32 v106, v108, v109
	v_add_f32_e32 v108, v110, v111
	s_waitcnt vmcnt(0)
	v_mov_b32_e32 v107, v114
	v_mov_b32_e32 v109, v115
	v_mov_b32_e32 v89, v112
	v_mov_b32_e32 v101, v113
	v_pk_add_f32 v[102:103], v[106:107], v[108:109]
	v_pk_add_f32 v[88:89], v[88:89], v[100:101]
	s_nop 0
	v_pk_add_f32 v[88:89], v[88:89], v[102:103]
	s_nop 0
	v_add_f32_e32 v7, v88, v89
	v_fmamk_f32 v7, v7, 0x3a800000, v98
	v_mul_f32_e32 v88, 0x4b800000, v7
	v_cmp_gt_f32_e32 vcc, s69, v7
	s_nop 1
	v_cndmask_b32_e32 v7, v7, v88, vcc
	v_rsq_f32_e32 v7, v7
	s_nop 0
	v_mul_f32_e32 v88, 0x45800000, v7
	v_cndmask_b32_e32 v7, v7, v88, vcc
	s_mov_b64 s[56:57], 0

.LBB0_1415:
	s_and_b64 vcc, exec, s[4:5]
	s_cbranch_vccz .LBB0_1425
	s_mov_b64 s[6:7], s[0:1]
	v_mov_b32_e32 v0, v244
	s_waitcnt vmcnt(0)
	s_waitcnt lgkmcnt(0)
	v_sub_u32_e32 v0, 0, v0
	v_cmp_eq_u32_e32 vcc, s76, v0
	s_barrier
	s_and_saveexec_b64 s[4:5], vcc
	s_cbranch_execz .LBB0_1424
	s_mov_b64 s[6:7], s[100:101]
	s_mov_b64 s[8:9], exec
	s_lshl_b32 s3, s2, 9
	s_and_b32 s3, s3, 0xe00
	v_mbcnt_lo_u32_b32 v0, s8, 0
	s_waitcnt lgkmcnt(0)
	s_add_u32 s6, s6, s3
	v_mbcnt_hi_u32_b32 v0, s9, v0
	s_addc_u32 s7, s7, 0
	v_cmp_eq_u32_e32 vcc, 0, v0
	s_and_saveexec_b64 s[10:11], vcc
	s_cbranch_execz .LBB0_1419
	s_bcnt1_i32_b64 s3, s[8:9]
	s_waitcnt vmcnt(0)
	v_mov_b32_e32 v1, 0x31000
	v_mov_b32_e32 v2, s3
	global_atomic_add v1, v1, v2, s[6:7] sc0

.LBB0_1429:
	s_load_dwordx2 s[8:9], s[12:13], 0x80
	s_load_dwordx4 s[4:7], s[12:13], 0x90
	s_mov_b64 s[10:11], s[100:101]
	s_lshl_b32 s12, s3, 6
	s_lshl_b32 s13, s75, 3
	s_add_i32 s42, s12, s13
	s_ashr_i32 s12, s3, 5
	s_and_b32 s26, s3, 3
	s_waitcnt lgkmcnt(0)
	s_add_u32 s34, s10, 0x1600000
	s_addc_u32 s35, s11, 0
	s_ashr_i32 s13, s12, 31
	s_lshl_b32 s3, s3, 5
	s_lshl_b64 s[14:15], s[12:13], 11
	s_and_b32 s3, s3, 0x380
	s_or_b32 s14, s14, s3
	s_mul_i32 s16, s12, 0x30000
	s_mul_hi_i32 s13, s12, 0x30000
	s_add_u32 s27, s10, s16
	s_addc_u32 s13, s11, s13
	s_lshl_b32 s16, s12, 2
	s_or_b32 s16, s16, s26
	s_ashr_i32 s17, s16, 31
	s_lshl_b64 s[18:19], s[16:17], 7
	s_lshl_b32 s3, s3, 1
	s_add_u32 s3, s27, s3
	s_addc_u32 s13, s13, 0
	s_add_u32 s36, s3, 0x8a00000
	s_addc_u32 s37, s13, 0
	s_lshl_b32 s16, s26, 7
	s_lshl_b32 s3, s26, 8
	s_add_u32 s3, s10, s3
	s_addc_u32 s13, s11, 0
	s_add_u32 s38, s3, 0x9c00000
	s_addc_u32 s39, s13, 0
	s_mul_hi_i32 s3, s12, 0x238000
	s_mul_i32 s12, s12, 0x238000
	s_add_u32 s12, s10, s12
	s_addc_u32 s3, s11, s3
	s_add_u32 s28, s12, 0xac00000
	s_addc_u32 s29, s3, 0
	s_and_b32 s3, s42, 0x7f8
	s_cmp_lg_u32 s3, 0
	s_cselect_b64 s[12:13], -1, 0
	s_ashr_i32 s26, s42, 11
	s_ashr_i32 s27, s26, 31
	s_lshl_b64 s[26:27], s[26:27], 18
	s_add_u32 s26, s10, s26
	s_addc_u32 s27, s11, s27
	s_add_u32 s26, s26, 0x7800000
	s_addc_u32 s27, s27, 0
	s_cmp_lg_u64 s[12:13], 0
	s_subb_u32 s12, s42, 0
	s_ashr_i32 s13, s12, 31
	s_lshl_b64 s[12:13], s[12:13], 10
	v_lshlrev_b32_e32 v126, 3, v0
	s_add_u32 s12, s26, s12
	v_ashrrev_i32_e32 v127, 31, v126
	s_addc_u32 s13, s27, s13
	v_lshlrev_b64 v[124:125], 1, v[126:127]
	v_lshl_add_u64 v[32:33], s[12:13], 0, v[124:125]
	v_lshl_add_u64 v[2:3], s[10:11], 0, v[124:125]
	s_mov_b64 s[12:13], 0xe200000
	s_ashr_i32 s43, s42, 31
	s_or_b32 s44, s42, 1
	s_waitcnt vmcnt(0)
	v_lshl_add_u64 v[0:1], s[26:27], 0, v[124:125]
	v_lshl_add_u64 v[2:3], v[2:3], 0, s[12:13]
	s_lshl_b64 s[12:13], s[42:43], 10
	s_ashr_i32 s45, s44, 31
	s_or_b32 s46, s42, 2
	v_lshl_add_u64 v[34:35], v[0:1], 0, s[12:13]
	v_lshl_add_u64 v[36:37], v[2:3], 0, s[12:13]
	s_lshl_b64 s[12:13], s[44:45], 10
	s_ashr_i32 s47, s46, 31
	s_or_b32 s48, s42, 3
	v_lshl_add_u64 v[38:39], v[0:1], 0, s[12:13]
	v_lshl_add_u64 v[40:41], v[2:3], 0, s[12:13]
	s_lshl_b64 s[12:13], s[46:47], 10
	s_ashr_i32 s49, s48, 31
	s_or_b32 s50, s42, 4
	v_lshl_add_u64 v[42:43], v[0:1], 0, s[12:13]
	v_lshl_add_u64 v[44:45], v[2:3], 0, s[12:13]
	s_lshl_b64 s[12:13], s[48:49], 10
	s_ashr_i32 s51, s50, 31
	s_or_b32 s52, s42, 5
	v_lshl_add_u64 v[46:47], v[0:1], 0, s[12:13]
	v_lshl_add_u64 v[48:49], v[2:3], 0, s[12:13]
	s_lshl_b64 s[12:13], s[50:51], 10
	s_ashr_i32 s53, s52, 31
	s_or_b32 s54, s42, 6
	v_lshl_add_u64 v[50:51], v[0:1], 0, s[12:13]
	v_lshl_add_u64 v[52:53], v[2:3], 0, s[12:13]
	s_lshl_b64 s[12:13], s[52:53], 10
	s_ashr_i32 s55, s54, 31
	s_or_b32 s56, s42, 7
	v_lshl_add_u64 v[54:55], v[0:1], 0, s[12:13]
	v_lshl_add_u64 v[128:129], v[2:3], 0, s[12:13]
	s_lshl_b64 s[12:13], s[54:55], 10
	s_ashr_i32 s57, s56, 31
	v_lshl_add_u64 v[130:131], v[0:1], 0, s[12:13]
	v_lshl_add_u64 v[132:133], v[2:3], 0, s[12:13]
	s_lshl_b64 s[12:13], s[56:57], 10
	v_lshl_add_u64 v[134:135], v[0:1], 0, s[12:13]
	v_lshl_add_u64 v[136:137], v[2:3], 0, s[12:13]
	s_and_b32 s12, s56, 0x7ff
	s_add_i32 s13, s42, 8
	s_cmpk_eq_i32 s12, 0x7ff
	v_mov_b32_e32 v0, v244
	s_cselect_b32 s12, s56, s13
	s_ashr_i32 s13, s12, 31
	v_add_u32_e32 v66, s76, v0
	v_ashrrev_i32_e32 v56, 4, v66
	s_lshl_b64 s[12:13], s[12:13], 10
	v_lshlrev_b32_e32 v0, 4, v0
	v_add_u32_e32 v12, 32, v56
	s_add_u32 s12, s26, s12
	v_and_b32_e32 v198, 0xf0, v0
	v_mov_b32_e32 v199, 0
	v_ashrrev_i32_e32 v13, 31, v12
	s_addc_u32 s13, s27, s13
	v_lshl_add_u64 v[58:59], s[36:37], 0, v[198:199]
	s_movk_i32 s63, 0x1080
	v_lshl_add_u64 v[14:15], s[18:19], 0, v[12:13]
	v_add_u32_e32 v28, 64, v56
	s_mov_b32 s17, 0
	v_lshl_add_u64 v[138:139], s[12:13], 0, v[124:125]
	v_ashrrev_i32_e32 v57, 31, v56
	v_mad_u64_u32 v[20:21], s[12:13], v14, s63, v[58:59]
	v_ashrrev_i32_e32 v29, 31, v28
	v_lshl_add_u64 v[0:1], s[18:19], 0, v[56:57]
	v_lshl_add_u64 v[4:5], v[56:57], 0, s[16:17]
	v_lshl_add_u64 v[6:7], s[14:15], 0, v[56:57]
	v_mad_i32_i24 v21, v15, s63, v21
	v_lshl_add_u64 v[14:15], v[12:13], 0, s[16:17]
	v_lshl_add_u64 v[12:13], s[14:15], 0, v[12:13]
	v_lshl_add_u64 v[22:23], s[18:19], 0, v[28:29]
	v_lshl_add_u64 v[30:31], v[28:29], 0, s[16:17]
	v_lshl_add_u64 v[28:29], s[14:15], 0, v[28:29]
	v_lshl_add_u64 v[60:61], s[34:35], 0, v[198:199]
	v_lshl_add_u64 v[62:63], s[38:39], 0, v[198:199]
	v_mad_u64_u32 v[2:3], s[12:13], v0, s63, v[58:59]
	v_lshlrev_b64 v[4:5], 8, v[4:5]
	v_lshlrev_b64 v[6:7], 10, v[6:7]
	v_lshlrev_b64 v[14:15], 8, v[14:15]
	v_lshlrev_b64 v[12:13], 10, v[12:13]
	v_mad_u64_u32 v[24:25], s[12:13], v22, s63, v[58:59]
	v_lshlrev_b64 v[30:31], 8, v[30:31]
	v_lshlrev_b64 v[28:29], 10, v[28:29]
	v_add_u32_e32 v56, 0x60, v56
	v_mad_i32_i24 v3, v1, s63, v3
	v_lshl_add_u64 v[4:5], v[60:61], 0, v[4:5]
	v_lshl_add_u64 v[6:7], v[62:63], 0, v[6:7]
	v_lshl_add_u64 v[14:15], v[60:61], 0, v[14:15]
	v_lshl_add_u64 v[16:17], v[62:63], 0, v[12:13]
	v_mad_i32_i24 v25, v23, s63, v25
	v_lshl_add_u64 v[30:31], v[60:61], 0, v[30:31]
	v_lshl_add_u64 v[64:65], v[62:63], 0, v[28:29]
	v_ashrrev_i32_e32 v57, 31, v56
	global_load_dwordx4 v[0:3], v[2:3], off nt
	s_nop 0
	global_load_dwordx4 v[8:11], v[4:5], off
	s_nop 0
	global_load_dwordx4 v[4:7], v[6:7], off nt
	s_nop 0
	global_load_dwordx4 v[12:15], v[14:15], off
	s_nop 0
	global_load_dwordx4 v[16:19], v[16:17], off nt
	s_nop 0
	global_load_dwordx4 v[20:23], v[20:21], off nt
	s_nop 0
	global_load_dwordx4 v[24:27], v[24:25], off nt
	s_nop 0
	global_load_dwordx4 v[28:31], v[30:31], off
	s_nop 0
	global_load_dwordx4 v[104:107], v[64:65], off nt
	v_lshl_add_u64 v[64:65], s[18:19], 0, v[56:57]
	v_mad_u64_u32 v[58:59], s[12:13], v64, s63, v[58:59]
	v_mad_i32_i24 v59, v65, s63, v59
	v_lshl_add_u64 v[64:65], v[56:57], 0, s[16:17]
	v_lshl_add_u64 v[56:57], s[14:15], 0, v[56:57]
	v_lshlrev_b64 v[64:65], 8, v[64:65]
	v_lshlrev_b64 v[56:57], 10, v[56:57]
	v_lshl_add_u64 v[60:61], v[60:61], 0, v[64:65]
	v_lshl_add_u64 v[56:57], v[62:63], 0, v[56:57]
	global_load_dwordx4 v[108:111], v[60:61], off
	global_load_dwordx4 v[112:115], v[56:57], off nt
	v_and_b32_e32 v56, 0x7f, v66
	v_or_b32_e32 v56, s14, v56
	v_mov_b32_e32 v57, s15
	v_lshl_add_u64 v[56:57], v[56:57], 4, s[28:29]
	global_load_dwordx4 v[116:119], v[58:59], off nt
	global_load_dwordx4 v[120:123], v[56:57], off
	global_load_dwordx4 v[100:103], v[32:33], off nt
	global_load_dwordx4 v[92:95], v[34:35], off nt
	global_load_dwordx4 v[96:99], v[36:37], off nt
	global_load_dwordx4 v[88:91], v[38:39], off nt
	global_load_dwordx4 v[84:87], v[40:41], off nt
	global_load_dwordx4 v[80:83], v[42:43], off nt
	global_load_dwordx4 v[76:79], v[44:45], off nt
	global_load_dwordx4 v[72:75], v[46:47], off nt
	global_load_dwordx4 v[68:71], v[48:49], off nt
	global_load_dwordx4 v[64:67], v[50:51], off nt
	global_load_dwordx4 v[60:63], v[52:53], off nt
	global_load_dwordx4 v[56:59], v[54:55], off nt
	s_nop 0
	global_load_dwordx4 v[52:55], v[128:129], off nt
	global_load_dwordx4 v[48:51], v[130:131], off nt
	global_load_dwordx4 v[44:47], v[132:133], off nt
	global_load_dwordx4 v[40:43], v[134:135], off nt
	global_load_dwordx4 v[32:35], v[136:137], off nt
	global_load_dwordx4 v[36:39], v[138:139], off nt
	v_mov_b32_e32 v207, v244
	s_movk_i32 s62, 0x80
	v_add_u32_e32 v128, s76, v207
	v_cmp_gt_i32_e32 vcc, s62, v128
	s_and_saveexec_b64 s[12:13], vcc
	s_cbranch_execz .LBB0_1431
	s_waitcnt vmcnt(18)
	v_mov_b32_e32 v130, v121
	v_mov_b32_e32 v131, v122
	v_mov_b32_e32 v121, v123
	v_pk_add_f32 v[120:121], v[130:131], v[120:121]
	s_mov_b32 s26, 0x800000
	v_add_f32_e32 v120, v120, v121
	v_mov_b32_e32 v121, 0x358637bd
	v_fmac_f32_e32 v121, 0x3b000000, v120
	v_mul_f32_e32 v120, 0x4b800000, v121
	v_cmp_gt_f32_e32 vcc, s26, v121
	s_nop 1
	v_cndmask_b32_e32 v120, v121, v120, vcc
	v_rsq_f32_e32 v120, v120
	s_nop 0
	v_mul_f32_e32 v121, 0x45800000, v120
	v_cndmask_b32_e32 v120, v120, v121, vcc
	v_lshl_add_u32 v121, v128, 2, 0
	v_add_u32_e32 v121, 0x18000, v121
	ds_write_b32 v121, v120

.LBB0_1498:
	s_and_b64 vcc, exec, s[4:5]
	s_cbranch_vccz .LBB0_1508
	s_mov_b64 s[6:7], s[0:1]
	v_mov_b32_e32 v0, v244
	s_waitcnt vmcnt(0)
	s_nop 0
	v_sub_u32_e32 v0, 0, v0
	v_cmp_eq_u32_e32 vcc, s76, v0
	s_barrier
	s_and_saveexec_b64 s[4:5], vcc
	s_cbranch_execz .LBB0_1507
	s_mov_b64 s[6:7], s[100:101]
	s_mov_b64 s[8:9], exec
	s_lshl_b32 s3, s2, 9
	s_and_b32 s3, s3, 0xe00
	v_mbcnt_lo_u32_b32 v0, s8, 0
	s_waitcnt lgkmcnt(0)
	s_add_u32 s6, s6, s3
	v_mbcnt_hi_u32_b32 v0, s9, v0
	s_addc_u32 s7, s7, 0
	v_cmp_eq_u32_e32 vcc, 0, v0
	s_and_saveexec_b64 s[10:11], vcc
	s_cbranch_execz .LBB0_1502
	s_bcnt1_i32_b64 s3, s[8:9]
	v_mov_b32_e32 v1, 0x32000
	v_mov_b32_e32 v2, s3
	global_atomic_add v1, v1, v2, s[6:7] sc0

.LBB0_1508:
.LBB0_1509:
	s_cmp_lt_i32 s20, 9
	s_cselect_b64 s[4:5], -1, 0
	s_cmp_gt_i32 s21, 8
	s_cselect_b64 s[6:7], -1, 0
	s_and_b64 s[4:5], s[4:5], s[6:7]
	s_andn2_b64 vcc, exec, s[4:5]
	s_cbranch_vccnz .LBB0_1526
	s_mov_b64 s[4:5], s[0:1]
	v_mov_b32_e32 v0, v244
	s_waitcnt vmcnt(0)
	v_mov_b32_e32 v9, v244
	s_cmpk_gt_i32 s2, 0xff
	s_cbranch_scc1 .LBB0_1526
	s_lshl_b32 s3, s75, 10
	v_lshl_add_u32 v0, v9, 4, s3
	s_waitcnt lgkmcnt(0)
	v_add_u32_e32 v1, 0x2000, v0
	v_ashrrev_i32_e32 v2, 31, v1
	v_lshrrev_b32_e32 v2, 22, v2
	v_add_u32_e32 v2, v1, v2
	v_ashrrev_i32_e32 v8, 10, v2
	v_mul_i32_i24_e32 v2, 0x400, v8
	v_sub_u32_e32 v1, v1, v2
	v_lshrrev_b32_e32 v2, 4, v1
	v_bitop3_b32 v1, v2, v1, 32 bitop3:0x6c
	v_ashrrev_i32_e32 v2, 31, v1
	v_lshrrev_b32_e32 v2, 26, v2
	v_add_u32_e32 v2, v1, v2
	v_ashrrev_i32_e32 v10, 6, v2
	v_lshlrev_b32_e32 v3, 3, v8
	v_and_b32_e32 v2, 0xffc0, v2
	v_and_b32_e32 v3, -16, v3
	v_sub_u32_e32 v1, v1, v2
	v_add_u32_e32 v3, v10, v3
	v_lshrrev_b16_e32 v2, 7, v1
	v_and_b32_e32 v4, 3, v10
	s_mov_b32 s4, 0x1fffe0
	v_lshrrev_b32_e32 v5, 2, v3
	v_lshlrev_b32_e32 v6, 1, v3
	v_and_b32_e32 v2, 1, v2
	v_and_or_b32 v4, v3, s4, v4
	v_and_b32_e32 v5, 4, v5
	v_and_b32_e32 v6, 24, v6
	v_add_u16_e32 v1, v1, v2
	v_mov_b32_e32 v2, 1
	v_or3_b32 v4, v4, v5, v6
	v_lshlrev_b32_e32 v5, 5, v8
	v_ashrrev_i16_sdwa v1, v2, sext(v1) dst_sel:DWORD dst_unused:UNUSED_PAD src0_sel:DWORD src1_sel:BYTE_0
	v_and_b32_e32 v5, 32, v5
	v_bfe_i32 v11, v1, 0, 16
	v_add_lshl_u32 v1, v5, v11, 1
	v_lshl_add_u32 v208, v4, 11, v1
	v_lshl_add_u32 v210, v3, 11, v1
	v_ashrrev_i32_e32 v1, 31, v0
	v_lshrrev_b32_e32 v1, 22, v1
	v_add_u32_e32 v1, v0, v1
	v_ashrrev_i32_e32 v12, 10, v1
	v_mul_i32_i24_e32 v1, 0x400, v12
	v_sub_u32_e32 v0, v0, v1
	v_lshrrev_b32_e32 v1, 4, v0
	v_bitop3_b32 v0, v1, v0, 32 bitop3:0x6c
	v_ashrrev_i32_e32 v1, 31, v0
	v_lshrrev_b32_e32 v1, 26, v1
	v_add_u32_e32 v1, v0, v1
	v_lshlrev_b32_e32 v3, 3, v12
	v_ashrrev_i32_e32 v13, 6, v1
	v_and_b32_e32 v3, -16, v3
	v_add_u32_e32 v3, v13, v3
	v_and_b32_e32 v4, 3, v13
	v_and_or_b32 v4, v3, s4, v4
	s_mov_b64 s[4:5], s[0:1]
	s_mov_b64 s[6:7], s[100:101]
	s_ashr_i32 s4, s2, 31
	s_lshr_b32 s4, s4, 29
	s_add_i32 s4, s2, s4
	s_ashr_i32 s5, s4, 3
	s_and_b32 s4, s4, -8
	s_sub_i32 s4, s2, s4
	s_lshl_b32 s8, s4, 5
	s_add_i32 s5, s8, s5
	s_ashr_i32 s8, s5, 31
	s_lshr_b32 s8, s8, 27
	s_add_i32 s8, s5, s8
	s_andn2_b32 s8, s8, 31
	s_sub_i32 s5, s5, s8
	s_bfe_i32 s8, s5, 0x80000
	s_bfe_u32 s8, s8, 0x3000c
	s_add_i32 s8, s5, s8
	s_bfe_i32 s9, s8, 0x80000
	s_and_b32 s8, s8, 0xf8
	s_sub_i32 s5, s5, s8
	s_lshl_b32 s4, s4, 3
	s_sext_i32_i8 s5, s5
	s_add_i32 s30, s4, s5
	s_sext_i32_i16 s9, s9
	s_ashr_i32 s31, s30, 31
	s_lshr_b32 s10, s74, 8
	s_lshr_b32 s12, s9, 3
	s_lshl_b64 s[4:5], s[30:31], 19
	s_waitcnt lgkmcnt(0)
	s_add_u32 s11, s6, s4
	s_addc_u32 s13, s7, s5
	s_add_u32 s4, s11, 0x5800000
	s_addc_u32 s5, s13, 0
	s_bfe_i64 s[8:9], s[12:13], 0x100000
	v_lshrrev_b32_e32 v5, 2, v3
	v_lshlrev_b32_e32 v6, 1, v3
	v_and_b32_e32 v1, 0xc0, v1
	s_lshl_b64 s[8:9], s[8:9], 19
	v_and_b32_e32 v5, 4, v5
	v_and_b32_e32 v6, 24, v6
	v_sub_u32_e32 v0, v0, v1
	s_add_u32 s8, s6, s8
	v_or3_b32 v4, v4, v5, v6
	v_lshlrev_b32_e32 v5, 5, v12
	v_ashrrev_i16_sdwa v0, v2, sext(v0) dst_sel:DWORD dst_unused:UNUSED_PAD src0_sel:DWORD src1_sel:BYTE_0
	s_addc_u32 s9, s7, s9
	v_and_b32_e32 v5, 32, v5
	v_bfe_i32 v14, v0, 0, 16
	s_add_u32 s6, s8, 0x1400000
	v_add_lshl_u32 v0, v5, v14, 1
	s_addc_u32 s7, s9, 0
	s_add_i32 s36, s3, 0
	v_lshl_add_u32 v212, v4, 11, v0
	s_add_i32 m0, s36, 0x10000
	v_lshl_add_u32 v214, v3, 11, v0
	global_load_lds_dwordx4 v212, s[6:7]
	s_add_i32 m0, s36, 0x12000
	s_add_u32 s8, s8, 0x1440000
	global_load_lds_dwordx4 v208, s[6:7]
	s_addc_u32 s9, s9, 0
	s_add_i32 m0, s36, 0x14000
	s_add_i32 s37, s36, 0x2000
	global_load_lds_dwordx4 v212, s[8:9]
	s_add_i32 m0, s36, 0x16000
	v_mov_b32_e32 v213, 0
	global_load_lds_dwordx4 v208, s[8:9]
	s_mov_b32 m0, s36
	s_add_u32 s8, s11, 0x5840000
	global_load_lds_dwordx4 v214, s[4:5]
	s_mov_b32 m0, s37
	s_addc_u32 s9, s13, 0
	s_add_i32 s38, s36, 0x4000
	global_load_lds_dwordx4 v210, s[4:5]
	s_mov_b32 m0, s38
	s_add_i32 s39, s36, 0x6000
	global_load_lds_dwordx4 v214, s[8:9]
	s_mov_b32 m0, s39
	v_mov_b32_e32 v209, v213
	global_load_lds_dwordx4 v210, s[8:9]
	v_mov_b32_e32 v215, v213
	v_mov_b32_e32 v211, v213
	s_cmp_eq_u32 s10, 1
	s_mov_b32 s40, 0
	s_mov_b32 s41, 0x10000
	v_lshl_add_u64 v[6:7], s[6:7], 0, v[212:213]
	v_lshl_add_u64 v[4:5], s[6:7], 0, v[208:209]
	v_lshl_add_u64 v[0:1], s[4:5], 0, v[214:215]
	s_cselect_b64 s[8:9], -1, 0
	s_cmp_lg_u32 s10, 1
	v_lshl_add_u64 v[2:3], s[4:5], 0, v[210:211]
	s_cbranch_scc1 .LBB0_1513
	s_barrier

.LBB0_1516:
	s_add_i32 s40, s40, 1
	s_mul_i32 s23, s40, s33
	s_add_i32 s23, s23, s2
	s_cmpk_lt_i32 s23, 0x100
	s_cselect_b64 s[28:29], -1, 0
	s_cmpk_gt_i32 s23, 0xff
	s_cbranch_scc1 .LBB0_1518
	s_ashr_i32 s22, s23, 31
	s_mov_b64 s[24:25], s[0:1]
	s_lshr_b32 s22, s22, 29
	s_add_i32 s22, s23, s22
	s_mov_b64 s[26:27], s[100:101]
	s_ashr_i32 s24, s22, 3
	s_and_b32 s22, s22, -8
	s_sub_i32 s22, s23, s22
	s_lshl_b32 s23, s22, 5
	s_add_i32 s23, s23, s24
	s_ashr_i32 s24, s23, 31
	s_lshr_b32 s24, s24, 27
	s_add_i32 s24, s23, s24
	s_andn2_b32 s24, s24, 31
	s_sub_i32 s23, s23, s24
	s_bfe_i32 s24, s23, 0x80000
	s_bfe_u32 s24, s24, 0x3000c
	s_add_i32 s24, s23, s24
	s_bfe_i32 s25, s24, 0x80000
	s_and_b32 s24, s24, 0xf8
	s_sub_i32 s23, s23, s24
	s_lshl_b32 s22, s22, 3
	s_sext_i32_i8 s23, s23
	s_add_i32 s22, s22, s23
	s_sext_i32_i16 s25, s25
	s_ashr_i32 s23, s22, 31
	s_lshr_b32 s34, s25, 3
	s_ashr_i32 s59, s25, 3
	s_lshl_b64 s[24:25], s[22:23], 19
	s_waitcnt lgkmcnt(0)
	s_add_u32 s23, s26, s24
	s_addc_u32 s25, s27, s25
	s_add_u32 s24, s23, 0x5800000
	s_addc_u32 s25, s25, 0
	s_bfe_i64 s[34:35], s[34:35], 0x100000
	s_lshl_b64 s[34:35], s[34:35], 19
	s_add_u32 s23, s26, s34
	s_addc_u32 s27, s27, s35
	s_add_u32 s26, s23, 0x1400000
	s_addc_u32 s27, s27, 0

	.amdhsa_kernel _Z6mk_fwd4Args
		.amdhsa_group_segment_fixed_size 0
		.amdhsa_private_segment_fixed_size 0
		.amdhsa_kernarg_size 448
		.amdhsa_user_sgpr_count 2
		.amdhsa_user_sgpr_dispatch_ptr 0
		.amdhsa_user_sgpr_queue_ptr 0
		.amdhsa_user_sgpr_kernarg_segment_ptr 1
		.amdhsa_user_sgpr_dispatch_id 0
		.amdhsa_user_sgpr_kernarg_preload_length 0
		.amdhsa_user_sgpr_kernarg_preload_offset 0
		.amdhsa_user_sgpr_private_segment_size 0
		.amdhsa_uses_dynamic_stack 0
		.amdhsa_enable_private_segment 0
		.amdhsa_system_sgpr_workgroup_id_x 1
		.amdhsa_system_sgpr_workgroup_id_y 0
		.amdhsa_system_sgpr_workgroup_id_z 0
		.amdhsa_system_sgpr_workgroup_info 0
		.amdhsa_system_vgpr_workitem_id 0
		.amdhsa_next_free_vgpr 253
		.amdhsa_next_free_sgpr 102
		.amdhsa_accum_offset 256
		.amdhsa_reserve_vcc 1
		.amdhsa_float_round_mode_32 0
		.amdhsa_float_round_mode_16_64 0
		.amdhsa_float_denorm_mode_32 3
		.amdhsa_float_denorm_mode_16_64 3
		.amdhsa_dx10_clamp 1
		.amdhsa_ieee_mode 1
		.amdhsa_fp16_overflow 0
		.amdhsa_tg_split 0
		.amdhsa_exception_fp_ieee_invalid_op 0
		.amdhsa_exception_fp_denorm_src 0
		.amdhsa_exception_fp_ieee_div_zero 0
		.amdhsa_exception_fp_ieee_overflow 0
		.amdhsa_exception_fp_ieee_underflow 0
		.amdhsa_exception_fp_ieee_inexact 0
		.amdhsa_exception_int_div_zero 0
	.end_amdhsa_kernel

amdhsa.kernels:
  - .agpr_count:     0
    .args:
      - .offset:         0
        .size:           192
        .value_kind:     by_value
      - .offset:         192
        .size:           4
        .value_kind:     hidden_block_count_x
      - .offset:         196
        .size:           4
        .value_kind:     hidden_block_count_y
      - .offset:         200
        .size:           4
        .value_kind:     hidden_block_count_z
      - .offset:         204
        .size:           2
        .value_kind:     hidden_group_size_x
      - .offset:         206
        .size:           2
        .value_kind:     hidden_group_size_y
      - .offset:         208
        .size:           2
        .value_kind:     hidden_group_size_z
      - .offset:         210
        .size:           2
        .value_kind:     hidden_remainder_x
      - .offset:         212
        .size:           2
        .value_kind:     hidden_remainder_y
      - .offset:         214
        .size:           2
        .value_kind:     hidden_remainder_z
      - .offset:         232
        .size:           8
        .value_kind:     hidden_global_offset_x
      - .offset:         240
        .size:           8
        .value_kind:     hidden_global_offset_y
      - .offset:         248
        .size:           8
        .value_kind:     hidden_global_offset_z
      - .offset:         256
        .size:           2
        .value_kind:     hidden_grid_dims
      - .offset:         312
        .size:           4
        .value_kind:     hidden_dynamic_lds_size
    .group_segment_fixed_size: 0
    .kernarg_segment_align: 8
    .kernarg_segment_size: 448
    .language:       OpenCL C
    .language_version:
      - 2
      - 0
    .max_flat_workgroup_size: 512
    .name:           _Z6mk_fwd4Args
    .private_segment_fixed_size: 0
    .sgpr_count:     108
    .sgpr_spill_count: 9
    .symbol:         _Z6mk_fwd4Args.kd
    .uniform_work_group_size: 1
    .uses_dynamic_stack: false
    .vgpr_count:     253
    .vgpr_spill_count: 0
    .wavefront_size: 64
